# v30 + GEMM MFMA blocks 8-byte aligned (.p2align 3 before each 16-MFMA run)
# speedup vs baseline: 1.0027x; 1.0027x over previous
; #define PG8_STAGEA(bufoff, gbase, voff) PG8_STAGE_X(bufoff, gbase, voff, PG8_AUX_A)
; #define PG8_STAGEB(bufoff, gbase, voff) PG8_STAGE_X(bufoff, gbase, voff, PG8_AUX_B)
; #define PG8_LDA(dst, b, h) do { _Pragma("unroll") for (int m = 0; m < 4; ++m) _Pragma("unroll") for (int k = 0; k < 2; ++k) dst[m][k] = *(const PG8_LAS bf16x8*)(lds + PG8_SA(b, h) + aoff + m * 2048 + k * 1024); } while (0)
; #define PG8_LDB(dst, b, h) do { _Pragma("unroll") for (int n = 0; n < 2; ++n) _Pragma("unroll") for (int k = 0; k < 2; ++k) dst[n][k] = *(const PG8_LAS bf16x8*)(lds + PG8_SB(b, h) + boff + n * 2048 + k * 1024); } while (0)
; #define PG8_MMA(ai, bj, At, Bt) do { __builtin_amdgcn_s_setprio(1); _Pragma("unroll") for (int m = 0; m < 4; ++m) _Pragma("unroll") for (int n = 0; n < 2; ++n) _Pragma("unroll") for (int k = 0; k < 2; ++k) \
;         acc[ai][bj][m][n] = __builtin_amdgcn_mfma_f32_16x16x32_bf16(Bt[n][k], At[m][k], acc[ai][bj][m][n], 0, 0, 0); __builtin_amdgcn_s_setprio(0); } while (0)
; #define PG8_WAIT_V(n) asm volatile("s_waitcnt vmcnt(" #n ")" ::: "memory")
; #define PG8_WAIT_L(n) asm volatile("s_waitcnt lgkmcnt(" #n ")" ::: "memory")
; #define PG8_BAR __builtin_amdgcn_s_barrier()
; #define PG8_SCHED __builtin_amdgcn_sched_barrier(0)
; template <class Epi, class Sched, bool ALIGN_EPI = false, bool SP2 = false>
; __device__ __forceinline__ void gemm_phase(PG8_LAS unsigned char* lds, const Gemm g, const Sched& S, const Epi& E) {
;     ...
;             PG8_LDB(B0, 0, 0); PG8_LDB(B1, 0, 1); PG8_SCHED; PG8_LDA(At, 0, 0); PG8_STAGEA(PG8_SA(1, 1), a1 + hstep, voffA);
;             PG8_WAIT_V(8); PG8_WAIT_L(0); PG8_BAR; PG8_MMA(0, 0, At, B0); PG8_MMA(0, 1, At, B1); PG8_BAR; PG8_SCHED;
;             PG8_LDA(At, 0, 1); PG8_STAGEB(PG8_SB(0, 0), b2, voffB); PG8_STAGEB(PG8_SB(0, 1), b2 + hstep, voffB); PG8_STAGEA(PG8_SA(0, 0), a2, voffA);
.LBB0_94:
	s_add_i32 s71, s73, 2
	s_cmp_gt_u32 s71, 29
	s_cselect_b64 s[34:35], -1, 0
	s_and_b64 vcc, s[34:35], exec
	ds_read_b128 v[134:137], v184
	ds_read_b128 v[138:141], v184 offset:1024
	ds_read_b128 v[142:145], v184 offset:2048
	ds_read_b128 v[170:173], v184 offset:3072
	ds_read_b128 v[174:177], v185
	ds_read_b128 v[178:181], v185 offset:1024
	ds_read_b128 v[190:193], v185 offset:2048
	ds_read_b128 v[194:197], v185 offset:3072
	s_cselect_b32 s83, s60, s78
	s_cselect_b32 s34, s59, s9
	s_cselect_b32 s35, s58, s8
	s_cselect_b32 s82, s61, s79
	s_add_u32 s83, s83, s80
	s_addc_u32 s82, s82, s81
	s_add_u32 s83, s83, 0xfff80080
	s_addc_u32 s82, s82, -1
	s_add_u32 s35, s35, s80
	s_addc_u32 s34, s34, s81
	s_add_u32 s35, s35, 0xfff80080
	s_addc_u32 s34, s34, -1
	s_cmp_eq_u32 s73, 28
	s_cselect_b32 s85, s7, s82
	s_cselect_b32 s84, s26, s83
	s_cselect_b32 s83, s27, s34
	s_cselect_b32 s82, s57, s35
	v_lshl_add_u64 v[230:231], v[130:131], 0, s[80:81]
	s_add_i32 m0, s90, 0xc000
	ds_read_b128 v[198:201], v186
	ds_read_b128 v[202:205], v186 offset:1024
	ds_read_b128 v[206:209], v186 offset:2048
	ds_read_b128 v[210:213], v186 offset:3072
	ds_read_b128 v[214:217], v186 offset:4096
	ds_read_b128 v[218:221], v186 offset:5120
	ds_read_b128 v[222:225], v186 offset:6144
	ds_read_b128 v[226:229], v186 offset:7168
	global_load_lds_dwordx4 v[230:231], off
	v_lshl_add_u64 v[230:231], v[132:133], 0, s[80:81]
	s_add_i32 m0, s90, 0xe000
	s_nop 0
	global_load_lds_dwordx4 v[230:231], off
	s_waitcnt vmcnt(8)
	s_waitcnt lgkmcnt(0)
	s_barrier
	s_setprio 1
	s_waitcnt lgkmcnt(0)
	.p2align 3
	v_mfma_f32_16x16x32_bf16 v[126:129], v[134:137], v[198:201], v[126:129]
	v_mfma_f32_16x16x32_bf16 v[94:97], v[142:145], v[198:201], v[94:97]
	v_mfma_f32_16x16x32_bf16 v[122:125], v[134:137], v[206:209], v[122:125]
	v_mfma_f32_16x16x32_bf16 v[90:93], v[142:145], v[206:209], v[90:93]
	v_mfma_f32_16x16x32_bf16 v[118:121], v[134:137], v[214:217], v[118:121]
	v_mfma_f32_16x16x32_bf16 v[86:89], v[142:145], v[214:217], v[86:89]
	v_mfma_f32_16x16x32_bf16 v[114:117], v[134:137], v[222:225], v[114:117]
	v_mfma_f32_16x16x32_bf16 v[82:85], v[142:145], v[222:225], v[82:85]
	v_mfma_f32_16x16x32_bf16 v[126:129], v[138:141], v[202:205], v[126:129]
	v_mfma_f32_16x16x32_bf16 v[94:97], v[170:173], v[202:205], v[94:97]
	v_mfma_f32_16x16x32_bf16 v[122:125], v[138:141], v[210:213], v[122:125]
	v_mfma_f32_16x16x32_bf16 v[90:93], v[170:173], v[210:213], v[90:93]
	v_mfma_f32_16x16x32_bf16 v[118:121], v[138:141], v[218:221], v[118:121]
	v_mfma_f32_16x16x32_bf16 v[86:89], v[170:173], v[218:221], v[86:89]
	v_mfma_f32_16x16x32_bf16 v[114:117], v[138:141], v[226:229], v[114:117]
	v_mfma_f32_16x16x32_bf16 v[82:85], v[170:173], v[226:229], v[82:85]
	s_setprio 0
	s_setprio 1
	.p2align 3
	v_mfma_f32_16x16x32_bf16 v[62:65], v[174:177], v[198:201], v[62:65]
	v_mfma_f32_16x16x32_bf16 v[30:33], v[190:193], v[198:201], v[30:33]
	v_mfma_f32_16x16x32_bf16 v[58:61], v[174:177], v[206:209], v[58:61]
	v_mfma_f32_16x16x32_bf16 v[26:29], v[190:193], v[206:209], v[26:29]
	v_mfma_f32_16x16x32_bf16 v[54:57], v[174:177], v[214:217], v[54:57]
	v_mfma_f32_16x16x32_bf16 v[22:25], v[190:193], v[214:217], v[22:25]
	v_mfma_f32_16x16x32_bf16 v[50:53], v[174:177], v[222:225], v[50:53]
	v_mfma_f32_16x16x32_bf16 v[18:21], v[190:193], v[222:225], v[18:21]
	v_mfma_f32_16x16x32_bf16 v[62:65], v[178:181], v[202:205], v[62:65]
	v_mfma_f32_16x16x32_bf16 v[30:33], v[194:197], v[202:205], v[30:33]
	v_mfma_f32_16x16x32_bf16 v[58:61], v[178:181], v[210:213], v[58:61]
	v_mfma_f32_16x16x32_bf16 v[26:29], v[194:197], v[210:213], v[26:29]
	v_mfma_f32_16x16x32_bf16 v[54:57], v[178:181], v[218:221], v[54:57]
	v_mfma_f32_16x16x32_bf16 v[22:25], v[194:197], v[218:221], v[22:25]
	v_mfma_f32_16x16x32_bf16 v[50:53], v[178:181], v[226:229], v[50:53]
	v_mfma_f32_16x16x32_bf16 v[18:21], v[194:197], v[226:229], v[18:21]
	s_setprio 0
	s_barrier
	s_add_i32 s34, s97, s87
	v_lshl_add_u64 v[230:231], s[82:83], 0, v[148:149]
	s_mov_b32 m0, s34
	ds_read_b128 v[198:201], v186 offset:16384
	ds_read_b128 v[202:205], v186 offset:17408
	ds_read_b128 v[206:209], v186 offset:18432
	ds_read_b128 v[210:213], v186 offset:19456
	ds_read_b128 v[214:217], v186 offset:20480
	ds_read_b128 v[218:221], v186 offset:21504
	ds_read_b128 v[222:225], v186 offset:22528
	ds_read_b128 v[226:229], v186 offset:23552
	global_load_lds_dwordx4 v[230:231], off
	s_add_i32 m0, s34, 0x2000
	s_add_u32 s34, s82, 0x80000
	v_lshl_add_u64 v[232:233], s[82:83], 0, v[152:153]
	s_addc_u32 s35, s83, 0
	s_add_i32 s73, s11, s87
	global_load_lds_dwordx4 v[232:233], off
	v_lshl_add_u64 v[234:235], s[34:35], 0, v[148:149]
	s_mov_b32 m0, s73
	v_lshl_add_u64 v[236:237], s[84:85], 0, v[150:151]
	global_load_lds_dwordx4 v[234:235], off
	v_lshl_add_u64 v[234:235], s[34:35], 0, v[152:153]
	s_add_i32 m0, s73, 0x2000
	s_nop 0
	global_load_lds_dwordx4 v[234:235], off
	v_lshl_add_u64 v[234:235], s[84:85], 0, v[146:147]
	s_mov_b32 m0, s90
	s_nop 0
	global_load_lds_dwordx4 v[234:235], off
	s_mov_b32 m0, s91
	s_nop 0
	global_load_lds_dwordx4 v[236:237], off
	s_waitcnt vmcnt(8)
	s_waitcnt lgkmcnt(0)
	s_barrier
; #define PG8_STAGEA(bufoff, gbase, voff) PG8_STAGE_X(bufoff, gbase, voff, PG8_AUX_A)
; #define PG8_LDA(dst, b, h) do { _Pragma("unroll") for (int m = 0; m < 4; ++m) _Pragma("unroll") for (int k = 0; k < 2; ++k) dst[m][k] = *(const PG8_LAS bf16x8*)(lds + PG8_SA(b, h) + aoff + m * 2048 + k * 1024); } while (0)
; #define PG8_LDB(dst, b, h) do { _Pragma("unroll") for (int n = 0; n < 2; ++n) _Pragma("unroll") for (int k = 0; k < 2; ++k) dst[n][k] = *(const PG8_LAS bf16x8*)(lds + PG8_SB(b, h) + boff + n * 2048 + k * 1024); } while (0)
; #define PG8_MMA(ai, bj, At, Bt) do { __builtin_amdgcn_s_setprio(1); _Pragma("unroll") for (int m = 0; m < 4; ++m) _Pragma("unroll") for (int n = 0; n < 2; ++n) _Pragma("unroll") for (int k = 0; k < 2; ++k) \
;         acc[ai][bj][m][n] = __builtin_amdgcn_mfma_f32_16x16x32_bf16(Bt[n][k], At[m][k], acc[ai][bj][m][n], 0, 0, 0); __builtin_amdgcn_s_setprio(0); } while (0)
; #define PG8_WAIT_V(n) asm volatile("s_waitcnt vmcnt(" #n ")" ::: "memory")
; #define PG8_WAIT_L(n) asm volatile("s_waitcnt lgkmcnt(" #n ")" ::: "memory")
; #define PG8_BAR __builtin_amdgcn_s_barrier()
; #define PG8_SCHED __builtin_amdgcn_sched_barrier(0)
; template <class Epi, class Sched, bool ALIGN_EPI = false, bool SP2 = false>
; __device__ __forceinline__ void gemm_phase(PG8_LAS unsigned char* lds, const Gemm g, const Sched& S, const Epi& E) {
;     ...
;             PG8_WAIT_V(8); PG8_WAIT_L(0); PG8_BAR; PG8_MMA(1, 0, At, B0); PG8_MMA(1, 1, At, B1); PG8_BAR; PG8_SCHED;
;             PG8_LDB(B0, 1, 0); PG8_LDB(B1, 1, 1); PG8_SCHED; PG8_LDA(At, 1, 0); PG8_STAGEA(PG8_SA(0, 1), a2 + hstep, voffA);
;             PG8_WAIT_V(8); PG8_WAIT_L(0); PG8_BAR; PG8_MMA(0, 0, At, B0); PG8_MMA(0, 1, At, B1); PG8_BAR; PG8_SCHED;
	s_setprio 1
	s_waitcnt lgkmcnt(0)
	.p2align 3
	v_mfma_f32_16x16x32_bf16 v[110:113], v[134:137], v[198:201], v[110:113]
	v_mfma_f32_16x16x32_bf16 v[78:81], v[142:145], v[198:201], v[78:81]
	v_mfma_f32_16x16x32_bf16 v[106:109], v[134:137], v[206:209], v[106:109]
	v_mfma_f32_16x16x32_bf16 v[74:77], v[142:145], v[206:209], v[74:77]
	v_mfma_f32_16x16x32_bf16 v[102:105], v[134:137], v[214:217], v[102:105]
	v_mfma_f32_16x16x32_bf16 v[70:73], v[142:145], v[214:217], v[70:73]
	v_mfma_f32_16x16x32_bf16 v[98:101], v[134:137], v[222:225], v[98:101]
	v_mfma_f32_16x16x32_bf16 v[66:69], v[142:145], v[222:225], v[66:69]
	v_mfma_f32_16x16x32_bf16 v[110:113], v[138:141], v[202:205], v[110:113]
	v_mfma_f32_16x16x32_bf16 v[78:81], v[170:173], v[202:205], v[78:81]
	v_mfma_f32_16x16x32_bf16 v[106:109], v[138:141], v[210:213], v[106:109]
	v_mfma_f32_16x16x32_bf16 v[74:77], v[170:173], v[210:213], v[74:77]
	v_mfma_f32_16x16x32_bf16 v[102:105], v[138:141], v[218:221], v[102:105]
	v_mfma_f32_16x16x32_bf16 v[70:73], v[170:173], v[218:221], v[70:73]
	v_mfma_f32_16x16x32_bf16 v[98:101], v[138:141], v[226:229], v[98:101]
	v_mfma_f32_16x16x32_bf16 v[66:69], v[170:173], v[226:229], v[66:69]
	s_setprio 0
	s_setprio 1
	.p2align 3
	v_mfma_f32_16x16x32_bf16 v[46:49], v[174:177], v[198:201], v[46:49]
	v_mfma_f32_16x16x32_bf16 v[14:17], v[190:193], v[198:201], v[14:17]
	v_mfma_f32_16x16x32_bf16 v[42:45], v[174:177], v[206:209], v[42:45]
	v_mfma_f32_16x16x32_bf16 v[10:13], v[190:193], v[206:209], v[10:13]
	v_mfma_f32_16x16x32_bf16 v[38:41], v[174:177], v[214:217], v[38:41]
	v_mfma_f32_16x16x32_bf16 v[6:9], v[190:193], v[214:217], v[6:9]
	v_mfma_f32_16x16x32_bf16 v[34:37], v[174:177], v[222:225], v[34:37]
	v_mfma_f32_16x16x32_bf16 v[2:5], v[190:193], v[222:225], v[2:5]
	v_mfma_f32_16x16x32_bf16 v[46:49], v[178:181], v[202:205], v[46:49]
	v_mfma_f32_16x16x32_bf16 v[14:17], v[194:197], v[202:205], v[14:17]
	v_mfma_f32_16x16x32_bf16 v[42:45], v[178:181], v[210:213], v[42:45]
	v_mfma_f32_16x16x32_bf16 v[10:13], v[194:197], v[210:213], v[10:13]
	v_mfma_f32_16x16x32_bf16 v[38:41], v[178:181], v[218:221], v[38:41]
	v_mfma_f32_16x16x32_bf16 v[6:9], v[194:197], v[218:221], v[6:9]
	v_mfma_f32_16x16x32_bf16 v[34:37], v[178:181], v[226:229], v[34:37]
	v_mfma_f32_16x16x32_bf16 v[2:5], v[194:197], v[226:229], v[2:5]
	s_setprio 0
	s_barrier
	s_add_i32 s73, 0, 0x18000
	v_add_u32_e32 v154, s73, v182
	s_add_i32 s54, 0, 0x1c000
	ds_read_b128 v[134:137], v154
	ds_read_b128 v[138:141], v154 offset:1024
	ds_read_b128 v[142:145], v154 offset:2048
	ds_read_b128 v[170:173], v154 offset:3072
	v_add_u32_e32 v154, s54, v182
	ds_read_b128 v[174:177], v154
	ds_read_b128 v[178:181], v154 offset:1024
	ds_read_b128 v[190:193], v154 offset:2048
	ds_read_b128 v[194:197], v154 offset:3072
	s_add_u32 s34, s84, 0x80000
	s_addc_u32 s35, s85, 0
	s_mov_b32 m0, s92
	v_lshl_add_u64 v[238:239], s[34:35], 0, v[146:147]
	ds_read_b128 v[198:201], v186 offset:32768
	ds_read_b128 v[202:205], v186 offset:33792
	ds_read_b128 v[206:209], v186 offset:34816
	ds_read_b128 v[210:213], v186 offset:35840
	ds_read_b128 v[214:217], v186 offset:36864
	ds_read_b128 v[218:221], v186 offset:37888
	ds_read_b128 v[222:225], v186 offset:38912
	ds_read_b128 v[226:229], v186 offset:39936
	global_load_lds_dwordx4 v[238:239], off
	v_lshl_add_u64 v[238:239], s[34:35], 0, v[150:151]
	s_mov_b32 m0, s93
	s_nop 0
	global_load_lds_dwordx4 v[238:239], off
	s_waitcnt vmcnt(8)
	s_waitcnt lgkmcnt(0)
	s_barrier
	s_setprio 1
	s_waitcnt lgkmcnt(0)
	.p2align 3
	v_mfma_f32_16x16x32_bf16 v[126:129], v[134:137], v[198:201], v[126:129]
	v_mfma_f32_16x16x32_bf16 v[94:97], v[142:145], v[198:201], v[94:97]
	v_mfma_f32_16x16x32_bf16 v[122:125], v[134:137], v[206:209], v[122:125]
	v_mfma_f32_16x16x32_bf16 v[90:93], v[142:145], v[206:209], v[90:93]
	v_mfma_f32_16x16x32_bf16 v[118:121], v[134:137], v[214:217], v[118:121]
	v_mfma_f32_16x16x32_bf16 v[86:89], v[142:145], v[214:217], v[86:89]
	v_mfma_f32_16x16x32_bf16 v[114:117], v[134:137], v[222:225], v[114:117]
	v_mfma_f32_16x16x32_bf16 v[82:85], v[142:145], v[222:225], v[82:85]
	v_mfma_f32_16x16x32_bf16 v[126:129], v[138:141], v[202:205], v[126:129]
	v_mfma_f32_16x16x32_bf16 v[94:97], v[170:173], v[202:205], v[94:97]
	v_mfma_f32_16x16x32_bf16 v[122:125], v[138:141], v[210:213], v[122:125]
	v_mfma_f32_16x16x32_bf16 v[90:93], v[170:173], v[210:213], v[90:93]
	v_mfma_f32_16x16x32_bf16 v[118:121], v[138:141], v[218:221], v[118:121]
	v_mfma_f32_16x16x32_bf16 v[86:89], v[170:173], v[218:221], v[86:89]
	v_mfma_f32_16x16x32_bf16 v[114:117], v[138:141], v[226:229], v[114:117]
	v_mfma_f32_16x16x32_bf16 v[82:85], v[170:173], v[226:229], v[82:85]
	s_setprio 0
	s_setprio 1
	.p2align 3
	v_mfma_f32_16x16x32_bf16 v[62:65], v[174:177], v[198:201], v[62:65]
	v_mfma_f32_16x16x32_bf16 v[30:33], v[190:193], v[198:201], v[30:33]
	v_mfma_f32_16x16x32_bf16 v[58:61], v[174:177], v[206:209], v[58:61]
	v_mfma_f32_16x16x32_bf16 v[26:29], v[190:193], v[206:209], v[26:29]
	v_mfma_f32_16x16x32_bf16 v[54:57], v[174:177], v[214:217], v[54:57]
	v_mfma_f32_16x16x32_bf16 v[22:25], v[190:193], v[214:217], v[22:25]
	v_mfma_f32_16x16x32_bf16 v[50:53], v[174:177], v[222:225], v[50:53]
	v_mfma_f32_16x16x32_bf16 v[18:21], v[190:193], v[222:225], v[18:21]
	v_mfma_f32_16x16x32_bf16 v[62:65], v[178:181], v[202:205], v[62:65]
	v_mfma_f32_16x16x32_bf16 v[30:33], v[194:197], v[202:205], v[30:33]
	v_mfma_f32_16x16x32_bf16 v[58:61], v[178:181], v[210:213], v[58:61]
	v_mfma_f32_16x16x32_bf16 v[26:29], v[194:197], v[210:213], v[26:29]
	v_mfma_f32_16x16x32_bf16 v[54:57], v[178:181], v[218:221], v[54:57]
	v_mfma_f32_16x16x32_bf16 v[22:25], v[194:197], v[218:221], v[22:25]
	v_mfma_f32_16x16x32_bf16 v[50:53], v[178:181], v[226:229], v[50:53]
	v_mfma_f32_16x16x32_bf16 v[18:21], v[194:197], v[226:229], v[18:21]
	s_setprio 0
	s_barrier
; #define PG8_STAGEA(bufoff, gbase, voff) PG8_STAGE_X(bufoff, gbase, voff, PG8_AUX_A)
; #define PG8_STAGEB(bufoff, gbase, voff) PG8_STAGE_X(bufoff, gbase, voff, PG8_AUX_B)
; #define PG8_LDA(dst, b, h) do { _Pragma("unroll") for (int m = 0; m < 4; ++m) _Pragma("unroll") for (int k = 0; k < 2; ++k) dst[m][k] = *(const PG8_LAS bf16x8*)(lds + PG8_SA(b, h) + aoff + m * 2048 + k * 1024); } while (0)
; #define PG8_MMA(ai, bj, At, Bt) do { __builtin_amdgcn_s_setprio(1); _Pragma("unroll") for (int m = 0; m < 4; ++m) _Pragma("unroll") for (int n = 0; n < 2; ++n) _Pragma("unroll") for (int k = 0; k < 2; ++k) \
;         acc[ai][bj][m][n] = __builtin_amdgcn_mfma_f32_16x16x32_bf16(Bt[n][k], At[m][k], acc[ai][bj][m][n], 0, 0, 0); __builtin_amdgcn_s_setprio(0); } while (0)
; #define PG8_WAIT_V(n) asm volatile("s_waitcnt vmcnt(" #n ")" ::: "memory")
; #define PG8_WAIT_L(n) asm volatile("s_waitcnt lgkmcnt(" #n ")" ::: "memory")
; #define PG8_BAR __builtin_amdgcn_s_barrier()
; #define PG8_SCHED __builtin_amdgcn_sched_barrier(0)
; template <class Epi, class Sched, bool ALIGN_EPI = false, bool SP2 = false>
; __device__ __forceinline__ void gemm_phase(PG8_LAS unsigned char* lds, const Gemm g, const Sched& S, const Epi& E) {
;     ...
;             PG8_LDA(At, 1, 1); PG8_STAGEB(PG8_SB(1, 0), b3, voffB); PG8_STAGEB(PG8_SB(1, 1), b3 + hstep, voffB); PG8_STAGEA(PG8_SA(1, 0), a3, voffA);
;             PG8_WAIT_V(8); PG8_WAIT_L(0); PG8_BAR; PG8_MMA(1, 0, At, B0); PG8_MMA(1, 1, At, B1); PG8_BAR; PG8_SCHED;
;     ...
;         if constexpr (ALIGN_EPI) { if (wr == 0) PG8_BAR; }
	s_add_i32 s34, s73, s87
	v_lshl_add_u64 v[230:231], v[230:231], 0, s[64:65]
	s_mov_b32 m0, s34
	ds_read_b128 v[198:201], v186 offset:49152
	ds_read_b128 v[202:205], v186 offset:50176
	ds_read_b128 v[206:209], v186 offset:51200
	ds_read_b128 v[210:213], v186 offset:52224
	ds_read_b128 v[214:217], v186 offset:53248
	ds_read_b128 v[218:221], v186 offset:54272
	ds_read_b128 v[222:225], v186 offset:55296
	ds_read_b128 v[226:229], v186 offset:56320
	global_load_lds_dwordx4 v[230:231], off
	s_add_i32 m0, s34, 0x2000
	s_add_u32 s34, s82, 0x80080
	v_lshl_add_u64 v[230:231], v[232:233], 0, s[64:65]
	s_addc_u32 s35, s83, 0
	s_add_i32 s54, s54, s87
	global_load_lds_dwordx4 v[230:231], off
	v_lshl_add_u64 v[230:231], s[34:35], 0, v[148:149]
	s_mov_b32 m0, s54
	s_nop 0
	global_load_lds_dwordx4 v[230:231], off
	v_lshl_add_u64 v[230:231], s[34:35], 0, v[152:153]
	s_add_i32 m0, s54, 0x2000
	s_nop 0
	global_load_lds_dwordx4 v[230:231], off
	v_lshl_add_u64 v[230:231], v[234:235], 0, s[64:65]
	s_mov_b32 m0, s95
	s_nop 0
	global_load_lds_dwordx4 v[230:231], off
	v_lshl_add_u64 v[230:231], v[236:237], 0, s[64:65]
	s_mov_b32 m0, s96
	s_nop 0
	global_load_lds_dwordx4 v[230:231], off
	s_waitcnt vmcnt(8)
	s_waitcnt lgkmcnt(0)
	s_barrier
	s_setprio 1
	s_waitcnt lgkmcnt(0)
	.p2align 3
	v_mfma_f32_16x16x32_bf16 v[110:113], v[134:137], v[198:201], v[110:113]
	v_mfma_f32_16x16x32_bf16 v[78:81], v[142:145], v[198:201], v[78:81]
	v_mfma_f32_16x16x32_bf16 v[106:109], v[134:137], v[206:209], v[106:109]
	v_mfma_f32_16x16x32_bf16 v[74:77], v[142:145], v[206:209], v[74:77]
	v_mfma_f32_16x16x32_bf16 v[102:105], v[134:137], v[214:217], v[102:105]
	v_mfma_f32_16x16x32_bf16 v[70:73], v[142:145], v[214:217], v[70:73]
	v_mfma_f32_16x16x32_bf16 v[98:101], v[134:137], v[222:225], v[98:101]
	v_mfma_f32_16x16x32_bf16 v[66:69], v[142:145], v[222:225], v[66:69]
	v_mfma_f32_16x16x32_bf16 v[110:113], v[138:141], v[202:205], v[110:113]
	v_mfma_f32_16x16x32_bf16 v[78:81], v[170:173], v[202:205], v[78:81]
	v_mfma_f32_16x16x32_bf16 v[106:109], v[138:141], v[210:213], v[106:109]
	v_mfma_f32_16x16x32_bf16 v[74:77], v[170:173], v[210:213], v[74:77]
	v_mfma_f32_16x16x32_bf16 v[102:105], v[138:141], v[218:221], v[102:105]
	v_mfma_f32_16x16x32_bf16 v[70:73], v[170:173], v[218:221], v[70:73]
	v_mfma_f32_16x16x32_bf16 v[98:101], v[138:141], v[226:229], v[98:101]
	v_mfma_f32_16x16x32_bf16 v[66:69], v[170:173], v[226:229], v[66:69]
	s_setprio 0
	s_setprio 1
	.p2align 3
	v_mfma_f32_16x16x32_bf16 v[46:49], v[174:177], v[198:201], v[46:49]
	v_mfma_f32_16x16x32_bf16 v[14:17], v[190:193], v[198:201], v[14:17]
	v_mfma_f32_16x16x32_bf16 v[42:45], v[174:177], v[206:209], v[42:45]
	v_mfma_f32_16x16x32_bf16 v[10:13], v[190:193], v[206:209], v[10:13]
	v_mfma_f32_16x16x32_bf16 v[38:41], v[174:177], v[214:217], v[38:41]
	v_mfma_f32_16x16x32_bf16 v[6:9], v[190:193], v[214:217], v[6:9]
	v_mfma_f32_16x16x32_bf16 v[34:37], v[174:177], v[222:225], v[34:37]
	v_mfma_f32_16x16x32_bf16 v[2:5], v[190:193], v[222:225], v[2:5]
	v_mfma_f32_16x16x32_bf16 v[46:49], v[178:181], v[202:205], v[46:49]
	v_mfma_f32_16x16x32_bf16 v[14:17], v[194:197], v[202:205], v[14:17]
	v_mfma_f32_16x16x32_bf16 v[42:45], v[178:181], v[210:213], v[42:45]
	v_mfma_f32_16x16x32_bf16 v[10:13], v[194:197], v[210:213], v[10:13]
	v_mfma_f32_16x16x32_bf16 v[38:41], v[178:181], v[218:221], v[38:41]
	v_mfma_f32_16x16x32_bf16 v[6:9], v[194:197], v[218:221], v[6:9]
	v_mfma_f32_16x16x32_bf16 v[34:37], v[178:181], v[226:229], v[34:37]
	v_mfma_f32_16x16x32_bf16 v[2:5], v[194:197], v[226:229], v[2:5]
	s_setprio 0
	s_barrier
	s_add_u32 s80, s80, 0x100
	s_addc_u32 s81, s81, 0
	s_mov_b32 s73, s71
	s_cbranch_vccz .LBB0_94
	s_and_b64 vcc, exec, s[66:67]
	s_cbranch_vccz .LBB0_97
	s_barrier

; #define PG8_STAGEA(bufoff, gbase, voff) PG8_STAGE_X(bufoff, gbase, voff, PG8_AUX_A)
; #define PG8_STAGEB(bufoff, gbase, voff) PG8_STAGE_X(bufoff, gbase, voff, PG8_AUX_B)
; #define PG8_LDA(dst, b, h) do { _Pragma("unroll") for (int m = 0; m < 4; ++m) _Pragma("unroll") for (int k = 0; k < 2; ++k) dst[m][k] = *(const PG8_LAS bf16x8*)(lds + PG8_SA(b, h) + aoff + m * 2048 + k * 1024); } while (0)
; #define PG8_LDB(dst, b, h) do { _Pragma("unroll") for (int n = 0; n < 2; ++n) _Pragma("unroll") for (int k = 0; k < 2; ++k) dst[n][k] = *(const PG8_LAS bf16x8*)(lds + PG8_SB(b, h) + boff + n * 2048 + k * 1024); } while (0)
; #define PG8_WAIT_V(n) asm volatile("s_waitcnt vmcnt(" #n ")" ::: "memory")
; #define PG8_WAIT_L(n) asm volatile("s_waitcnt lgkmcnt(" #n ")" ::: "memory")
; template <class Epi, class Sched, bool ALIGN_EPI = false, bool SP2 = false>
; __device__ __forceinline__ void gemm_phase(PG8_LAS unsigned char* lds, const Gemm g, const Sched& S, const Epi& E) {
;     ...
;             const bool last = (t == nt - 2);
;             if constexpr (HasMid<Epi>::value) { if (t == ns) E.mid(acc, cur, wr, wc, fr, fq); }
;             const char* sA1 = (t + 1 >= ns) ? cA2 : cA; const char* sA2 = (t + 2 >= ns) ? cA2 : cA; const char* sB2 = (t + 2 >= ns) ? cB2 : cB;
;             const char* a1 = sA1 + (size_t)(t + 1) * kstep;
;             const char* a2 = last ? nA : sA2 + (size_t)(t + 2) * kstep; const char* b2 = last ? nB : sB2 + (size_t)(t + 2) * kstep;
;             const char* a3 = a2 + kstep; const char* b3 = b2 + kstep;
;             if (last && has_next) S.a_ready(nxt);
;             if constexpr (SP2) {
;             PG8_LDB(B0, 0, 0); PG8_LDB(B1, 0, 1); PG8_SCHED; PG8_LDA(At, 0, 0); PG8_STAGEA(PG8_SA(1, 1), a1 + hstep, voffA);
;             PG8_WAIT_V(8); PG8_WAIT_L(0); PG8_BAR; PG8_MMA(0, 0, At, B0); PG8_MMA(0, 1, At, B1); PG8_BAR; PG8_SCHED;
;             PG8_LDA(At, 0, 1); PG8_STAGEB(PG8_SB(0, 0), b2, voffB); PG8_STAGEB(PG8_SB(0, 1), b2 + hstep, voffB); PG8_STAGEA(PG8_SA(0, 0), a2, voffA);
;             PG8_WAIT_V(8); PG8_WAIT_L(0); PG8_BAR; PG8_MMA(1, 0, At, B0); PG8_MMA(1, 1, At, B1); PG8_BAR; PG8_SCHED;
;             PG8_LDB(B0, 1, 0); PG8_LDB(B1, 1, 1); PG8_SCHED; PG8_LDA(At, 1, 0); PG8_STAGEA(PG8_SA(0, 1), a2 + hstep, voffA);
;             PG8_WAIT_V(8); PG8_WAIT_L(0); PG8_BAR; PG8_MMA(0, 0, At, B0); PG8_MMA(0, 1, At, B1); PG8_BAR; PG8_SCHED;
.LBB0_295:
	s_add_i32 s92, s74, 2
	s_cmp_gt_u32 s92, 29
	s_cselect_b64 s[34:35], -1, 0
	s_and_b64 vcc, s[34:35], exec
	s_cselect_b32 s76, s6, s70
	ds_read_b128 v[156:159], v152
	ds_read_b128 v[160:163], v152 offset:1024
	ds_read_b128 v[164:167], v152 offset:2048
	ds_read_b128 v[168:171], v152 offset:3072
	ds_read_b128 v[172:175], v153
	ds_read_b128 v[176:179], v153 offset:1024
	ds_read_b128 v[180:183], v153 offset:2048
	ds_read_b128 v[184:187], v153 offset:3072
	s_cselect_b32 s34, s5, s69
	s_cselect_b32 s35, s4, s68
	s_cselect_b32 s75, s7, s71
	s_add_u32 s76, s76, s72
	s_addc_u32 s75, s75, s73
	s_add_u32 s76, s76, 0xfff80080
	s_addc_u32 s75, s75, -1
	s_add_u32 s35, s35, s72
	s_addc_u32 s34, s34, s73
	s_add_u32 s35, s35, 0xfff80080
	s_addc_u32 s34, s34, -1
	s_cmp_eq_u32 s74, 28
	s_cselect_b32 s74, s91, s35
	s_cselect_b32 s77, s61, s75
	s_cselect_b32 s76, s90, s76
	s_cselect_b32 s75, s59, s34
	v_lshl_add_u64 v[220:221], v[146:147], 0, s[72:73]
	s_add_i32 m0, s67, 0xc000
	ds_read_b128 v[188:191], v154
	ds_read_b128 v[192:195], v154 offset:1024
	ds_read_b128 v[196:199], v154 offset:2048
	ds_read_b128 v[200:203], v154 offset:3072
	ds_read_b128 v[204:207], v154 offset:4096
	ds_read_b128 v[208:211], v154 offset:5120
	ds_read_b128 v[212:215], v154 offset:6144
	ds_read_b128 v[216:219], v154 offset:7168
	global_load_lds_dwordx4 v[220:221], off
	v_lshl_add_u64 v[220:221], v[148:149], 0, s[72:73]
	s_add_i32 m0, s67, 0xe000
	s_nop 0
	global_load_lds_dwordx4 v[220:221], off
	s_waitcnt vmcnt(8)
	s_waitcnt lgkmcnt(0)
	s_barrier
	s_setprio 1
	s_waitcnt lgkmcnt(0)
	.p2align 3
	v_mfma_f32_16x16x32_bf16 v[126:129], v[156:159], v[188:191], v[126:129]
	v_mfma_f32_16x16x32_bf16 v[122:125], v[164:167], v[188:191], v[122:125]
	v_mfma_f32_16x16x32_bf16 v[118:121], v[156:159], v[196:199], v[118:121]
	v_mfma_f32_16x16x32_bf16 v[110:113], v[164:167], v[196:199], v[110:113]
	v_mfma_f32_16x16x32_bf16 v[102:105], v[156:159], v[204:207], v[102:105]
	v_mfma_f32_16x16x32_bf16 v[94:97], v[164:167], v[204:207], v[94:97]
	v_mfma_f32_16x16x32_bf16 v[86:89], v[156:159], v[212:215], v[86:89]
	v_mfma_f32_16x16x32_bf16 v[78:81], v[164:167], v[212:215], v[78:81]
	v_mfma_f32_16x16x32_bf16 v[126:129], v[160:163], v[192:195], v[126:129]
	v_mfma_f32_16x16x32_bf16 v[122:125], v[168:171], v[192:195], v[122:125]
	v_mfma_f32_16x16x32_bf16 v[118:121], v[160:163], v[200:203], v[118:121]
	v_mfma_f32_16x16x32_bf16 v[110:113], v[168:171], v[200:203], v[110:113]
	v_mfma_f32_16x16x32_bf16 v[102:105], v[160:163], v[208:211], v[102:105]
	v_mfma_f32_16x16x32_bf16 v[94:97], v[168:171], v[208:211], v[94:97]
	v_mfma_f32_16x16x32_bf16 v[86:89], v[160:163], v[216:219], v[86:89]
	v_mfma_f32_16x16x32_bf16 v[78:81], v[168:171], v[216:219], v[78:81]
	s_setprio 0
	s_setprio 1
	.p2align 3
	v_mfma_f32_16x16x32_bf16 v[114:117], v[172:175], v[188:191], v[114:117]
	v_mfma_f32_16x16x32_bf16 v[106:109], v[180:183], v[188:191], v[106:109]
	v_mfma_f32_16x16x32_bf16 v[98:101], v[172:175], v[196:199], v[98:101]
	v_mfma_f32_16x16x32_bf16 v[90:93], v[180:183], v[196:199], v[90:93]
	v_mfma_f32_16x16x32_bf16 v[82:85], v[172:175], v[204:207], v[82:85]
	v_mfma_f32_16x16x32_bf16 v[74:77], v[180:183], v[204:207], v[74:77]
	v_mfma_f32_16x16x32_bf16 v[70:73], v[172:175], v[212:215], v[70:73]
	v_mfma_f32_16x16x32_bf16 v[66:69], v[180:183], v[212:215], v[66:69]
	v_mfma_f32_16x16x32_bf16 v[114:117], v[176:179], v[192:195], v[114:117]
	v_mfma_f32_16x16x32_bf16 v[106:109], v[184:187], v[192:195], v[106:109]
	v_mfma_f32_16x16x32_bf16 v[98:101], v[176:179], v[200:203], v[98:101]
	v_mfma_f32_16x16x32_bf16 v[90:93], v[184:187], v[200:203], v[90:93]
	v_mfma_f32_16x16x32_bf16 v[82:85], v[176:179], v[208:211], v[82:85]
	v_mfma_f32_16x16x32_bf16 v[74:77], v[184:187], v[208:211], v[74:77]
	v_mfma_f32_16x16x32_bf16 v[70:73], v[176:179], v[216:219], v[70:73]
	v_mfma_f32_16x16x32_bf16 v[66:69], v[184:187], v[216:219], v[66:69]
	s_setprio 0
	s_barrier
	s_add_i32 s34, s84, s11
	v_lshl_add_u64 v[220:221], s[74:75], 0, v[134:135]
	s_mov_b32 m0, s34
	ds_read_b128 v[188:191], v154 offset:16384
	ds_read_b128 v[192:195], v154 offset:17408
	ds_read_b128 v[196:199], v154 offset:18432
	ds_read_b128 v[200:203], v154 offset:19456
	ds_read_b128 v[204:207], v154 offset:20480
	ds_read_b128 v[208:211], v154 offset:21504
	ds_read_b128 v[212:215], v154 offset:22528
	ds_read_b128 v[216:219], v154 offset:23552
	global_load_lds_dwordx4 v[220:221], off
	s_add_i32 m0, s34, 0x2000
	s_add_u32 s34, s74, 0x80000
	v_lshl_add_u64 v[222:223], s[74:75], 0, v[130:131]
	s_addc_u32 s35, s75, 0
	s_add_i32 s93, s85, s11
	global_load_lds_dwordx4 v[222:223], off
	v_lshl_add_u64 v[224:225], s[34:35], 0, v[134:135]
	s_mov_b32 m0, s93
	v_lshl_add_u64 v[226:227], s[76:77], 0, v[132:133]
	global_load_lds_dwordx4 v[224:225], off
	v_lshl_add_u64 v[224:225], s[34:35], 0, v[130:131]
	s_add_i32 m0, s93, 0x2000
	s_nop 0
	global_load_lds_dwordx4 v[224:225], off
	v_lshl_add_u64 v[224:225], s[76:77], 0, v[136:137]
	s_mov_b32 m0, s67
	s_nop 0
	global_load_lds_dwordx4 v[224:225], off
	s_mov_b32 m0, s78
	s_nop 0
	global_load_lds_dwordx4 v[226:227], off
	s_waitcnt vmcnt(8)
	s_waitcnt lgkmcnt(0)
	s_barrier
; #define PG8_STAGEA(bufoff, gbase, voff) PG8_STAGE_X(bufoff, gbase, voff, PG8_AUX_A)
; #define PG8_LDA(dst, b, h) do { _Pragma("unroll") for (int m = 0; m < 4; ++m) _Pragma("unroll") for (int k = 0; k < 2; ++k) dst[m][k] = *(const PG8_LAS bf16x8*)(lds + PG8_SA(b, h) + aoff + m * 2048 + k * 1024); } while (0)
; #define PG8_LDB(dst, b, h) do { _Pragma("unroll") for (int n = 0; n < 2; ++n) _Pragma("unroll") for (int k = 0; k < 2; ++k) dst[n][k] = *(const PG8_LAS bf16x8*)(lds + PG8_SB(b, h) + boff + n * 2048 + k * 1024); } while (0)
; #define PG8_MMA(ai, bj, At, Bt) do { __builtin_amdgcn_s_setprio(1); _Pragma("unroll") for (int m = 0; m < 4; ++m) _Pragma("unroll") for (int n = 0; n < 2; ++n) _Pragma("unroll") for (int k = 0; k < 2; ++k) \
;         acc[ai][bj][m][n] = __builtin_amdgcn_mfma_f32_16x16x32_bf16(Bt[n][k], At[m][k], acc[ai][bj][m][n], 0, 0, 0); __builtin_amdgcn_s_setprio(0); } while (0)
; #define PG8_WAIT_V(n) asm volatile("s_waitcnt vmcnt(" #n ")" ::: "memory")
; #define PG8_WAIT_L(n) asm volatile("s_waitcnt lgkmcnt(" #n ")" ::: "memory")
; #define PG8_BAR __builtin_amdgcn_s_barrier()
; #define PG8_SCHED __builtin_amdgcn_sched_barrier(0)
; template <class Epi, class Sched, bool ALIGN_EPI = false, bool SP2 = false>
; __device__ __forceinline__ void gemm_phase(PG8_LAS unsigned char* lds, const Gemm g, const Sched& S, const Epi& E) {
;     ...
;             PG8_WAIT_V(8); PG8_WAIT_L(0); PG8_BAR; PG8_MMA(1, 0, At, B0); PG8_MMA(1, 1, At, B1); PG8_BAR; PG8_SCHED;
;             PG8_LDB(B0, 1, 0); PG8_LDB(B1, 1, 1); PG8_SCHED; PG8_LDA(At, 1, 0); PG8_STAGEA(PG8_SA(0, 1), a2 + hstep, voffA);
;             PG8_WAIT_V(8); PG8_WAIT_L(0); PG8_BAR; PG8_MMA(0, 0, At, B0); PG8_MMA(0, 1, At, B1); PG8_BAR; PG8_SCHED;
	s_setprio 1
	s_waitcnt lgkmcnt(0)
	.p2align 3
	v_mfma_f32_16x16x32_bf16 v[62:65], v[156:159], v[188:191], v[62:65]
	v_mfma_f32_16x16x32_bf16 v[58:61], v[164:167], v[188:191], v[58:61]
	v_mfma_f32_16x16x32_bf16 v[54:57], v[156:159], v[196:199], v[54:57]
	v_mfma_f32_16x16x32_bf16 v[46:49], v[164:167], v[196:199], v[46:49]
	v_mfma_f32_16x16x32_bf16 v[38:41], v[156:159], v[204:207], v[38:41]
	v_mfma_f32_16x16x32_bf16 v[30:33], v[164:167], v[204:207], v[30:33]
	v_mfma_f32_16x16x32_bf16 v[22:25], v[156:159], v[212:215], v[22:25]
	v_mfma_f32_16x16x32_bf16 v[14:17], v[164:167], v[212:215], v[14:17]
	v_mfma_f32_16x16x32_bf16 v[62:65], v[160:163], v[192:195], v[62:65]
	v_mfma_f32_16x16x32_bf16 v[58:61], v[168:171], v[192:195], v[58:61]
	v_mfma_f32_16x16x32_bf16 v[54:57], v[160:163], v[200:203], v[54:57]
	v_mfma_f32_16x16x32_bf16 v[46:49], v[168:171], v[200:203], v[46:49]
	v_mfma_f32_16x16x32_bf16 v[38:41], v[160:163], v[208:211], v[38:41]
	v_mfma_f32_16x16x32_bf16 v[30:33], v[168:171], v[208:211], v[30:33]
	v_mfma_f32_16x16x32_bf16 v[22:25], v[160:163], v[216:219], v[22:25]
	v_mfma_f32_16x16x32_bf16 v[14:17], v[168:171], v[216:219], v[14:17]
	s_setprio 0
	s_setprio 1
	.p2align 3
	v_mfma_f32_16x16x32_bf16 v[50:53], v[172:175], v[188:191], v[50:53]
	v_mfma_f32_16x16x32_bf16 v[42:45], v[180:183], v[188:191], v[42:45]
	v_mfma_f32_16x16x32_bf16 v[34:37], v[172:175], v[196:199], v[34:37]
	v_mfma_f32_16x16x32_bf16 v[26:29], v[180:183], v[196:199], v[26:29]
	v_mfma_f32_16x16x32_bf16 v[18:21], v[172:175], v[204:207], v[18:21]
	v_mfma_f32_16x16x32_bf16 v[10:13], v[180:183], v[204:207], v[10:13]
	v_mfma_f32_16x16x32_bf16 v[6:9], v[172:175], v[212:215], v[6:9]
	v_mfma_f32_16x16x32_bf16 v[2:5], v[180:183], v[212:215], v[2:5]
	v_mfma_f32_16x16x32_bf16 v[50:53], v[176:179], v[192:195], v[50:53]
	v_mfma_f32_16x16x32_bf16 v[42:45], v[184:187], v[192:195], v[42:45]
	v_mfma_f32_16x16x32_bf16 v[34:37], v[176:179], v[200:203], v[34:37]
	v_mfma_f32_16x16x32_bf16 v[26:29], v[184:187], v[200:203], v[26:29]
	v_mfma_f32_16x16x32_bf16 v[18:21], v[176:179], v[208:211], v[18:21]
	v_mfma_f32_16x16x32_bf16 v[10:13], v[184:187], v[208:211], v[10:13]
	v_mfma_f32_16x16x32_bf16 v[6:9], v[176:179], v[216:219], v[6:9]
	v_mfma_f32_16x16x32_bf16 v[2:5], v[184:187], v[216:219], v[2:5]
	s_setprio 0
	s_barrier
	s_add_i32 s93, 0, 0x18000
	v_add_u32_e32 v155, s93, v150
	s_add_i32 s94, 0, 0x1c000
	ds_read_b128 v[156:159], v155
	ds_read_b128 v[160:163], v155 offset:1024
	ds_read_b128 v[164:167], v155 offset:2048
	ds_read_b128 v[168:171], v155 offset:3072
	v_add_u32_e32 v155, s94, v150
	ds_read_b128 v[172:175], v155
	ds_read_b128 v[176:179], v155 offset:1024
	ds_read_b128 v[180:183], v155 offset:2048
	ds_read_b128 v[184:187], v155 offset:3072
	s_add_u32 s34, s76, 0x80000
	s_addc_u32 s35, s77, 0
	s_mov_b32 m0, s79
	v_lshl_add_u64 v[228:229], s[34:35], 0, v[136:137]
	ds_read_b128 v[188:191], v154 offset:32768
	ds_read_b128 v[192:195], v154 offset:33792
	ds_read_b128 v[196:199], v154 offset:34816
	ds_read_b128 v[200:203], v154 offset:35840
	ds_read_b128 v[204:207], v154 offset:36864
	ds_read_b128 v[208:211], v154 offset:37888
	ds_read_b128 v[212:215], v154 offset:38912
	ds_read_b128 v[216:219], v154 offset:39936
	global_load_lds_dwordx4 v[228:229], off
	v_lshl_add_u64 v[228:229], s[34:35], 0, v[132:133]
	s_mov_b32 m0, s80
	s_nop 0
	global_load_lds_dwordx4 v[228:229], off
	s_waitcnt vmcnt(8)
	s_waitcnt lgkmcnt(0)
	s_barrier
	s_setprio 1
	s_waitcnt lgkmcnt(0)
	.p2align 3
	v_mfma_f32_16x16x32_bf16 v[126:129], v[156:159], v[188:191], v[126:129]
	v_mfma_f32_16x16x32_bf16 v[122:125], v[164:167], v[188:191], v[122:125]
	v_mfma_f32_16x16x32_bf16 v[118:121], v[156:159], v[196:199], v[118:121]
	v_mfma_f32_16x16x32_bf16 v[110:113], v[164:167], v[196:199], v[110:113]
	v_mfma_f32_16x16x32_bf16 v[102:105], v[156:159], v[204:207], v[102:105]
	v_mfma_f32_16x16x32_bf16 v[94:97], v[164:167], v[204:207], v[94:97]
	v_mfma_f32_16x16x32_bf16 v[86:89], v[156:159], v[212:215], v[86:89]
	v_mfma_f32_16x16x32_bf16 v[78:81], v[164:167], v[212:215], v[78:81]
	v_mfma_f32_16x16x32_bf16 v[126:129], v[160:163], v[192:195], v[126:129]
	v_mfma_f32_16x16x32_bf16 v[122:125], v[168:171], v[192:195], v[122:125]
	v_mfma_f32_16x16x32_bf16 v[118:121], v[160:163], v[200:203], v[118:121]
	v_mfma_f32_16x16x32_bf16 v[110:113], v[168:171], v[200:203], v[110:113]
	v_mfma_f32_16x16x32_bf16 v[102:105], v[160:163], v[208:211], v[102:105]
	v_mfma_f32_16x16x32_bf16 v[94:97], v[168:171], v[208:211], v[94:97]
	v_mfma_f32_16x16x32_bf16 v[86:89], v[160:163], v[216:219], v[86:89]
	v_mfma_f32_16x16x32_bf16 v[78:81], v[168:171], v[216:219], v[78:81]
	s_setprio 0
	s_setprio 1
	.p2align 3
	v_mfma_f32_16x16x32_bf16 v[114:117], v[172:175], v[188:191], v[114:117]
	v_mfma_f32_16x16x32_bf16 v[106:109], v[180:183], v[188:191], v[106:109]
	v_mfma_f32_16x16x32_bf16 v[98:101], v[172:175], v[196:199], v[98:101]
	v_mfma_f32_16x16x32_bf16 v[90:93], v[180:183], v[196:199], v[90:93]
	v_mfma_f32_16x16x32_bf16 v[82:85], v[172:175], v[204:207], v[82:85]
	v_mfma_f32_16x16x32_bf16 v[74:77], v[180:183], v[204:207], v[74:77]
	v_mfma_f32_16x16x32_bf16 v[70:73], v[172:175], v[212:215], v[70:73]
	v_mfma_f32_16x16x32_bf16 v[66:69], v[180:183], v[212:215], v[66:69]
	v_mfma_f32_16x16x32_bf16 v[114:117], v[176:179], v[192:195], v[114:117]
	v_mfma_f32_16x16x32_bf16 v[106:109], v[184:187], v[192:195], v[106:109]
	v_mfma_f32_16x16x32_bf16 v[98:101], v[176:179], v[200:203], v[98:101]
	v_mfma_f32_16x16x32_bf16 v[90:93], v[184:187], v[200:203], v[90:93]
	v_mfma_f32_16x16x32_bf16 v[82:85], v[176:179], v[208:211], v[82:85]
	v_mfma_f32_16x16x32_bf16 v[74:77], v[184:187], v[208:211], v[74:77]
	v_mfma_f32_16x16x32_bf16 v[70:73], v[176:179], v[216:219], v[70:73]
	v_mfma_f32_16x16x32_bf16 v[66:69], v[184:187], v[216:219], v[66:69]
	s_setprio 0
	s_barrier
; #define PG8_STAGEA(bufoff, gbase, voff) PG8_STAGE_X(bufoff, gbase, voff, PG8_AUX_A)
; #define PG8_STAGEB(bufoff, gbase, voff) PG8_STAGE_X(bufoff, gbase, voff, PG8_AUX_B)
; #define PG8_LDA(dst, b, h) do { _Pragma("unroll") for (int m = 0; m < 4; ++m) _Pragma("unroll") for (int k = 0; k < 2; ++k) dst[m][k] = *(const PG8_LAS bf16x8*)(lds + PG8_SA(b, h) + aoff + m * 2048 + k * 1024); } while (0)
; #define PG8_MMA(ai, bj, At, Bt) do { __builtin_amdgcn_s_setprio(1); _Pragma("unroll") for (int m = 0; m < 4; ++m) _Pragma("unroll") for (int n = 0; n < 2; ++n) _Pragma("unroll") for (int k = 0; k < 2; ++k) \
;         acc[ai][bj][m][n] = __builtin_amdgcn_mfma_f32_16x16x32_bf16(Bt[n][k], At[m][k], acc[ai][bj][m][n], 0, 0, 0); __builtin_amdgcn_s_setprio(0); } while (0)
; #define PG8_WAIT_V(n) asm volatile("s_waitcnt vmcnt(" #n ")" ::: "memory")
; #define PG8_WAIT_L(n) asm volatile("s_waitcnt lgkmcnt(" #n ")" ::: "memory")
; #define PG8_BAR __builtin_amdgcn_s_barrier()
; #define PG8_SCHED __builtin_amdgcn_sched_barrier(0)
; template <class Epi, class Sched, bool ALIGN_EPI = false, bool SP2 = false>
; __device__ __forceinline__ void gemm_phase(PG8_LAS unsigned char* lds, const Gemm g, const Sched& S, const Epi& E) {
;     ...
;             PG8_LDA(At, 1, 1); PG8_STAGEB(PG8_SB(1, 0), b3, voffB); PG8_STAGEB(PG8_SB(1, 1), b3 + hstep, voffB); PG8_STAGEA(PG8_SA(1, 0), a3, voffA);
;             PG8_WAIT_V(8); PG8_WAIT_L(0); PG8_BAR; PG8_MMA(1, 0, At, B0); PG8_MMA(1, 1, At, B1); PG8_BAR; PG8_SCHED;
;     ...
;         if constexpr (ALIGN_EPI) { if (wr == 0) PG8_BAR; }
	s_add_i32 s34, s93, s11
	v_lshl_add_u64 v[220:221], v[220:221], 0, s[54:55]
	s_mov_b32 m0, s34
	ds_read_b128 v[188:191], v154 offset:49152
	ds_read_b128 v[192:195], v154 offset:50176
	ds_read_b128 v[196:199], v154 offset:51200
	ds_read_b128 v[200:203], v154 offset:52224
	ds_read_b128 v[204:207], v154 offset:53248
	ds_read_b128 v[208:211], v154 offset:54272
	ds_read_b128 v[212:215], v154 offset:55296
	ds_read_b128 v[216:219], v154 offset:56320
	global_load_lds_dwordx4 v[220:221], off
	s_add_i32 m0, s34, 0x2000
	s_add_u32 s34, s74, 0x80080
	v_lshl_add_u64 v[220:221], v[222:223], 0, s[54:55]
	s_addc_u32 s35, s75, 0
	s_add_i32 s74, s94, s11
	global_load_lds_dwordx4 v[220:221], off
	v_lshl_add_u64 v[220:221], s[34:35], 0, v[134:135]
	s_mov_b32 m0, s74
	s_nop 0
	global_load_lds_dwordx4 v[220:221], off
	v_lshl_add_u64 v[220:221], s[34:35], 0, v[130:131]
	s_add_i32 m0, s74, 0x2000
	s_nop 0
	global_load_lds_dwordx4 v[220:221], off
	v_lshl_add_u64 v[220:221], v[224:225], 0, s[54:55]
	s_mov_b32 m0, s82
	s_nop 0
	global_load_lds_dwordx4 v[220:221], off
	v_lshl_add_u64 v[220:221], v[226:227], 0, s[54:55]
	s_mov_b32 m0, s83
	s_nop 0
	global_load_lds_dwordx4 v[220:221], off
	s_waitcnt vmcnt(8)
	s_waitcnt lgkmcnt(0)
	s_barrier
	s_setprio 1
	s_waitcnt lgkmcnt(0)
	.p2align 3
	v_mfma_f32_16x16x32_bf16 v[62:65], v[156:159], v[188:191], v[62:65]
	v_mfma_f32_16x16x32_bf16 v[58:61], v[164:167], v[188:191], v[58:61]
	v_mfma_f32_16x16x32_bf16 v[54:57], v[156:159], v[196:199], v[54:57]
	v_mfma_f32_16x16x32_bf16 v[46:49], v[164:167], v[196:199], v[46:49]
	v_mfma_f32_16x16x32_bf16 v[38:41], v[156:159], v[204:207], v[38:41]
	v_mfma_f32_16x16x32_bf16 v[30:33], v[164:167], v[204:207], v[30:33]
	v_mfma_f32_16x16x32_bf16 v[22:25], v[156:159], v[212:215], v[22:25]
	v_mfma_f32_16x16x32_bf16 v[14:17], v[164:167], v[212:215], v[14:17]
	v_mfma_f32_16x16x32_bf16 v[62:65], v[160:163], v[192:195], v[62:65]
	v_mfma_f32_16x16x32_bf16 v[58:61], v[168:171], v[192:195], v[58:61]
	v_mfma_f32_16x16x32_bf16 v[54:57], v[160:163], v[200:203], v[54:57]
	v_mfma_f32_16x16x32_bf16 v[46:49], v[168:171], v[200:203], v[46:49]
	v_mfma_f32_16x16x32_bf16 v[38:41], v[160:163], v[208:211], v[38:41]
	v_mfma_f32_16x16x32_bf16 v[30:33], v[168:171], v[208:211], v[30:33]
	v_mfma_f32_16x16x32_bf16 v[22:25], v[160:163], v[216:219], v[22:25]
	v_mfma_f32_16x16x32_bf16 v[14:17], v[168:171], v[216:219], v[14:17]
	s_setprio 0
	s_setprio 1
	.p2align 3
	v_mfma_f32_16x16x32_bf16 v[50:53], v[172:175], v[188:191], v[50:53]
	v_mfma_f32_16x16x32_bf16 v[42:45], v[180:183], v[188:191], v[42:45]
	v_mfma_f32_16x16x32_bf16 v[34:37], v[172:175], v[196:199], v[34:37]
	v_mfma_f32_16x16x32_bf16 v[26:29], v[180:183], v[196:199], v[26:29]
	v_mfma_f32_16x16x32_bf16 v[18:21], v[172:175], v[204:207], v[18:21]
	v_mfma_f32_16x16x32_bf16 v[10:13], v[180:183], v[204:207], v[10:13]
	v_mfma_f32_16x16x32_bf16 v[6:9], v[172:175], v[212:215], v[6:9]
	v_mfma_f32_16x16x32_bf16 v[2:5], v[180:183], v[212:215], v[2:5]
	v_mfma_f32_16x16x32_bf16 v[50:53], v[176:179], v[192:195], v[50:53]
	v_mfma_f32_16x16x32_bf16 v[42:45], v[184:187], v[192:195], v[42:45]
	v_mfma_f32_16x16x32_bf16 v[34:37], v[176:179], v[200:203], v[34:37]
	v_mfma_f32_16x16x32_bf16 v[26:29], v[184:187], v[200:203], v[26:29]
	v_mfma_f32_16x16x32_bf16 v[18:21], v[176:179], v[208:211], v[18:21]
	v_mfma_f32_16x16x32_bf16 v[10:13], v[184:187], v[208:211], v[10:13]
	v_mfma_f32_16x16x32_bf16 v[6:9], v[176:179], v[216:219], v[6:9]
	v_mfma_f32_16x16x32_bf16 v[2:5], v[184:187], v[216:219], v[2:5]
	s_setprio 0
	s_barrier
	s_add_u32 s72, s72, 0x100
	s_addc_u32 s73, s73, 0
	s_mov_b32 s74, s92
	s_cbranch_vccz .LBB0_295
	s_and_b64 vcc, exec, s[56:57]
	s_cbranch_vccz .LBB0_298
	s_barrier

; #define PG8_STAGEA(bufoff, gbase, voff) PG8_STAGE_X(bufoff, gbase, voff, PG8_AUX_A)
; #define PG8_STAGEB(bufoff, gbase, voff) PG8_STAGE_X(bufoff, gbase, voff, PG8_AUX_B)
; #define PG8_LDA(dst, b, h) do { _Pragma("unroll") for (int m = 0; m < 4; ++m) _Pragma("unroll") for (int k = 0; k < 2; ++k) dst[m][k] = *(const PG8_LAS bf16x8*)(lds + PG8_SA(b, h) + aoff + m * 2048 + k * 1024); } while (0)
; #define PG8_LDB(dst, b, h) do { _Pragma("unroll") for (int n = 0; n < 2; ++n) _Pragma("unroll") for (int k = 0; k < 2; ++k) dst[n][k] = *(const PG8_LAS bf16x8*)(lds + PG8_SB(b, h) + boff + n * 2048 + k * 1024); } while (0)
; #define PG8_WAIT_V(n) asm volatile("s_waitcnt vmcnt(" #n ")" ::: "memory")
; #define PG8_WAIT_L(n) asm volatile("s_waitcnt lgkmcnt(" #n ")" ::: "memory")
; template <class Epi, class Sched, bool ALIGN_EPI = false, bool SP2 = false>
; __device__ __forceinline__ void gemm_phase(PG8_LAS unsigned char* lds, const Gemm g, const Sched& S, const Epi& E) {
;     ...
;             const bool last = (t == nt - 2);
;             if constexpr (HasMid<Epi>::value) { if (t == ns) E.mid(acc, cur, wr, wc, fr, fq); }
;             const char* sA1 = (t + 1 >= ns) ? cA2 : cA; const char* sA2 = (t + 2 >= ns) ? cA2 : cA; const char* sB2 = (t + 2 >= ns) ? cB2 : cB;
;             const char* a1 = sA1 + (size_t)(t + 1) * kstep;
;             const char* a2 = last ? nA : sA2 + (size_t)(t + 2) * kstep; const char* b2 = last ? nB : sB2 + (size_t)(t + 2) * kstep;
;             const char* a3 = a2 + kstep; const char* b3 = b2 + kstep;
;             if (last && has_next) S.a_ready(nxt);
;             if constexpr (SP2) {
;             PG8_LDB(B0, 0, 0); PG8_LDB(B1, 0, 1); PG8_SCHED; PG8_LDA(At, 0, 0); PG8_STAGEA(PG8_SA(1, 1), a1 + hstep, voffA);
;             PG8_WAIT_V(8); PG8_WAIT_L(0); PG8_BAR; PG8_MMA(0, 0, At, B0); PG8_MMA(0, 1, At, B1); PG8_BAR; PG8_SCHED;
;             PG8_LDA(At, 0, 1); PG8_STAGEB(PG8_SB(0, 0), b2, voffB); PG8_STAGEB(PG8_SB(0, 1), b2 + hstep, voffB); PG8_STAGEA(PG8_SA(0, 0), a2, voffA);
;             PG8_WAIT_V(8); PG8_WAIT_L(0); PG8_BAR; PG8_MMA(1, 0, At, B0); PG8_MMA(1, 1, At, B1); PG8_BAR; PG8_SCHED;
;             PG8_LDB(B0, 1, 0); PG8_LDB(B1, 1, 1); PG8_SCHED; PG8_LDA(At, 1, 0); PG8_STAGEA(PG8_SA(0, 1), a2 + hstep, voffA);
;             PG8_WAIT_V(8); PG8_WAIT_L(0); PG8_BAR; PG8_MMA(0, 0, At, B0); PG8_MMA(0, 1, At, B1); PG8_BAR; PG8_SCHED;
.LBB0_564:
	s_add_i32 s26, s26, 2
	s_cmp_gt_u32 s26, 29
	s_cselect_b32 s80, vcc_lo, s76
	s_cselect_b32 s27, s9, s75
	s_cselect_b32 s34, s8, s74
	s_cselect_b32 s35, vcc_hi, s77
	s_add_u32 s80, s80, s78
	s_addc_u32 s35, s35, s79
	v_add_u32_e32 v3, s11, v162
	s_add_u32 s80, s80, 0x100
	ds_read_b128 v[134:137], v3
	ds_read_b128 v[138:141], v3 offset:1024
	ds_read_b128 v[166:169], v3 offset:2048
	ds_read_b128 v[170:173], v3 offset:3072
	v_add_u32_e32 v3, s90, v162
	s_addc_u32 s81, s35, 0
	ds_read_b128 v[174:177], v3
	ds_read_b128 v[178:181], v3 offset:1024
	ds_read_b128 v[182:185], v3 offset:2048
	ds_read_b128 v[186:189], v3 offset:3072
	s_add_u32 s34, s34, s78
	s_addc_u32 s27, s27, s79
	s_add_u32 s36, s34, 0x100
	s_addc_u32 s27, s27, 0
	s_cmp_gt_u32 s26, 31
	s_cselect_b32 s34, vcc_lo, s76
	s_cselect_b32 s35, vcc_hi, s77
	s_cmpk_eq_i32 s78, 0x1f00
	s_cselect_b32 s83, s69, s81
	s_cselect_b32 s82, s4, s80
	s_cselect_b32 s81, s5, s27
	s_cselect_b32 s80, s67, s36
	v_lshl_add_u64 v[4:5], s[34:35], 0, v[150:151]
	v_lshl_add_u64 v[4:5], v[4:5], 0, s[78:79]
	s_add_i32 m0, s86, 0xc000
	ds_read_b128 v[190:193], v164
	ds_read_b128 v[194:197], v164 offset:1024
	ds_read_b128 v[198:201], v164 offset:2048
	ds_read_b128 v[202:205], v164 offset:3072
	ds_read_b128 v[206:209], v164 offset:4096
	ds_read_b128 v[210:213], v164 offset:5120
	ds_read_b128 v[214:217], v164 offset:6144
	ds_read_b128 v[218:221], v164 offset:7168
	global_load_lds_dwordx4 v[4:5], off
	v_lshl_add_u64 v[4:5], s[34:35], 0, v[152:153]
	v_lshl_add_u64 v[4:5], v[4:5], 0, s[78:79]
	s_add_i32 m0, s86, 0xe000
	s_nop 0
	global_load_lds_dwordx4 v[4:5], off
	s_waitcnt vmcnt(8)
	s_waitcnt lgkmcnt(0)
	s_barrier
	s_setprio 1
	s_waitcnt lgkmcnt(0)
	.p2align 3
	v_mfma_f32_16x16x32_bf16 v[130:133], v[134:137], v[190:193], v[130:133]
	v_mfma_f32_16x16x32_bf16 v[126:129], v[166:169], v[190:193], v[126:129]
	v_mfma_f32_16x16x32_bf16 v[114:117], v[134:137], v[198:201], v[114:117]
	v_mfma_f32_16x16x32_bf16 v[110:113], v[166:169], v[198:201], v[110:113]
	v_mfma_f32_16x16x32_bf16 v[98:101], v[134:137], v[206:209], v[98:101]
	v_mfma_f32_16x16x32_bf16 v[94:97], v[166:169], v[206:209], v[94:97]
	v_mfma_f32_16x16x32_bf16 v[82:85], v[134:137], v[214:217], v[82:85]
	v_mfma_f32_16x16x32_bf16 v[78:81], v[166:169], v[214:217], v[78:81]
	v_mfma_f32_16x16x32_bf16 v[130:133], v[138:141], v[194:197], v[130:133]
	v_mfma_f32_16x16x32_bf16 v[126:129], v[170:173], v[194:197], v[126:129]
	v_mfma_f32_16x16x32_bf16 v[114:117], v[138:141], v[202:205], v[114:117]
	v_mfma_f32_16x16x32_bf16 v[110:113], v[170:173], v[202:205], v[110:113]
	v_mfma_f32_16x16x32_bf16 v[98:101], v[138:141], v[210:213], v[98:101]
	v_mfma_f32_16x16x32_bf16 v[94:97], v[170:173], v[210:213], v[94:97]
	v_mfma_f32_16x16x32_bf16 v[82:85], v[138:141], v[218:221], v[82:85]
	v_mfma_f32_16x16x32_bf16 v[78:81], v[170:173], v[218:221], v[78:81]
	s_setprio 0
	s_setprio 1
	.p2align 3
	v_mfma_f32_16x16x32_bf16 v[122:125], v[174:177], v[190:193], v[122:125]
	v_mfma_f32_16x16x32_bf16 v[118:121], v[182:185], v[190:193], v[118:121]
	v_mfma_f32_16x16x32_bf16 v[106:109], v[174:177], v[198:201], v[106:109]
	v_mfma_f32_16x16x32_bf16 v[102:105], v[182:185], v[198:201], v[102:105]
	v_mfma_f32_16x16x32_bf16 v[90:93], v[174:177], v[206:209], v[90:93]
	v_mfma_f32_16x16x32_bf16 v[86:89], v[182:185], v[206:209], v[86:89]
	v_mfma_f32_16x16x32_bf16 v[74:77], v[174:177], v[214:217], v[74:77]
	v_mfma_f32_16x16x32_bf16 v[70:73], v[182:185], v[214:217], v[70:73]
	v_mfma_f32_16x16x32_bf16 v[122:125], v[178:181], v[194:197], v[122:125]
	v_mfma_f32_16x16x32_bf16 v[118:121], v[186:189], v[194:197], v[118:121]
	v_mfma_f32_16x16x32_bf16 v[106:109], v[178:181], v[202:205], v[106:109]
	v_mfma_f32_16x16x32_bf16 v[102:105], v[186:189], v[202:205], v[102:105]
	v_mfma_f32_16x16x32_bf16 v[90:93], v[178:181], v[210:213], v[90:93]
	v_mfma_f32_16x16x32_bf16 v[86:89], v[186:189], v[210:213], v[86:89]
	v_mfma_f32_16x16x32_bf16 v[74:77], v[178:181], v[218:221], v[74:77]
	v_mfma_f32_16x16x32_bf16 v[70:73], v[186:189], v[218:221], v[70:73]
	s_setprio 0
	s_barrier
	s_add_i32 s27, s11, s84
	v_lshl_add_u64 v[222:223], s[80:81], 0, v[146:147]
	s_mov_b32 m0, s27
	ds_read_b128 v[190:193], v164 offset:16384
	ds_read_b128 v[194:197], v164 offset:17408
	ds_read_b128 v[198:201], v164 offset:18432
	ds_read_b128 v[202:205], v164 offset:19456
	ds_read_b128 v[206:209], v164 offset:20480
	ds_read_b128 v[210:213], v164 offset:21504
	ds_read_b128 v[214:217], v164 offset:22528
	ds_read_b128 v[218:221], v164 offset:23552
	global_load_lds_dwordx4 v[222:223], off
	s_add_i32 m0, s27, 0x2000
	s_add_u32 s34, s80, 0x80000
	v_lshl_add_u64 v[224:225], s[80:81], 0, v[142:143]
	s_addc_u32 s35, s81, 0
	s_add_i32 s27, s90, s84
	global_load_lds_dwordx4 v[224:225], off
	v_lshl_add_u64 v[4:5], s[34:35], 0, v[146:147]
	s_mov_b32 m0, s27
	v_lshl_add_u64 v[226:227], s[82:83], 0, v[148:149]
	global_load_lds_dwordx4 v[4:5], off
	v_lshl_add_u64 v[4:5], s[34:35], 0, v[142:143]
	s_add_i32 m0, s27, 0x2000
	v_lshl_add_u64 v[228:229], s[82:83], 0, v[144:145]
	global_load_lds_dwordx4 v[4:5], off
	s_mov_b32 m0, s86
	s_nop 0
	global_load_lds_dwordx4 v[226:227], off
	s_mov_b32 m0, s87
	s_nop 0
	global_load_lds_dwordx4 v[228:229], off
	s_waitcnt vmcnt(8)
	s_waitcnt lgkmcnt(0)
	s_barrier
; #define PG8_STAGEA(bufoff, gbase, voff) PG8_STAGE_X(bufoff, gbase, voff, PG8_AUX_A)
; #define PG8_LDA(dst, b, h) do { _Pragma("unroll") for (int m = 0; m < 4; ++m) _Pragma("unroll") for (int k = 0; k < 2; ++k) dst[m][k] = *(const PG8_LAS bf16x8*)(lds + PG8_SA(b, h) + aoff + m * 2048 + k * 1024); } while (0)
; #define PG8_LDB(dst, b, h) do { _Pragma("unroll") for (int n = 0; n < 2; ++n) _Pragma("unroll") for (int k = 0; k < 2; ++k) dst[n][k] = *(const PG8_LAS bf16x8*)(lds + PG8_SB(b, h) + boff + n * 2048 + k * 1024); } while (0)
; #define PG8_MMA(ai, bj, At, Bt) do { __builtin_amdgcn_s_setprio(1); _Pragma("unroll") for (int m = 0; m < 4; ++m) _Pragma("unroll") for (int n = 0; n < 2; ++n) _Pragma("unroll") for (int k = 0; k < 2; ++k) \
;         acc[ai][bj][m][n] = __builtin_amdgcn_mfma_f32_16x16x32_bf16(Bt[n][k], At[m][k], acc[ai][bj][m][n], 0, 0, 0); __builtin_amdgcn_s_setprio(0); } while (0)
; #define PG8_WAIT_V(n) asm volatile("s_waitcnt vmcnt(" #n ")" ::: "memory")
; #define PG8_WAIT_L(n) asm volatile("s_waitcnt lgkmcnt(" #n ")" ::: "memory")
; #define PG8_BAR __builtin_amdgcn_s_barrier()
; #define PG8_SCHED __builtin_amdgcn_sched_barrier(0)
; template <class Epi, class Sched, bool ALIGN_EPI = false, bool SP2 = false>
; __device__ __forceinline__ void gemm_phase(PG8_LAS unsigned char* lds, const Gemm g, const Sched& S, const Epi& E) {
;     ...
;             PG8_WAIT_V(8); PG8_WAIT_L(0); PG8_BAR; PG8_MMA(1, 0, At, B0); PG8_MMA(1, 1, At, B1); PG8_BAR; PG8_SCHED;
;             PG8_LDB(B0, 1, 0); PG8_LDB(B1, 1, 1); PG8_SCHED; PG8_LDA(At, 1, 0); PG8_STAGEA(PG8_SA(0, 1), a2 + hstep, voffA);
;             PG8_WAIT_V(8); PG8_WAIT_L(0); PG8_BAR; PG8_MMA(0, 0, At, B0); PG8_MMA(0, 1, At, B1); PG8_BAR; PG8_SCHED;
	s_setprio 1
	s_waitcnt lgkmcnt(0)
	.p2align 3
	v_mfma_f32_16x16x32_bf16 v[66:69], v[134:137], v[190:193], v[66:69]
	v_mfma_f32_16x16x32_bf16 v[62:65], v[166:169], v[190:193], v[62:65]
	v_mfma_f32_16x16x32_bf16 v[50:53], v[134:137], v[198:201], v[50:53]
	v_mfma_f32_16x16x32_bf16 v[46:49], v[166:169], v[198:201], v[46:49]
	v_mfma_f32_16x16x32_bf16 v[34:37], v[134:137], v[206:209], v[34:37]
	v_mfma_f32_16x16x32_bf16 v[30:33], v[166:169], v[206:209], v[30:33]
	v_mfma_f32_16x16x32_bf16 v[18:21], v[134:137], v[214:217], v[18:21]
	v_mfma_f32_16x16x32_bf16 v[14:17], v[166:169], v[214:217], v[14:17]
	v_mfma_f32_16x16x32_bf16 v[66:69], v[138:141], v[194:197], v[66:69]
	v_mfma_f32_16x16x32_bf16 v[62:65], v[170:173], v[194:197], v[62:65]
	v_mfma_f32_16x16x32_bf16 v[50:53], v[138:141], v[202:205], v[50:53]
	v_mfma_f32_16x16x32_bf16 v[46:49], v[170:173], v[202:205], v[46:49]
	v_mfma_f32_16x16x32_bf16 v[34:37], v[138:141], v[210:213], v[34:37]
	v_mfma_f32_16x16x32_bf16 v[30:33], v[170:173], v[210:213], v[30:33]
	v_mfma_f32_16x16x32_bf16 v[18:21], v[138:141], v[218:221], v[18:21]
	v_mfma_f32_16x16x32_bf16 v[14:17], v[170:173], v[218:221], v[14:17]
	s_setprio 0
	s_setprio 1
	.p2align 3
	v_mfma_f32_16x16x32_bf16 v[58:61], v[174:177], v[190:193], v[58:61]
	v_mfma_f32_16x16x32_bf16 v[54:57], v[182:185], v[190:193], v[54:57]
	v_mfma_f32_16x16x32_bf16 v[42:45], v[174:177], v[198:201], v[42:45]
	v_mfma_f32_16x16x32_bf16 v[38:41], v[182:185], v[198:201], v[38:41]
	v_mfma_f32_16x16x32_bf16 v[26:29], v[174:177], v[206:209], v[26:29]
	v_mfma_f32_16x16x32_bf16 v[22:25], v[182:185], v[206:209], v[22:25]
	v_mfma_f32_16x16x32_bf16 v[10:13], v[174:177], v[214:217], v[10:13]
	v_mfma_f32_16x16x32_bf16 v[4:7], v[182:185], v[214:217], v[6:9]
	v_mfma_f32_16x16x32_bf16 v[58:61], v[178:181], v[194:197], v[58:61]
	v_mfma_f32_16x16x32_bf16 v[54:57], v[186:189], v[194:197], v[54:57]
	v_mfma_f32_16x16x32_bf16 v[42:45], v[178:181], v[202:205], v[42:45]
	v_mfma_f32_16x16x32_bf16 v[38:41], v[186:189], v[202:205], v[38:41]
	v_mfma_f32_16x16x32_bf16 v[26:29], v[178:181], v[210:213], v[26:29]
	v_mfma_f32_16x16x32_bf16 v[22:25], v[186:189], v[210:213], v[22:25]
	v_mfma_f32_16x16x32_bf16 v[10:13], v[178:181], v[218:221], v[10:13]
	v_mfma_f32_16x16x32_bf16 v[4:7], v[186:189], v[218:221], v[4:7]
	s_setprio 0
	s_barrier
	s_add_i32 s27, 0, 0x18000
	v_add_u32_e32 v3, s27, v162
	s_add_i32 s36, 0, 0x1c000
	ds_read_b128 v[134:137], v3
	ds_read_b128 v[138:141], v3 offset:1024
	ds_read_b128 v[166:169], v3 offset:2048
	ds_read_b128 v[170:173], v3 offset:3072
	v_add_u32_e32 v3, s36, v162
	ds_read_b128 v[174:177], v3
	ds_read_b128 v[178:181], v3 offset:1024
	ds_read_b128 v[182:185], v3 offset:2048
	ds_read_b128 v[186:189], v3 offset:3072
	s_add_u32 s34, s82, 0x80000
	s_addc_u32 s35, s83, 0
	s_mov_b32 m0, s91
	v_lshl_add_u64 v[8:9], s[34:35], 0, v[148:149]
	ds_read_b128 v[190:193], v164 offset:32768
	ds_read_b128 v[194:197], v164 offset:33792
	ds_read_b128 v[198:201], v164 offset:34816
	ds_read_b128 v[202:205], v164 offset:35840
	ds_read_b128 v[206:209], v164 offset:36864
	ds_read_b128 v[210:213], v164 offset:37888
	ds_read_b128 v[214:217], v164 offset:38912
	ds_read_b128 v[218:221], v164 offset:39936
	global_load_lds_dwordx4 v[8:9], off
	v_lshl_add_u64 v[8:9], s[34:35], 0, v[144:145]
	s_mov_b32 m0, s92
	s_nop 0
	global_load_lds_dwordx4 v[8:9], off
	s_waitcnt vmcnt(8)
	s_waitcnt lgkmcnt(0)
	s_barrier
	s_setprio 1
	s_waitcnt lgkmcnt(0)
	.p2align 3
	v_mfma_f32_16x16x32_bf16 v[130:133], v[134:137], v[190:193], v[130:133]
	v_mfma_f32_16x16x32_bf16 v[126:129], v[166:169], v[190:193], v[126:129]
	v_mfma_f32_16x16x32_bf16 v[114:117], v[134:137], v[198:201], v[114:117]
	v_mfma_f32_16x16x32_bf16 v[110:113], v[166:169], v[198:201], v[110:113]
	v_mfma_f32_16x16x32_bf16 v[98:101], v[134:137], v[206:209], v[98:101]
	v_mfma_f32_16x16x32_bf16 v[94:97], v[166:169], v[206:209], v[94:97]
	v_mfma_f32_16x16x32_bf16 v[82:85], v[134:137], v[214:217], v[82:85]
	v_mfma_f32_16x16x32_bf16 v[78:81], v[166:169], v[214:217], v[78:81]
	v_mfma_f32_16x16x32_bf16 v[130:133], v[138:141], v[194:197], v[130:133]
	v_mfma_f32_16x16x32_bf16 v[126:129], v[170:173], v[194:197], v[126:129]
	v_mfma_f32_16x16x32_bf16 v[114:117], v[138:141], v[202:205], v[114:117]
	v_mfma_f32_16x16x32_bf16 v[110:113], v[170:173], v[202:205], v[110:113]
	v_mfma_f32_16x16x32_bf16 v[98:101], v[138:141], v[210:213], v[98:101]
	v_mfma_f32_16x16x32_bf16 v[94:97], v[170:173], v[210:213], v[94:97]
	v_mfma_f32_16x16x32_bf16 v[82:85], v[138:141], v[218:221], v[82:85]
	v_mfma_f32_16x16x32_bf16 v[78:81], v[170:173], v[218:221], v[78:81]
	s_setprio 0
	s_setprio 1
	.p2align 3
	v_mfma_f32_16x16x32_bf16 v[122:125], v[174:177], v[190:193], v[122:125]
	v_mfma_f32_16x16x32_bf16 v[118:121], v[182:185], v[190:193], v[118:121]
	v_mfma_f32_16x16x32_bf16 v[106:109], v[174:177], v[198:201], v[106:109]
	v_mfma_f32_16x16x32_bf16 v[102:105], v[182:185], v[198:201], v[102:105]
	v_mfma_f32_16x16x32_bf16 v[90:93], v[174:177], v[206:209], v[90:93]
	v_mfma_f32_16x16x32_bf16 v[86:89], v[182:185], v[206:209], v[86:89]
	v_mfma_f32_16x16x32_bf16 v[74:77], v[174:177], v[214:217], v[74:77]
	v_mfma_f32_16x16x32_bf16 v[70:73], v[182:185], v[214:217], v[70:73]
	v_mfma_f32_16x16x32_bf16 v[122:125], v[178:181], v[194:197], v[122:125]
	v_mfma_f32_16x16x32_bf16 v[118:121], v[186:189], v[194:197], v[118:121]
	v_mfma_f32_16x16x32_bf16 v[106:109], v[178:181], v[202:205], v[106:109]
	v_mfma_f32_16x16x32_bf16 v[102:105], v[186:189], v[202:205], v[102:105]
	v_mfma_f32_16x16x32_bf16 v[90:93], v[178:181], v[210:213], v[90:93]
	v_mfma_f32_16x16x32_bf16 v[86:89], v[186:189], v[210:213], v[86:89]
	v_mfma_f32_16x16x32_bf16 v[74:77], v[178:181], v[218:221], v[74:77]
	v_mfma_f32_16x16x32_bf16 v[70:73], v[186:189], v[218:221], v[70:73]
	s_setprio 0
	s_barrier
; #define PG8_STAGEA(bufoff, gbase, voff) PG8_STAGE_X(bufoff, gbase, voff, PG8_AUX_A)
; #define PG8_STAGEB(bufoff, gbase, voff) PG8_STAGE_X(bufoff, gbase, voff, PG8_AUX_B)
; #define PG8_LDA(dst, b, h) do { _Pragma("unroll") for (int m = 0; m < 4; ++m) _Pragma("unroll") for (int k = 0; k < 2; ++k) dst[m][k] = *(const PG8_LAS bf16x8*)(lds + PG8_SA(b, h) + aoff + m * 2048 + k * 1024); } while (0)
; #define PG8_MMA(ai, bj, At, Bt) do { __builtin_amdgcn_s_setprio(1); _Pragma("unroll") for (int m = 0; m < 4; ++m) _Pragma("unroll") for (int n = 0; n < 2; ++n) _Pragma("unroll") for (int k = 0; k < 2; ++k) \
;         acc[ai][bj][m][n] = __builtin_amdgcn_mfma_f32_16x16x32_bf16(Bt[n][k], At[m][k], acc[ai][bj][m][n], 0, 0, 0); __builtin_amdgcn_s_setprio(0); } while (0)
; #define PG8_WAIT_V(n) asm volatile("s_waitcnt vmcnt(" #n ")" ::: "memory")
; #define PG8_WAIT_L(n) asm volatile("s_waitcnt lgkmcnt(" #n ")" ::: "memory")
; #define PG8_BAR __builtin_amdgcn_s_barrier()
; #define PG8_SCHED __builtin_amdgcn_sched_barrier(0)
; template <class Epi, class Sched, bool ALIGN_EPI = false, bool SP2 = false>
; __device__ __forceinline__ void gemm_phase(PG8_LAS unsigned char* lds, const Gemm g, const Sched& S, const Epi& E) {
;     ...
;             PG8_LDA(At, 1, 1); PG8_STAGEB(PG8_SB(1, 0), b3, voffB); PG8_STAGEB(PG8_SB(1, 1), b3 + hstep, voffB); PG8_STAGEA(PG8_SA(1, 0), a3, voffA);
;             PG8_WAIT_V(8); PG8_WAIT_L(0); PG8_BAR; PG8_MMA(1, 0, At, B0); PG8_MMA(1, 1, At, B1); PG8_BAR; PG8_SCHED;
	s_add_i32 s27, s27, s84
	v_lshl_add_u64 v[8:9], v[222:223], 0, s[56:57]
	s_mov_b32 m0, s27
	ds_read_b128 v[190:193], v164 offset:49152
	ds_read_b128 v[194:197], v164 offset:50176
	ds_read_b128 v[198:201], v164 offset:51200
	ds_read_b128 v[202:205], v164 offset:52224
	ds_read_b128 v[206:209], v164 offset:53248
	ds_read_b128 v[210:213], v164 offset:54272
	ds_read_b128 v[214:217], v164 offset:55296
	ds_read_b128 v[218:221], v164 offset:56320
	global_load_lds_dwordx4 v[8:9], off
	s_add_i32 m0, s27, 0x2000
	s_add_u32 s34, s80, 0x80080
	v_lshl_add_u64 v[8:9], v[224:225], 0, s[56:57]
	s_addc_u32 s35, s81, 0
	s_add_i32 s27, s36, s84
	global_load_lds_dwordx4 v[8:9], off
	v_lshl_add_u64 v[8:9], s[34:35], 0, v[146:147]
	s_mov_b32 m0, s27
	s_nop 0
	global_load_lds_dwordx4 v[8:9], off
	v_lshl_add_u64 v[8:9], s[34:35], 0, v[142:143]
	s_add_i32 m0, s27, 0x2000
	s_nop 0
	global_load_lds_dwordx4 v[8:9], off
	v_lshl_add_u64 v[8:9], v[226:227], 0, s[56:57]
	s_mov_b32 m0, s95
	s_nop 0
	global_load_lds_dwordx4 v[8:9], off
	v_lshl_add_u64 v[8:9], v[228:229], 0, s[56:57]
	s_mov_b32 m0, s96
	s_nop 0
	global_load_lds_dwordx4 v[8:9], off
	s_waitcnt vmcnt(8)
	s_waitcnt lgkmcnt(0)
	s_barrier
	s_setprio 1
	s_waitcnt lgkmcnt(0)
	.p2align 3
	v_mfma_f32_16x16x32_bf16 v[66:69], v[134:137], v[190:193], v[66:69]
	v_mfma_f32_16x16x32_bf16 v[62:65], v[166:169], v[190:193], v[62:65]
	v_mfma_f32_16x16x32_bf16 v[50:53], v[134:137], v[198:201], v[50:53]
	v_mfma_f32_16x16x32_bf16 v[46:49], v[166:169], v[198:201], v[46:49]
	v_mfma_f32_16x16x32_bf16 v[34:37], v[134:137], v[206:209], v[34:37]
	v_mfma_f32_16x16x32_bf16 v[30:33], v[166:169], v[206:209], v[30:33]
	v_mfma_f32_16x16x32_bf16 v[18:21], v[134:137], v[214:217], v[18:21]
	v_mfma_f32_16x16x32_bf16 v[14:17], v[166:169], v[214:217], v[14:17]
	v_mfma_f32_16x16x32_bf16 v[66:69], v[138:141], v[194:197], v[66:69]
	v_mfma_f32_16x16x32_bf16 v[62:65], v[170:173], v[194:197], v[62:65]
	v_mfma_f32_16x16x32_bf16 v[50:53], v[138:141], v[202:205], v[50:53]
	v_mfma_f32_16x16x32_bf16 v[46:49], v[170:173], v[202:205], v[46:49]
	v_mfma_f32_16x16x32_bf16 v[34:37], v[138:141], v[210:213], v[34:37]
	v_mfma_f32_16x16x32_bf16 v[30:33], v[170:173], v[210:213], v[30:33]
	v_mfma_f32_16x16x32_bf16 v[18:21], v[138:141], v[218:221], v[18:21]
	v_mfma_f32_16x16x32_bf16 v[14:17], v[170:173], v[218:221], v[14:17]
	s_setprio 0
	s_setprio 1
	.p2align 3
	v_mfma_f32_16x16x32_bf16 v[58:61], v[174:177], v[190:193], v[58:61]
	v_mfma_f32_16x16x32_bf16 v[54:57], v[182:185], v[190:193], v[54:57]
	v_mfma_f32_16x16x32_bf16 v[42:45], v[174:177], v[198:201], v[42:45]
	v_mfma_f32_16x16x32_bf16 v[38:41], v[182:185], v[198:201], v[38:41]
	v_mfma_f32_16x16x32_bf16 v[26:29], v[174:177], v[206:209], v[26:29]
	v_mfma_f32_16x16x32_bf16 v[22:25], v[182:185], v[206:209], v[22:25]
	v_mfma_f32_16x16x32_bf16 v[8:11], v[174:177], v[214:217], v[10:13]
	v_mfma_f32_16x16x32_bf16 v[4:7], v[182:185], v[214:217], v[4:7]
	v_mfma_f32_16x16x32_bf16 v[58:61], v[178:181], v[194:197], v[58:61]
	v_mfma_f32_16x16x32_bf16 v[54:57], v[186:189], v[194:197], v[54:57]
	v_mfma_f32_16x16x32_bf16 v[42:45], v[178:181], v[202:205], v[42:45]
	v_mfma_f32_16x16x32_bf16 v[38:41], v[186:189], v[202:205], v[38:41]
	v_mfma_f32_16x16x32_bf16 v[26:29], v[178:181], v[210:213], v[26:29]
	v_mfma_f32_16x16x32_bf16 v[22:25], v[186:189], v[210:213], v[22:25]
	v_mfma_f32_16x16x32_bf16 v[10:13], v[178:181], v[218:221], v[8:11]
	v_mfma_f32_16x16x32_bf16 v[6:9], v[186:189], v[218:221], v[4:7]
	s_setprio 0
	s_barrier
	s_add_u32 s78, s78, 0x100
	s_addc_u32 s79, s79, 0
	s_cmp_gt_u32 s26, 61
	s_cbranch_scc1 .LBB0_567

; #define PG8_STAGEA(bufoff, gbase, voff) PG8_STAGE_X(bufoff, gbase, voff, PG8_AUX_A)
; #define PG8_STAGEB(bufoff, gbase, voff) PG8_STAGE_X(bufoff, gbase, voff, PG8_AUX_B)
; #define PG8_LDA(dst, b, h) do { _Pragma("unroll") for (int m = 0; m < 4; ++m) _Pragma("unroll") for (int k = 0; k < 2; ++k) dst[m][k] = *(const PG8_LAS bf16x8*)(lds + PG8_SA(b, h) + aoff + m * 2048 + k * 1024); } while (0)
; #define PG8_LDB(dst, b, h) do { _Pragma("unroll") for (int n = 0; n < 2; ++n) _Pragma("unroll") for (int k = 0; k < 2; ++k) dst[n][k] = *(const PG8_LAS bf16x8*)(lds + PG8_SB(b, h) + boff + n * 2048 + k * 1024); } while (0)
; #define PG8_WAIT_V(n) asm volatile("s_waitcnt vmcnt(" #n ")" ::: "memory")
; #define PG8_WAIT_L(n) asm volatile("s_waitcnt lgkmcnt(" #n ")" ::: "memory")
; template <class Epi, class Sched, bool ALIGN_EPI = false, bool SP2 = false>
; __device__ __forceinline__ void gemm_phase(PG8_LAS unsigned char* lds, const Gemm g, const Sched& S, const Epi& E) {
;     ...
;             const bool last = (t == nt - 2);
;             if constexpr (HasMid<Epi>::value) { if (t == ns) E.mid(acc, cur, wr, wc, fr, fq); }
;             const char* sA1 = (t + 1 >= ns) ? cA2 : cA; const char* sA2 = (t + 2 >= ns) ? cA2 : cA; const char* sB2 = (t + 2 >= ns) ? cB2 : cB;
;             const char* a1 = sA1 + (size_t)(t + 1) * kstep;
;             const char* a2 = last ? nA : sA2 + (size_t)(t + 2) * kstep; const char* b2 = last ? nB : sB2 + (size_t)(t + 2) * kstep;
;             const char* a3 = a2 + kstep; const char* b3 = b2 + kstep;
;             if (last && has_next) S.a_ready(nxt);
;             if constexpr (SP2) {
;             PG8_LDB(B0, 0, 0); PG8_LDB(B1, 0, 1); PG8_SCHED; PG8_LDA(At, 0, 0); PG8_STAGEA(PG8_SA(1, 1), a1 + hstep, voffA);
;             PG8_WAIT_V(8); PG8_WAIT_L(0); PG8_BAR; PG8_MMA(0, 0, At, B0); PG8_MMA(0, 1, At, B1); PG8_BAR; PG8_SCHED;
;             PG8_LDA(At, 0, 1); PG8_STAGEB(PG8_SB(0, 0), b2, voffB); PG8_STAGEB(PG8_SB(0, 1), b2 + hstep, voffB); PG8_STAGEA(PG8_SA(0, 0), a2, voffA);
;             PG8_WAIT_V(8); PG8_WAIT_L(0); PG8_BAR; PG8_MMA(1, 0, At, B0); PG8_MMA(1, 1, At, B1); PG8_BAR; PG8_SCHED;
;             PG8_LDB(B0, 1, 0); PG8_LDB(B1, 1, 1); PG8_SCHED; PG8_LDA(At, 1, 0); PG8_STAGEA(PG8_SA(0, 1), a2 + hstep, voffA);
;             PG8_WAIT_V(8); PG8_WAIT_L(0); PG8_BAR; PG8_MMA(0, 0, At, B0); PG8_MMA(0, 1, At, B1); PG8_BAR; PG8_SCHED;
.LBB0_643:
	s_add_i32 s97, s96, 2
	s_cmp_lt_u32 s96, 30
	s_cselect_b32 s37, s72, s50
	s_cselect_b32 s34, s71, s47
	s_cselect_b32 s35, s70, s46
	s_cselect_b32 s36, s73, s51
	s_add_u32 s37, s37, s74
	s_addc_u32 s36, s36, s75
	s_add_u32 s37, s37, 0xfff80080
	s_addc_u32 s36, s36, -1
	s_add_u32 s35, s35, s74
	s_addc_u32 s34, s34, s75
	s_add_u32 s35, s35, 0xfff80080
	s_addc_u32 s34, s34, -1
	s_cmp_eq_u32 s96, 30
	s_cselect_b32 s83, s61, s36
	s_cselect_b32 s82, s67, s37
	s_cselect_b32 s85, s59, s34
	s_cselect_b32 s84, s95, s35
	s_add_i32 s37, s93, s8
	s_add_i32 m0, s9, 0xc000
	s_add_i32 s36, s9, 0xe000
	s_add_i32 s38, s37, 0x2000
	s_add_u32 s86, s84, 0x80000
	ds_read_b128 v[82:85], v166
	ds_read_b128 v[90:93], v166 offset:1024
	ds_read_b128 v[94:97], v166 offset:2048
	ds_read_b128 v[158:161], v166 offset:3072
	ds_read_b128 v[170:173], v167
	ds_read_b128 v[174:177], v167 offset:1024
	ds_read_b128 v[178:181], v167 offset:2048
	ds_read_b128 v[182:185], v167 offset:3072
	s_addc_u32 s87, s85, 0
	s_add_i32 s39, s94, s8
	s_add_i32 s24, s39, 0x2000
	s_add_i32 s25, 0, 0x18000
	s_add_i32 vcc_hi, 0, 0x1c000
	s_add_u32 s80, s82, 0x80000
	s_addc_u32 s81, s83, 0
	s_add_i32 vcc_lo, s25, s8
	s_add_i32 s34, vcc_lo, 0x2000
	s_add_u32 s78, s84, 0x80080
	s_addc_u32 s79, s85, 0
	s_add_i32 s35, vcc_hi, s8
	s_add_i32 s28, s35, 0x2000
	s_add_u32 s76, s74, 0x100
	s_addc_u32 s77, s75, 0
	s_cmp_gt_u32 s96, 29
	v_lshl_add_u64 v[162:163], v[74:75], 0, s[74:75]
	ds_read_b128 v[186:189], v168
	ds_read_b128 v[190:193], v168 offset:1024
	ds_read_b128 v[194:197], v168 offset:2048
	ds_read_b128 v[198:201], v168 offset:3072
	ds_read_b128 v[202:205], v168 offset:4096
	ds_read_b128 v[206:209], v168 offset:5120
	ds_read_b128 v[210:213], v168 offset:6144
	ds_read_b128 v[214:217], v168 offset:7168
	global_load_lds_dwordx4 v[162:163], off
	v_lshl_add_u64 v[162:163], v[76:77], 0, s[74:75]
	s_mov_b32 m0, s36
	s_nop 0
	global_load_lds_dwordx4 v[162:163], off
	s_waitcnt vmcnt(8)
	s_waitcnt lgkmcnt(0)
	s_barrier
	s_setprio 1
	s_waitcnt lgkmcnt(0)
	.p2align 3
	v_mfma_f32_16x16x32_bf16 v[142:145], v[82:85], v[186:189], v[142:145]
	v_mfma_f32_16x16x32_bf16 v[138:141], v[94:97], v[186:189], v[138:141]
	v_mfma_f32_16x16x32_bf16 v[126:129], v[82:85], v[194:197], v[126:129]
	v_mfma_f32_16x16x32_bf16 v[122:125], v[94:97], v[194:197], v[122:125]
	v_mfma_f32_16x16x32_bf16 v[110:113], v[82:85], v[202:205], v[110:113]
	v_mfma_f32_16x16x32_bf16 v[106:109], v[94:97], v[202:205], v[106:109]
	v_mfma_f32_16x16x32_bf16 v[86:89], v[82:85], v[210:213], v[86:89]
	v_mfma_f32_16x16x32_bf16 v[78:81], v[94:97], v[210:213], v[78:81]
	v_mfma_f32_16x16x32_bf16 v[142:145], v[90:93], v[190:193], v[142:145]
	v_mfma_f32_16x16x32_bf16 v[138:141], v[158:161], v[190:193], v[138:141]
	v_mfma_f32_16x16x32_bf16 v[126:129], v[90:93], v[198:201], v[126:129]
	v_mfma_f32_16x16x32_bf16 v[122:125], v[158:161], v[198:201], v[122:125]
	v_mfma_f32_16x16x32_bf16 v[110:113], v[90:93], v[206:209], v[110:113]
	v_mfma_f32_16x16x32_bf16 v[106:109], v[158:161], v[206:209], v[106:109]
	v_mfma_f32_16x16x32_bf16 v[86:89], v[90:93], v[214:217], v[86:89]
	v_mfma_f32_16x16x32_bf16 v[78:81], v[158:161], v[214:217], v[78:81]
	s_setprio 0
	s_setprio 1
	.p2align 3
	v_mfma_f32_16x16x32_bf16 v[134:137], v[170:173], v[186:189], v[134:137]
	v_mfma_f32_16x16x32_bf16 v[130:133], v[178:181], v[186:189], v[130:133]
	v_mfma_f32_16x16x32_bf16 v[118:121], v[170:173], v[194:197], v[118:121]
	v_mfma_f32_16x16x32_bf16 v[114:117], v[178:181], v[194:197], v[114:117]
	v_mfma_f32_16x16x32_bf16 v[102:105], v[170:173], v[202:205], v[102:105]
	v_mfma_f32_16x16x32_bf16 v[98:101], v[178:181], v[202:205], v[98:101]
	v_mfma_f32_16x16x32_bf16 v[70:73], v[170:173], v[210:213], v[70:73]
	v_mfma_f32_16x16x32_bf16 v[66:69], v[178:181], v[210:213], v[66:69]
	v_mfma_f32_16x16x32_bf16 v[134:137], v[174:177], v[190:193], v[134:137]
	v_mfma_f32_16x16x32_bf16 v[130:133], v[182:185], v[190:193], v[130:133]
	v_mfma_f32_16x16x32_bf16 v[118:121], v[174:177], v[198:201], v[118:121]
	v_mfma_f32_16x16x32_bf16 v[114:117], v[182:185], v[198:201], v[114:117]
	v_mfma_f32_16x16x32_bf16 v[102:105], v[174:177], v[206:209], v[102:105]
	v_mfma_f32_16x16x32_bf16 v[98:101], v[182:185], v[206:209], v[98:101]
	v_mfma_f32_16x16x32_bf16 v[70:73], v[174:177], v[214:217], v[70:73]
	v_mfma_f32_16x16x32_bf16 v[66:69], v[182:185], v[214:217], v[66:69]
	s_setprio 0
	s_barrier
	s_mov_b32 m0, s37
	v_lshl_add_u64 v[162:163], s[84:85], 0, v[146:147]
	ds_read_b128 v[186:189], v168 offset:16384
	ds_read_b128 v[190:193], v168 offset:17408
	ds_read_b128 v[194:197], v168 offset:18432
	ds_read_b128 v[198:201], v168 offset:19456
	ds_read_b128 v[202:205], v168 offset:20480
	ds_read_b128 v[206:209], v168 offset:21504
	ds_read_b128 v[210:213], v168 offset:22528
	ds_read_b128 v[214:217], v168 offset:23552
	global_load_lds_dwordx4 v[162:163], off
	v_lshl_add_u64 v[218:219], s[84:85], 0, v[148:149]
	s_mov_b32 m0, s38
	v_lshl_add_u64 v[220:221], s[86:87], 0, v[146:147]
	global_load_lds_dwordx4 v[218:219], off
	s_mov_b32 m0, s39
	v_lshl_add_u64 v[222:223], s[82:83], 0, v[148:149]
	global_load_lds_dwordx4 v[220:221], off
	v_lshl_add_u64 v[220:221], s[86:87], 0, v[148:149]
	s_mov_b32 m0, s24
	s_nop 0
	global_load_lds_dwordx4 v[220:221], off
	v_lshl_add_u64 v[220:221], s[82:83], 0, v[146:147]
	s_mov_b32 m0, s9
	s_nop 0
	global_load_lds_dwordx4 v[220:221], off
	s_mov_b32 m0, s11
	s_nop 0
	global_load_lds_dwordx4 v[222:223], off
	s_waitcnt vmcnt(8)
	s_waitcnt lgkmcnt(0)
	s_barrier
; #define PG8_STAGEA(bufoff, gbase, voff) PG8_STAGE_X(bufoff, gbase, voff, PG8_AUX_A)
; #define PG8_LDA(dst, b, h) do { _Pragma("unroll") for (int m = 0; m < 4; ++m) _Pragma("unroll") for (int k = 0; k < 2; ++k) dst[m][k] = *(const PG8_LAS bf16x8*)(lds + PG8_SA(b, h) + aoff + m * 2048 + k * 1024); } while (0)
; #define PG8_LDB(dst, b, h) do { _Pragma("unroll") for (int n = 0; n < 2; ++n) _Pragma("unroll") for (int k = 0; k < 2; ++k) dst[n][k] = *(const PG8_LAS bf16x8*)(lds + PG8_SB(b, h) + boff + n * 2048 + k * 1024); } while (0)
; #define PG8_MMA(ai, bj, At, Bt) do { __builtin_amdgcn_s_setprio(1); _Pragma("unroll") for (int m = 0; m < 4; ++m) _Pragma("unroll") for (int n = 0; n < 2; ++n) _Pragma("unroll") for (int k = 0; k < 2; ++k) \
;         acc[ai][bj][m][n] = __builtin_amdgcn_mfma_f32_16x16x32_bf16(Bt[n][k], At[m][k], acc[ai][bj][m][n], 0, 0, 0); __builtin_amdgcn_s_setprio(0); } while (0)
; #define PG8_WAIT_V(n) asm volatile("s_waitcnt vmcnt(" #n ")" ::: "memory")
; #define PG8_WAIT_L(n) asm volatile("s_waitcnt lgkmcnt(" #n ")" ::: "memory")
; #define PG8_BAR __builtin_amdgcn_s_barrier()
; #define PG8_SCHED __builtin_amdgcn_sched_barrier(0)
; template <class Epi, class Sched, bool ALIGN_EPI = false, bool SP2 = false>
; __device__ __forceinline__ void gemm_phase(PG8_LAS unsigned char* lds, const Gemm g, const Sched& S, const Epi& E) {
;     ...
;             PG8_WAIT_V(8); PG8_WAIT_L(0); PG8_BAR; PG8_MMA(1, 0, At, B0); PG8_MMA(1, 1, At, B1); PG8_BAR; PG8_SCHED;
;             PG8_LDB(B0, 1, 0); PG8_LDB(B1, 1, 1); PG8_SCHED; PG8_LDA(At, 1, 0); PG8_STAGEA(PG8_SA(0, 1), a2 + hstep, voffA);
;             PG8_WAIT_V(8); PG8_WAIT_L(0); PG8_BAR; PG8_MMA(0, 0, At, B0); PG8_MMA(0, 1, At, B1); PG8_BAR; PG8_SCHED;
	s_setprio 1
	s_waitcnt lgkmcnt(0)
	.p2align 3
	v_mfma_f32_16x16x32_bf16 v[62:65], v[82:85], v[186:189], v[62:65]
	v_mfma_f32_16x16x32_bf16 v[58:61], v[94:97], v[186:189], v[58:61]
	v_mfma_f32_16x16x32_bf16 v[46:49], v[82:85], v[194:197], v[46:49]
	v_mfma_f32_16x16x32_bf16 v[42:45], v[94:97], v[194:197], v[42:45]
	v_mfma_f32_16x16x32_bf16 v[30:33], v[82:85], v[202:205], v[30:33]
	v_mfma_f32_16x16x32_bf16 v[26:29], v[94:97], v[202:205], v[26:29]
	v_mfma_f32_16x16x32_bf16 v[14:17], v[82:85], v[210:213], v[14:17]
	v_mfma_f32_16x16x32_bf16 v[10:13], v[94:97], v[210:213], v[10:13]
	v_mfma_f32_16x16x32_bf16 v[62:65], v[90:93], v[190:193], v[62:65]
	v_mfma_f32_16x16x32_bf16 v[58:61], v[158:161], v[190:193], v[58:61]
	v_mfma_f32_16x16x32_bf16 v[46:49], v[90:93], v[198:201], v[46:49]
	v_mfma_f32_16x16x32_bf16 v[42:45], v[158:161], v[198:201], v[42:45]
	v_mfma_f32_16x16x32_bf16 v[30:33], v[90:93], v[206:209], v[30:33]
	v_mfma_f32_16x16x32_bf16 v[26:29], v[158:161], v[206:209], v[26:29]
	v_mfma_f32_16x16x32_bf16 v[14:17], v[90:93], v[214:217], v[14:17]
	v_mfma_f32_16x16x32_bf16 v[10:13], v[158:161], v[214:217], v[10:13]
	s_setprio 0
	s_setprio 1
	.p2align 3
	v_mfma_f32_16x16x32_bf16 v[54:57], v[170:173], v[186:189], v[54:57]
	v_mfma_f32_16x16x32_bf16 v[50:53], v[178:181], v[186:189], v[50:53]
	v_mfma_f32_16x16x32_bf16 v[38:41], v[170:173], v[194:197], v[38:41]
	v_mfma_f32_16x16x32_bf16 v[34:37], v[178:181], v[194:197], v[34:37]
	v_mfma_f32_16x16x32_bf16 v[22:25], v[170:173], v[202:205], v[22:25]
	v_mfma_f32_16x16x32_bf16 v[18:21], v[178:181], v[202:205], v[18:21]
	v_mfma_f32_16x16x32_bf16 v[6:9], v[170:173], v[210:213], v[6:9]
	v_mfma_f32_16x16x32_bf16 v[2:5], v[178:181], v[210:213], v[2:5]
	v_mfma_f32_16x16x32_bf16 v[54:57], v[174:177], v[190:193], v[54:57]
	v_mfma_f32_16x16x32_bf16 v[50:53], v[182:185], v[190:193], v[50:53]
	v_mfma_f32_16x16x32_bf16 v[38:41], v[174:177], v[198:201], v[38:41]
	v_mfma_f32_16x16x32_bf16 v[34:37], v[182:185], v[198:201], v[34:37]
	v_mfma_f32_16x16x32_bf16 v[22:25], v[174:177], v[206:209], v[22:25]
	v_mfma_f32_16x16x32_bf16 v[18:21], v[182:185], v[206:209], v[18:21]
	v_mfma_f32_16x16x32_bf16 v[6:9], v[174:177], v[214:217], v[6:9]
	v_mfma_f32_16x16x32_bf16 v[2:5], v[182:185], v[214:217], v[2:5]
	s_setprio 0
	s_barrier
	v_add_u32_e32 v158, s25, v164
	v_add_u32_e32 v182, vcc_hi, v164
	ds_read_b128 v[82:85], v158
	ds_read_b128 v[90:93], v158 offset:1024
	ds_read_b128 v[94:97], v158 offset:2048
	ds_read_b128 v[158:161], v158 offset:3072
	ds_read_b128 v[170:173], v182
	ds_read_b128 v[174:177], v182 offset:1024
	ds_read_b128 v[178:181], v182 offset:2048
	ds_read_b128 v[182:185], v182 offset:3072
	s_mov_b32 m0, s21
	v_lshl_add_u64 v[224:225], s[80:81], 0, v[146:147]
	ds_read_b128 v[186:189], v168 offset:32768
	ds_read_b128 v[190:193], v168 offset:33792
	ds_read_b128 v[194:197], v168 offset:34816
	ds_read_b128 v[198:201], v168 offset:35840
	ds_read_b128 v[202:205], v168 offset:36864
	ds_read_b128 v[206:209], v168 offset:37888
	ds_read_b128 v[210:213], v168 offset:38912
	ds_read_b128 v[214:217], v168 offset:39936
	global_load_lds_dwordx4 v[224:225], off
	v_lshl_add_u64 v[224:225], s[80:81], 0, v[148:149]
	s_mov_b32 m0, s23
	s_nop 0
	global_load_lds_dwordx4 v[224:225], off
	s_waitcnt vmcnt(8)
	s_waitcnt lgkmcnt(0)
	s_barrier
	s_setprio 1
	s_waitcnt lgkmcnt(0)
	.p2align 3
	v_mfma_f32_16x16x32_bf16 v[142:145], v[82:85], v[186:189], v[142:145]
	v_mfma_f32_16x16x32_bf16 v[138:141], v[94:97], v[186:189], v[138:141]
	v_mfma_f32_16x16x32_bf16 v[126:129], v[82:85], v[194:197], v[126:129]
	v_mfma_f32_16x16x32_bf16 v[122:125], v[94:97], v[194:197], v[122:125]
	v_mfma_f32_16x16x32_bf16 v[110:113], v[82:85], v[202:205], v[110:113]
	v_mfma_f32_16x16x32_bf16 v[106:109], v[94:97], v[202:205], v[106:109]
	v_mfma_f32_16x16x32_bf16 v[86:89], v[82:85], v[210:213], v[86:89]
	v_mfma_f32_16x16x32_bf16 v[78:81], v[94:97], v[210:213], v[78:81]
	v_mfma_f32_16x16x32_bf16 v[142:145], v[90:93], v[190:193], v[142:145]
	v_mfma_f32_16x16x32_bf16 v[138:141], v[158:161], v[190:193], v[138:141]
	v_mfma_f32_16x16x32_bf16 v[126:129], v[90:93], v[198:201], v[126:129]
	v_mfma_f32_16x16x32_bf16 v[122:125], v[158:161], v[198:201], v[122:125]
	v_mfma_f32_16x16x32_bf16 v[110:113], v[90:93], v[206:209], v[110:113]
	v_mfma_f32_16x16x32_bf16 v[106:109], v[158:161], v[206:209], v[106:109]
	v_mfma_f32_16x16x32_bf16 v[86:89], v[90:93], v[214:217], v[86:89]
	v_mfma_f32_16x16x32_bf16 v[78:81], v[158:161], v[214:217], v[78:81]
	s_setprio 0
	s_setprio 1
	.p2align 3
	v_mfma_f32_16x16x32_bf16 v[134:137], v[170:173], v[186:189], v[134:137]
	v_mfma_f32_16x16x32_bf16 v[130:133], v[178:181], v[186:189], v[130:133]
	v_mfma_f32_16x16x32_bf16 v[118:121], v[170:173], v[194:197], v[118:121]
	v_mfma_f32_16x16x32_bf16 v[114:117], v[178:181], v[194:197], v[114:117]
	v_mfma_f32_16x16x32_bf16 v[102:105], v[170:173], v[202:205], v[102:105]
	v_mfma_f32_16x16x32_bf16 v[98:101], v[178:181], v[202:205], v[98:101]
	v_mfma_f32_16x16x32_bf16 v[70:73], v[170:173], v[210:213], v[70:73]
	v_mfma_f32_16x16x32_bf16 v[66:69], v[178:181], v[210:213], v[66:69]
	v_mfma_f32_16x16x32_bf16 v[134:137], v[174:177], v[190:193], v[134:137]
	v_mfma_f32_16x16x32_bf16 v[130:133], v[182:185], v[190:193], v[130:133]
	v_mfma_f32_16x16x32_bf16 v[118:121], v[174:177], v[198:201], v[118:121]
	v_mfma_f32_16x16x32_bf16 v[114:117], v[182:185], v[198:201], v[114:117]
	v_mfma_f32_16x16x32_bf16 v[102:105], v[174:177], v[206:209], v[102:105]
	v_mfma_f32_16x16x32_bf16 v[98:101], v[182:185], v[206:209], v[98:101]
	v_mfma_f32_16x16x32_bf16 v[70:73], v[174:177], v[214:217], v[70:73]
	v_mfma_f32_16x16x32_bf16 v[66:69], v[182:185], v[214:217], v[66:69]
	s_setprio 0
	s_barrier
; #define PG8_STAGEA(bufoff, gbase, voff) PG8_STAGE_X(bufoff, gbase, voff, PG8_AUX_A)
; #define PG8_STAGEB(bufoff, gbase, voff) PG8_STAGE_X(bufoff, gbase, voff, PG8_AUX_B)
; #define PG8_LDA(dst, b, h) do { _Pragma("unroll") for (int m = 0; m < 4; ++m) _Pragma("unroll") for (int k = 0; k < 2; ++k) dst[m][k] = *(const PG8_LAS bf16x8*)(lds + PG8_SA(b, h) + aoff + m * 2048 + k * 1024); } while (0)
; #define PG8_MMA(ai, bj, At, Bt) do { __builtin_amdgcn_s_setprio(1); _Pragma("unroll") for (int m = 0; m < 4; ++m) _Pragma("unroll") for (int n = 0; n < 2; ++n) _Pragma("unroll") for (int k = 0; k < 2; ++k) \
;         acc[ai][bj][m][n] = __builtin_amdgcn_mfma_f32_16x16x32_bf16(Bt[n][k], At[m][k], acc[ai][bj][m][n], 0, 0, 0); __builtin_amdgcn_s_setprio(0); } while (0)
; #define PG8_WAIT_V(n) asm volatile("s_waitcnt vmcnt(" #n ")" ::: "memory")
; #define PG8_WAIT_L(n) asm volatile("s_waitcnt lgkmcnt(" #n ")" ::: "memory")
; #define PG8_BAR __builtin_amdgcn_s_barrier()
; #define PG8_SCHED __builtin_amdgcn_sched_barrier(0)
; template <class Epi, class Sched, bool ALIGN_EPI = false, bool SP2 = false>
; __device__ __forceinline__ void gemm_phase(PG8_LAS unsigned char* lds, const Gemm g, const Sched& S, const Epi& E) {
;     ...
;             PG8_LDA(At, 1, 1); PG8_STAGEB(PG8_SB(1, 0), b3, voffB); PG8_STAGEB(PG8_SB(1, 1), b3 + hstep, voffB); PG8_STAGEA(PG8_SA(1, 0), a3, voffA);
;             PG8_WAIT_V(8); PG8_WAIT_L(0); PG8_BAR; PG8_MMA(1, 0, At, B0); PG8_MMA(1, 1, At, B1); PG8_BAR; PG8_SCHED;
;     ...
;         if constexpr (ALIGN_EPI) { if (wr == 0) PG8_BAR; }
	s_mov_b32 m0, vcc_lo
	v_lshl_add_u64 v[162:163], v[162:163], 0, s[54:55]
	ds_read_b128 v[186:189], v168 offset:49152
	ds_read_b128 v[190:193], v168 offset:50176
	ds_read_b128 v[194:197], v168 offset:51200
	ds_read_b128 v[198:201], v168 offset:52224
	ds_read_b128 v[202:205], v168 offset:53248
	ds_read_b128 v[206:209], v168 offset:54272
	ds_read_b128 v[210:213], v168 offset:55296
	ds_read_b128 v[214:217], v168 offset:56320
	global_load_lds_dwordx4 v[162:163], off
	v_lshl_add_u64 v[162:163], v[218:219], 0, s[54:55]
	s_mov_b32 m0, s34
	s_nop 0
	global_load_lds_dwordx4 v[162:163], off
	v_lshl_add_u64 v[162:163], s[78:79], 0, v[146:147]
	s_mov_b32 m0, s35
	s_nop 0
	global_load_lds_dwordx4 v[162:163], off
	v_lshl_add_u64 v[162:163], s[78:79], 0, v[148:149]
	s_mov_b32 m0, s28
	s_nop 0
	global_load_lds_dwordx4 v[162:163], off
	v_lshl_add_u64 v[162:163], v[220:221], 0, s[54:55]
	s_mov_b32 m0, s90
	s_nop 0
	global_load_lds_dwordx4 v[162:163], off
	v_lshl_add_u64 v[162:163], v[222:223], 0, s[54:55]
	s_mov_b32 m0, s91
	s_nop 0
	global_load_lds_dwordx4 v[162:163], off
	s_waitcnt vmcnt(8)
	s_waitcnt lgkmcnt(0)
	s_barrier
	s_setprio 1
	s_waitcnt lgkmcnt(0)
	.p2align 3
	v_mfma_f32_16x16x32_bf16 v[62:65], v[82:85], v[186:189], v[62:65]
	v_mfma_f32_16x16x32_bf16 v[58:61], v[94:97], v[186:189], v[58:61]
	v_mfma_f32_16x16x32_bf16 v[46:49], v[82:85], v[194:197], v[46:49]
	v_mfma_f32_16x16x32_bf16 v[42:45], v[94:97], v[194:197], v[42:45]
	v_mfma_f32_16x16x32_bf16 v[30:33], v[82:85], v[202:205], v[30:33]
	v_mfma_f32_16x16x32_bf16 v[26:29], v[94:97], v[202:205], v[26:29]
	v_mfma_f32_16x16x32_bf16 v[14:17], v[82:85], v[210:213], v[14:17]
	v_mfma_f32_16x16x32_bf16 v[10:13], v[94:97], v[210:213], v[10:13]
	v_mfma_f32_16x16x32_bf16 v[62:65], v[90:93], v[190:193], v[62:65]
	v_mfma_f32_16x16x32_bf16 v[58:61], v[158:161], v[190:193], v[58:61]
	v_mfma_f32_16x16x32_bf16 v[46:49], v[90:93], v[198:201], v[46:49]
	v_mfma_f32_16x16x32_bf16 v[42:45], v[158:161], v[198:201], v[42:45]
	v_mfma_f32_16x16x32_bf16 v[30:33], v[90:93], v[206:209], v[30:33]
	v_mfma_f32_16x16x32_bf16 v[26:29], v[158:161], v[206:209], v[26:29]
	v_mfma_f32_16x16x32_bf16 v[14:17], v[90:93], v[214:217], v[14:17]
	v_mfma_f32_16x16x32_bf16 v[10:13], v[158:161], v[214:217], v[10:13]
	s_setprio 0
	s_setprio 1
	.p2align 3
	v_mfma_f32_16x16x32_bf16 v[54:57], v[170:173], v[186:189], v[54:57]
	v_mfma_f32_16x16x32_bf16 v[50:53], v[178:181], v[186:189], v[50:53]
	v_mfma_f32_16x16x32_bf16 v[38:41], v[170:173], v[194:197], v[38:41]
	v_mfma_f32_16x16x32_bf16 v[34:37], v[178:181], v[194:197], v[34:37]
	v_mfma_f32_16x16x32_bf16 v[22:25], v[170:173], v[202:205], v[22:25]
	v_mfma_f32_16x16x32_bf16 v[18:21], v[178:181], v[202:205], v[18:21]
	v_mfma_f32_16x16x32_bf16 v[6:9], v[170:173], v[210:213], v[6:9]
	v_mfma_f32_16x16x32_bf16 v[2:5], v[178:181], v[210:213], v[2:5]
	v_mfma_f32_16x16x32_bf16 v[54:57], v[174:177], v[190:193], v[54:57]
	v_mfma_f32_16x16x32_bf16 v[50:53], v[182:185], v[190:193], v[50:53]
	v_mfma_f32_16x16x32_bf16 v[38:41], v[174:177], v[198:201], v[38:41]
	v_mfma_f32_16x16x32_bf16 v[34:37], v[182:185], v[198:201], v[34:37]
	v_mfma_f32_16x16x32_bf16 v[22:25], v[174:177], v[206:209], v[22:25]
	v_mfma_f32_16x16x32_bf16 v[18:21], v[182:185], v[206:209], v[18:21]
	v_mfma_f32_16x16x32_bf16 v[6:9], v[174:177], v[214:217], v[6:9]
	v_mfma_f32_16x16x32_bf16 v[2:5], v[182:185], v[214:217], v[2:5]
	s_setprio 0
	s_barrier
	s_mov_b64 s[74:75], s[76:77]
	s_mov_b32 s96, s97
	s_cbranch_scc0 .LBB0_643
	s_and_b64 vcc, exec, s[56:57]
	s_cbranch_vccz .LBB0_646
	s_barrier

; #define PG8_STAGEA(bufoff, gbase, voff) PG8_STAGE_X(bufoff, gbase, voff, PG8_AUX_A)
; #define PG8_STAGEB(bufoff, gbase, voff) PG8_STAGE_X(bufoff, gbase, voff, PG8_AUX_B)
; #define PG8_LDA(dst, b, h) do { _Pragma("unroll") for (int m = 0; m < 4; ++m) _Pragma("unroll") for (int k = 0; k < 2; ++k) dst[m][k] = *(const PG8_LAS bf16x8*)(lds + PG8_SA(b, h) + aoff + m * 2048 + k * 1024); } while (0)
; #define PG8_LDB(dst, b, h) do { _Pragma("unroll") for (int n = 0; n < 2; ++n) _Pragma("unroll") for (int k = 0; k < 2; ++k) dst[n][k] = *(const PG8_LAS bf16x8*)(lds + PG8_SB(b, h) + boff + n * 2048 + k * 1024); } while (0)
; #define PG8_WAIT_V(n) asm volatile("s_waitcnt vmcnt(" #n ")" ::: "memory")
; #define PG8_WAIT_L(n) asm volatile("s_waitcnt lgkmcnt(" #n ")" ::: "memory")
; template <class Epi, class Sched, bool ALIGN_EPI = false, bool SP2 = false>
; __device__ __forceinline__ void gemm_phase(PG8_LAS unsigned char* lds, const Gemm g, const Sched& S, const Epi& E) {
;     ...
;             const bool last = (t == nt - 2);
;             if constexpr (HasMid<Epi>::value) { if (t == ns) E.mid(acc, cur, wr, wc, fr, fq); }
;             const char* sA1 = (t + 1 >= ns) ? cA2 : cA; const char* sA2 = (t + 2 >= ns) ? cA2 : cA; const char* sB2 = (t + 2 >= ns) ? cB2 : cB;
;             const char* a1 = sA1 + (size_t)(t + 1) * kstep;
;             const char* a2 = last ? nA : sA2 + (size_t)(t + 2) * kstep; const char* b2 = last ? nB : sB2 + (size_t)(t + 2) * kstep;
;             const char* a3 = a2 + kstep; const char* b3 = b2 + kstep;
;             if (last && has_next) S.a_ready(nxt);
;             if constexpr (SP2) {
;             PG8_LDB(B0, 0, 0); PG8_LDB(B1, 0, 1); PG8_SCHED; PG8_LDA(At, 0, 0); PG8_STAGEA(PG8_SA(1, 1), a1 + hstep, voffA);
;             PG8_WAIT_V(8); PG8_WAIT_L(0); PG8_BAR; PG8_MMA(0, 0, At, B0); PG8_MMA(0, 1, At, B1); PG8_BAR; PG8_SCHED;
;             PG8_LDA(At, 0, 1); PG8_STAGEB(PG8_SB(0, 0), b2, voffB); PG8_STAGEB(PG8_SB(0, 1), b2 + hstep, voffB); PG8_STAGEA(PG8_SA(0, 0), a2, voffA);
;             PG8_WAIT_V(8); PG8_WAIT_L(0); PG8_BAR; PG8_MMA(1, 0, At, B0); PG8_MMA(1, 1, At, B1); PG8_BAR; PG8_SCHED;
;             PG8_LDB(B0, 1, 0); PG8_LDB(B1, 1, 1); PG8_SCHED; PG8_LDA(At, 1, 0); PG8_STAGEA(PG8_SA(0, 1), a2 + hstep, voffA);
;             PG8_WAIT_V(8); PG8_WAIT_L(0); PG8_BAR; PG8_MMA(0, 0, At, B0); PG8_MMA(0, 1, At, B1); PG8_BAR; PG8_SCHED;
.LBB0_734:
	s_add_i32 s90, s74, 2
	s_cmp_gt_u32 s90, 29
	s_cselect_b64 s[34:35], -1, 0
	s_and_b64 vcc, s[34:35], exec
	s_cselect_b32 s29, s50, s70
	ds_read_b128 v[150:153], v156
	ds_read_b128 v[162:165], v156 offset:1024
	ds_read_b128 v[166:169], v156 offset:2048
	ds_read_b128 v[170:173], v156 offset:3072
	ds_read_b128 v[174:177], v157
	ds_read_b128 v[178:181], v157 offset:1024
	ds_read_b128 v[182:185], v157 offset:2048
	ds_read_b128 v[186:189], v157 offset:3072
	s_cselect_b32 s24, s47, s69
	s_cselect_b32 s25, s46, s68
	s_cselect_b32 s28, s51, s71
	s_add_u32 s29, s29, s72
	s_addc_u32 s28, s28, s73
	s_add_u32 s29, s29, 0xfff80080
	s_addc_u32 s28, s28, -1
	s_add_u32 s25, s25, s72
	s_addc_u32 s24, s24, s73
	s_add_u32 s25, s25, 0xfff80080
	s_addc_u32 s24, s24, -1
	s_cmp_eq_u32 s74, 28
	s_cselect_b32 s74, s87, s25
	s_cselect_b32 s77, s63, s28
	s_cselect_b32 s76, s86, s29
	s_cselect_b32 s75, s61, s24
	v_lshl_add_u64 v[222:223], v[146:147], 0, s[72:73]
	s_add_i32 m0, s21, 0xc000
	ds_read_b128 v[190:193], v158
	ds_read_b128 v[194:197], v158 offset:1024
	ds_read_b128 v[198:201], v158 offset:2048
	ds_read_b128 v[202:205], v158 offset:3072
	ds_read_b128 v[206:209], v158 offset:4096
	ds_read_b128 v[210:213], v158 offset:5120
	ds_read_b128 v[214:217], v158 offset:6144
	ds_read_b128 v[218:221], v158 offset:7168
	global_load_lds_dwordx4 v[222:223], off
	v_lshl_add_u64 v[222:223], v[148:149], 0, s[72:73]
	s_add_i32 m0, s21, 0xe000
	s_nop 0
	global_load_lds_dwordx4 v[222:223], off
	s_waitcnt vmcnt(8)
	s_waitcnt lgkmcnt(0)
	s_barrier
	s_setprio 1
	s_waitcnt lgkmcnt(0)
	.p2align 3
	v_mfma_f32_16x16x32_bf16 v[126:129], v[150:153], v[190:193], v[126:129]
	v_mfma_f32_16x16x32_bf16 v[122:125], v[166:169], v[190:193], v[122:125]
	v_mfma_f32_16x16x32_bf16 v[110:113], v[150:153], v[198:201], v[110:113]
	v_mfma_f32_16x16x32_bf16 v[106:109], v[166:169], v[198:201], v[106:109]
	v_mfma_f32_16x16x32_bf16 v[94:97], v[150:153], v[206:209], v[94:97]
	v_mfma_f32_16x16x32_bf16 v[90:93], v[166:169], v[206:209], v[90:93]
	v_mfma_f32_16x16x32_bf16 v[78:81], v[150:153], v[214:217], v[78:81]
	v_mfma_f32_16x16x32_bf16 v[74:77], v[166:169], v[214:217], v[74:77]
	v_mfma_f32_16x16x32_bf16 v[126:129], v[162:165], v[194:197], v[126:129]
	v_mfma_f32_16x16x32_bf16 v[122:125], v[170:173], v[194:197], v[122:125]
	v_mfma_f32_16x16x32_bf16 v[110:113], v[162:165], v[202:205], v[110:113]
	v_mfma_f32_16x16x32_bf16 v[106:109], v[170:173], v[202:205], v[106:109]
	v_mfma_f32_16x16x32_bf16 v[94:97], v[162:165], v[210:213], v[94:97]
	v_mfma_f32_16x16x32_bf16 v[90:93], v[170:173], v[210:213], v[90:93]
	v_mfma_f32_16x16x32_bf16 v[78:81], v[162:165], v[218:221], v[78:81]
	v_mfma_f32_16x16x32_bf16 v[74:77], v[170:173], v[218:221], v[74:77]
	s_setprio 0
	s_setprio 1
	.p2align 3
	v_mfma_f32_16x16x32_bf16 v[118:121], v[174:177], v[190:193], v[118:121]
	v_mfma_f32_16x16x32_bf16 v[114:117], v[182:185], v[190:193], v[114:117]
	v_mfma_f32_16x16x32_bf16 v[102:105], v[174:177], v[198:201], v[102:105]
	v_mfma_f32_16x16x32_bf16 v[98:101], v[182:185], v[198:201], v[98:101]
	v_mfma_f32_16x16x32_bf16 v[86:89], v[174:177], v[206:209], v[86:89]
	v_mfma_f32_16x16x32_bf16 v[82:85], v[182:185], v[206:209], v[82:85]
	v_mfma_f32_16x16x32_bf16 v[70:73], v[174:177], v[214:217], v[70:73]
	v_mfma_f32_16x16x32_bf16 v[66:69], v[182:185], v[214:217], v[66:69]
	v_mfma_f32_16x16x32_bf16 v[118:121], v[178:181], v[194:197], v[118:121]
	v_mfma_f32_16x16x32_bf16 v[114:117], v[186:189], v[194:197], v[114:117]
	v_mfma_f32_16x16x32_bf16 v[102:105], v[178:181], v[202:205], v[102:105]
	v_mfma_f32_16x16x32_bf16 v[98:101], v[186:189], v[202:205], v[98:101]
	v_mfma_f32_16x16x32_bf16 v[86:89], v[178:181], v[210:213], v[86:89]
	v_mfma_f32_16x16x32_bf16 v[82:85], v[186:189], v[210:213], v[82:85]
	v_mfma_f32_16x16x32_bf16 v[70:73], v[178:181], v[218:221], v[70:73]
	v_mfma_f32_16x16x32_bf16 v[66:69], v[186:189], v[218:221], v[66:69]
	s_setprio 0
	s_barrier
	s_add_i32 s24, s81, s9
	v_lshl_add_u64 v[222:223], s[74:75], 0, v[134:135]
	s_mov_b32 m0, s24
	ds_read_b128 v[190:193], v158 offset:16384
	ds_read_b128 v[194:197], v158 offset:17408
	ds_read_b128 v[198:201], v158 offset:18432
	ds_read_b128 v[202:205], v158 offset:19456
	ds_read_b128 v[206:209], v158 offset:20480
	ds_read_b128 v[210:213], v158 offset:21504
	ds_read_b128 v[214:217], v158 offset:22528
	ds_read_b128 v[218:221], v158 offset:23552
	global_load_lds_dwordx4 v[222:223], off
	s_add_i32 m0, s24, 0x2000
	s_add_u32 s34, s74, 0x80000
	v_lshl_add_u64 v[224:225], s[74:75], 0, v[130:131]
	s_addc_u32 s35, s75, 0
	s_add_i32 s24, s82, s9
	global_load_lds_dwordx4 v[224:225], off
	v_lshl_add_u64 v[226:227], s[34:35], 0, v[134:135]
	s_mov_b32 m0, s24
	v_lshl_add_u64 v[228:229], s[76:77], 0, v[132:133]
	global_load_lds_dwordx4 v[226:227], off
	v_lshl_add_u64 v[226:227], s[34:35], 0, v[130:131]
	s_add_i32 m0, s24, 0x2000
	s_nop 0
	global_load_lds_dwordx4 v[226:227], off
	v_lshl_add_u64 v[226:227], s[76:77], 0, v[136:137]
	s_mov_b32 m0, s21
	s_nop 0
	global_load_lds_dwordx4 v[226:227], off
	s_mov_b32 m0, s23
	s_nop 0
	global_load_lds_dwordx4 v[228:229], off
	s_waitcnt vmcnt(8)
	s_waitcnt lgkmcnt(0)
	s_barrier
; #define PG8_STAGEA(bufoff, gbase, voff) PG8_STAGE_X(bufoff, gbase, voff, PG8_AUX_A)
; #define PG8_LDA(dst, b, h) do { _Pragma("unroll") for (int m = 0; m < 4; ++m) _Pragma("unroll") for (int k = 0; k < 2; ++k) dst[m][k] = *(const PG8_LAS bf16x8*)(lds + PG8_SA(b, h) + aoff + m * 2048 + k * 1024); } while (0)
; #define PG8_LDB(dst, b, h) do { _Pragma("unroll") for (int n = 0; n < 2; ++n) _Pragma("unroll") for (int k = 0; k < 2; ++k) dst[n][k] = *(const PG8_LAS bf16x8*)(lds + PG8_SB(b, h) + boff + n * 2048 + k * 1024); } while (0)
; #define PG8_MMA(ai, bj, At, Bt) do { __builtin_amdgcn_s_setprio(1); _Pragma("unroll") for (int m = 0; m < 4; ++m) _Pragma("unroll") for (int n = 0; n < 2; ++n) _Pragma("unroll") for (int k = 0; k < 2; ++k) \
;         acc[ai][bj][m][n] = __builtin_amdgcn_mfma_f32_16x16x32_bf16(Bt[n][k], At[m][k], acc[ai][bj][m][n], 0, 0, 0); __builtin_amdgcn_s_setprio(0); } while (0)
; #define PG8_WAIT_V(n) asm volatile("s_waitcnt vmcnt(" #n ")" ::: "memory")
; #define PG8_WAIT_L(n) asm volatile("s_waitcnt lgkmcnt(" #n ")" ::: "memory")
; #define PG8_BAR __builtin_amdgcn_s_barrier()
; #define PG8_SCHED __builtin_amdgcn_sched_barrier(0)
; template <class Epi, class Sched, bool ALIGN_EPI = false, bool SP2 = false>
; __device__ __forceinline__ void gemm_phase(PG8_LAS unsigned char* lds, const Gemm g, const Sched& S, const Epi& E) {
;     ...
;             PG8_WAIT_V(8); PG8_WAIT_L(0); PG8_BAR; PG8_MMA(1, 0, At, B0); PG8_MMA(1, 1, At, B1); PG8_BAR; PG8_SCHED;
;             PG8_LDB(B0, 1, 0); PG8_LDB(B1, 1, 1); PG8_SCHED; PG8_LDA(At, 1, 0); PG8_STAGEA(PG8_SA(0, 1), a2 + hstep, voffA);
;             PG8_WAIT_V(8); PG8_WAIT_L(0); PG8_BAR; PG8_MMA(0, 0, At, B0); PG8_MMA(0, 1, At, B1); PG8_BAR; PG8_SCHED;
	s_setprio 1
	s_waitcnt lgkmcnt(0)
	.p2align 3
	v_mfma_f32_16x16x32_bf16 v[62:65], v[150:153], v[190:193], v[62:65]
	v_mfma_f32_16x16x32_bf16 v[58:61], v[166:169], v[190:193], v[58:61]
	v_mfma_f32_16x16x32_bf16 v[46:49], v[150:153], v[198:201], v[46:49]
	v_mfma_f32_16x16x32_bf16 v[42:45], v[166:169], v[198:201], v[42:45]
	v_mfma_f32_16x16x32_bf16 v[30:33], v[150:153], v[206:209], v[30:33]
	v_mfma_f32_16x16x32_bf16 v[26:29], v[166:169], v[206:209], v[26:29]
	v_mfma_f32_16x16x32_bf16 v[14:17], v[150:153], v[214:217], v[14:17]
	v_mfma_f32_16x16x32_bf16 v[10:13], v[166:169], v[214:217], v[10:13]
	v_mfma_f32_16x16x32_bf16 v[62:65], v[162:165], v[194:197], v[62:65]
	v_mfma_f32_16x16x32_bf16 v[58:61], v[170:173], v[194:197], v[58:61]
	v_mfma_f32_16x16x32_bf16 v[46:49], v[162:165], v[202:205], v[46:49]
	v_mfma_f32_16x16x32_bf16 v[42:45], v[170:173], v[202:205], v[42:45]
	v_mfma_f32_16x16x32_bf16 v[30:33], v[162:165], v[210:213], v[30:33]
	v_mfma_f32_16x16x32_bf16 v[26:29], v[170:173], v[210:213], v[26:29]
	v_mfma_f32_16x16x32_bf16 v[14:17], v[162:165], v[218:221], v[14:17]
	v_mfma_f32_16x16x32_bf16 v[10:13], v[170:173], v[218:221], v[10:13]
	s_setprio 0
	s_setprio 1
	.p2align 3
	v_mfma_f32_16x16x32_bf16 v[54:57], v[174:177], v[190:193], v[54:57]
	v_mfma_f32_16x16x32_bf16 v[50:53], v[182:185], v[190:193], v[50:53]
	v_mfma_f32_16x16x32_bf16 v[38:41], v[174:177], v[198:201], v[38:41]
	v_mfma_f32_16x16x32_bf16 v[34:37], v[182:185], v[198:201], v[34:37]
	v_mfma_f32_16x16x32_bf16 v[22:25], v[174:177], v[206:209], v[22:25]
	v_mfma_f32_16x16x32_bf16 v[18:21], v[182:185], v[206:209], v[18:21]
	v_mfma_f32_16x16x32_bf16 v[6:9], v[174:177], v[214:217], v[6:9]
	v_mfma_f32_16x16x32_bf16 v[2:5], v[182:185], v[214:217], v[2:5]
	v_mfma_f32_16x16x32_bf16 v[54:57], v[178:181], v[194:197], v[54:57]
	v_mfma_f32_16x16x32_bf16 v[50:53], v[186:189], v[194:197], v[50:53]
	v_mfma_f32_16x16x32_bf16 v[38:41], v[178:181], v[202:205], v[38:41]
	v_mfma_f32_16x16x32_bf16 v[34:37], v[186:189], v[202:205], v[34:37]
	v_mfma_f32_16x16x32_bf16 v[22:25], v[178:181], v[210:213], v[22:25]
	v_mfma_f32_16x16x32_bf16 v[18:21], v[186:189], v[210:213], v[18:21]
	v_mfma_f32_16x16x32_bf16 v[6:9], v[178:181], v[218:221], v[6:9]
	v_mfma_f32_16x16x32_bf16 v[2:5], v[186:189], v[218:221], v[2:5]
	s_setprio 0
	s_barrier
	s_add_i32 s24, 0, 0x18000
	v_add_u32_e32 v161, s24, v154
	s_add_i32 s25, 0, 0x1c000
	ds_read_b128 v[150:153], v161
	ds_read_b128 v[162:165], v161 offset:1024
	ds_read_b128 v[166:169], v161 offset:2048
	ds_read_b128 v[170:173], v161 offset:3072
	v_add_u32_e32 v161, s25, v154
	ds_read_b128 v[174:177], v161
	ds_read_b128 v[178:181], v161 offset:1024
	ds_read_b128 v[182:185], v161 offset:2048
	ds_read_b128 v[186:189], v161 offset:3072
	s_add_u32 s34, s76, 0x80000
	s_addc_u32 s35, s77, 0
	s_mov_b32 m0, s26
	v_lshl_add_u64 v[230:231], s[34:35], 0, v[136:137]
	ds_read_b128 v[190:193], v158 offset:32768
	ds_read_b128 v[194:197], v158 offset:33792
	ds_read_b128 v[198:201], v158 offset:34816
	ds_read_b128 v[202:205], v158 offset:35840
	ds_read_b128 v[206:209], v158 offset:36864
	ds_read_b128 v[210:213], v158 offset:37888
	ds_read_b128 v[214:217], v158 offset:38912
	ds_read_b128 v[218:221], v158 offset:39936
	global_load_lds_dwordx4 v[230:231], off
	v_lshl_add_u64 v[230:231], s[34:35], 0, v[132:133]
	s_mov_b32 m0, s27
	s_nop 0
	global_load_lds_dwordx4 v[230:231], off
	s_waitcnt vmcnt(8)
	s_waitcnt lgkmcnt(0)
	s_barrier
	s_setprio 1
	s_waitcnt lgkmcnt(0)
	.p2align 3
	v_mfma_f32_16x16x32_bf16 v[126:129], v[150:153], v[190:193], v[126:129]
	v_mfma_f32_16x16x32_bf16 v[122:125], v[166:169], v[190:193], v[122:125]
	v_mfma_f32_16x16x32_bf16 v[110:113], v[150:153], v[198:201], v[110:113]
	v_mfma_f32_16x16x32_bf16 v[106:109], v[166:169], v[198:201], v[106:109]
	v_mfma_f32_16x16x32_bf16 v[94:97], v[150:153], v[206:209], v[94:97]
	v_mfma_f32_16x16x32_bf16 v[90:93], v[166:169], v[206:209], v[90:93]
	v_mfma_f32_16x16x32_bf16 v[78:81], v[150:153], v[214:217], v[78:81]
	v_mfma_f32_16x16x32_bf16 v[74:77], v[166:169], v[214:217], v[74:77]
	v_mfma_f32_16x16x32_bf16 v[126:129], v[162:165], v[194:197], v[126:129]
	v_mfma_f32_16x16x32_bf16 v[122:125], v[170:173], v[194:197], v[122:125]
	v_mfma_f32_16x16x32_bf16 v[110:113], v[162:165], v[202:205], v[110:113]
	v_mfma_f32_16x16x32_bf16 v[106:109], v[170:173], v[202:205], v[106:109]
	v_mfma_f32_16x16x32_bf16 v[94:97], v[162:165], v[210:213], v[94:97]
	v_mfma_f32_16x16x32_bf16 v[90:93], v[170:173], v[210:213], v[90:93]
	v_mfma_f32_16x16x32_bf16 v[78:81], v[162:165], v[218:221], v[78:81]
	v_mfma_f32_16x16x32_bf16 v[74:77], v[170:173], v[218:221], v[74:77]
	s_setprio 0
	s_setprio 1
	.p2align 3
	v_mfma_f32_16x16x32_bf16 v[118:121], v[174:177], v[190:193], v[118:121]
	v_mfma_f32_16x16x32_bf16 v[114:117], v[182:185], v[190:193], v[114:117]
	v_mfma_f32_16x16x32_bf16 v[102:105], v[174:177], v[198:201], v[102:105]
	v_mfma_f32_16x16x32_bf16 v[98:101], v[182:185], v[198:201], v[98:101]
	v_mfma_f32_16x16x32_bf16 v[86:89], v[174:177], v[206:209], v[86:89]
	v_mfma_f32_16x16x32_bf16 v[82:85], v[182:185], v[206:209], v[82:85]
	v_mfma_f32_16x16x32_bf16 v[70:73], v[174:177], v[214:217], v[70:73]
	v_mfma_f32_16x16x32_bf16 v[66:69], v[182:185], v[214:217], v[66:69]
	v_mfma_f32_16x16x32_bf16 v[118:121], v[178:181], v[194:197], v[118:121]
	v_mfma_f32_16x16x32_bf16 v[114:117], v[186:189], v[194:197], v[114:117]
	v_mfma_f32_16x16x32_bf16 v[102:105], v[178:181], v[202:205], v[102:105]
	v_mfma_f32_16x16x32_bf16 v[98:101], v[186:189], v[202:205], v[98:101]
	v_mfma_f32_16x16x32_bf16 v[86:89], v[178:181], v[210:213], v[86:89]
	v_mfma_f32_16x16x32_bf16 v[82:85], v[186:189], v[210:213], v[82:85]
	v_mfma_f32_16x16x32_bf16 v[70:73], v[178:181], v[218:221], v[70:73]
	v_mfma_f32_16x16x32_bf16 v[66:69], v[186:189], v[218:221], v[66:69]
	s_setprio 0
	s_barrier
; #define PG8_STAGEA(bufoff, gbase, voff) PG8_STAGE_X(bufoff, gbase, voff, PG8_AUX_A)
; #define PG8_STAGEB(bufoff, gbase, voff) PG8_STAGE_X(bufoff, gbase, voff, PG8_AUX_B)
; #define PG8_LDA(dst, b, h) do { _Pragma("unroll") for (int m = 0; m < 4; ++m) _Pragma("unroll") for (int k = 0; k < 2; ++k) dst[m][k] = *(const PG8_LAS bf16x8*)(lds + PG8_SA(b, h) + aoff + m * 2048 + k * 1024); } while (0)
; #define PG8_MMA(ai, bj, At, Bt) do { __builtin_amdgcn_s_setprio(1); _Pragma("unroll") for (int m = 0; m < 4; ++m) _Pragma("unroll") for (int n = 0; n < 2; ++n) _Pragma("unroll") for (int k = 0; k < 2; ++k) \
;         acc[ai][bj][m][n] = __builtin_amdgcn_mfma_f32_16x16x32_bf16(Bt[n][k], At[m][k], acc[ai][bj][m][n], 0, 0, 0); __builtin_amdgcn_s_setprio(0); } while (0)
; #define PG8_WAIT_V(n) asm volatile("s_waitcnt vmcnt(" #n ")" ::: "memory")
; #define PG8_WAIT_L(n) asm volatile("s_waitcnt lgkmcnt(" #n ")" ::: "memory")
; #define PG8_BAR __builtin_amdgcn_s_barrier()
; #define PG8_SCHED __builtin_amdgcn_sched_barrier(0)
; template <class Epi, class Sched, bool ALIGN_EPI = false, bool SP2 = false>
; __device__ __forceinline__ void gemm_phase(PG8_LAS unsigned char* lds, const Gemm g, const Sched& S, const Epi& E) {
;     ...
;             PG8_LDA(At, 1, 1); PG8_STAGEB(PG8_SB(1, 0), b3, voffB); PG8_STAGEB(PG8_SB(1, 1), b3 + hstep, voffB); PG8_STAGEA(PG8_SA(1, 0), a3, voffA);
;             PG8_WAIT_V(8); PG8_WAIT_L(0); PG8_BAR; PG8_MMA(1, 0, At, B0); PG8_MMA(1, 1, At, B1); PG8_BAR; PG8_SCHED;
;     ...
;         if constexpr (ALIGN_EPI) { if (wr == 0) PG8_BAR; }
	s_add_i32 s24, s24, s9
	v_lshl_add_u64 v[222:223], v[222:223], 0, s[54:55]
	s_mov_b32 m0, s24
	ds_read_b128 v[190:193], v158 offset:49152
	ds_read_b128 v[194:197], v158 offset:50176
	ds_read_b128 v[198:201], v158 offset:51200
	ds_read_b128 v[202:205], v158 offset:52224
	ds_read_b128 v[206:209], v158 offset:53248
	ds_read_b128 v[210:213], v158 offset:54272
	ds_read_b128 v[214:217], v158 offset:55296
	ds_read_b128 v[218:221], v158 offset:56320
	global_load_lds_dwordx4 v[222:223], off
	s_add_i32 m0, s24, 0x2000
	s_add_u32 s34, s74, 0x80080
	v_lshl_add_u64 v[222:223], v[224:225], 0, s[54:55]
	s_addc_u32 s35, s75, 0
	s_add_i32 s24, s25, s9
	global_load_lds_dwordx4 v[222:223], off
	v_lshl_add_u64 v[222:223], s[34:35], 0, v[134:135]
	s_mov_b32 m0, s24
	s_nop 0
	global_load_lds_dwordx4 v[222:223], off
	v_lshl_add_u64 v[222:223], s[34:35], 0, v[130:131]
	s_add_i32 m0, s24, 0x2000
	s_nop 0
	global_load_lds_dwordx4 v[222:223], off
	v_lshl_add_u64 v[222:223], v[226:227], 0, s[54:55]
	s_mov_b32 m0, s79
	s_nop 0
	global_load_lds_dwordx4 v[222:223], off
	v_lshl_add_u64 v[222:223], v[228:229], 0, s[54:55]
	s_mov_b32 m0, s80
	s_nop 0
	global_load_lds_dwordx4 v[222:223], off
	s_waitcnt vmcnt(8)
	s_waitcnt lgkmcnt(0)
	s_barrier
	s_setprio 1
	s_waitcnt lgkmcnt(0)
	.p2align 3
	v_mfma_f32_16x16x32_bf16 v[62:65], v[150:153], v[190:193], v[62:65]
	v_mfma_f32_16x16x32_bf16 v[58:61], v[166:169], v[190:193], v[58:61]
	v_mfma_f32_16x16x32_bf16 v[46:49], v[150:153], v[198:201], v[46:49]
	v_mfma_f32_16x16x32_bf16 v[42:45], v[166:169], v[198:201], v[42:45]
	v_mfma_f32_16x16x32_bf16 v[30:33], v[150:153], v[206:209], v[30:33]
	v_mfma_f32_16x16x32_bf16 v[26:29], v[166:169], v[206:209], v[26:29]
	v_mfma_f32_16x16x32_bf16 v[14:17], v[150:153], v[214:217], v[14:17]
	v_mfma_f32_16x16x32_bf16 v[10:13], v[166:169], v[214:217], v[10:13]
	v_mfma_f32_16x16x32_bf16 v[62:65], v[162:165], v[194:197], v[62:65]
	v_mfma_f32_16x16x32_bf16 v[58:61], v[170:173], v[194:197], v[58:61]
	v_mfma_f32_16x16x32_bf16 v[46:49], v[162:165], v[202:205], v[46:49]
	v_mfma_f32_16x16x32_bf16 v[42:45], v[170:173], v[202:205], v[42:45]
	v_mfma_f32_16x16x32_bf16 v[30:33], v[162:165], v[210:213], v[30:33]
	v_mfma_f32_16x16x32_bf16 v[26:29], v[170:173], v[210:213], v[26:29]
	v_mfma_f32_16x16x32_bf16 v[14:17], v[162:165], v[218:221], v[14:17]
	v_mfma_f32_16x16x32_bf16 v[10:13], v[170:173], v[218:221], v[10:13]
	s_setprio 0
	s_setprio 1
	.p2align 3
	v_mfma_f32_16x16x32_bf16 v[54:57], v[174:177], v[190:193], v[54:57]
	v_mfma_f32_16x16x32_bf16 v[50:53], v[182:185], v[190:193], v[50:53]
	v_mfma_f32_16x16x32_bf16 v[38:41], v[174:177], v[198:201], v[38:41]
	v_mfma_f32_16x16x32_bf16 v[34:37], v[182:185], v[198:201], v[34:37]
	v_mfma_f32_16x16x32_bf16 v[22:25], v[174:177], v[206:209], v[22:25]
	v_mfma_f32_16x16x32_bf16 v[18:21], v[182:185], v[206:209], v[18:21]
	v_mfma_f32_16x16x32_bf16 v[6:9], v[174:177], v[214:217], v[6:9]
	v_mfma_f32_16x16x32_bf16 v[2:5], v[182:185], v[214:217], v[2:5]
	v_mfma_f32_16x16x32_bf16 v[54:57], v[178:181], v[194:197], v[54:57]
	v_mfma_f32_16x16x32_bf16 v[50:53], v[186:189], v[194:197], v[50:53]
	v_mfma_f32_16x16x32_bf16 v[38:41], v[178:181], v[202:205], v[38:41]
	v_mfma_f32_16x16x32_bf16 v[34:37], v[186:189], v[202:205], v[34:37]
	v_mfma_f32_16x16x32_bf16 v[22:25], v[178:181], v[210:213], v[22:25]
	v_mfma_f32_16x16x32_bf16 v[18:21], v[186:189], v[210:213], v[18:21]
	v_mfma_f32_16x16x32_bf16 v[6:9], v[178:181], v[218:221], v[6:9]
	v_mfma_f32_16x16x32_bf16 v[2:5], v[186:189], v[218:221], v[2:5]
	s_setprio 0
	s_barrier
	s_add_u32 s72, s72, 0x100
	s_addc_u32 s73, s73, 0
	s_mov_b32 s74, s90
	s_cbranch_vccz .LBB0_734
	s_and_b64 vcc, exec, s[56:57]
	s_cbranch_vccz .LBB0_737
	s_barrier

; #define PG8_STAGEA(bufoff, gbase, voff) PG8_STAGE_X(bufoff, gbase, voff, PG8_AUX_A)
; #define PG8_STAGEB(bufoff, gbase, voff) PG8_STAGE_X(bufoff, gbase, voff, PG8_AUX_B)
; #define PG8_LDA(dst, b, h) do { _Pragma("unroll") for (int m = 0; m < 4; ++m) _Pragma("unroll") for (int k = 0; k < 2; ++k) dst[m][k] = *(const PG8_LAS bf16x8*)(lds + PG8_SA(b, h) + aoff + m * 2048 + k * 1024); } while (0)
; #define PG8_LDB(dst, b, h) do { _Pragma("unroll") for (int n = 0; n < 2; ++n) _Pragma("unroll") for (int k = 0; k < 2; ++k) dst[n][k] = *(const PG8_LAS bf16x8*)(lds + PG8_SB(b, h) + boff + n * 2048 + k * 1024); } while (0)
; #define PG8_WAIT_V(n) asm volatile("s_waitcnt vmcnt(" #n ")" ::: "memory")
; #define PG8_WAIT_L(n) asm volatile("s_waitcnt lgkmcnt(" #n ")" ::: "memory")
; template <class Epi, class Sched, bool ALIGN_EPI = false, bool SP2 = false>
; __device__ __forceinline__ void gemm_phase(PG8_LAS unsigned char* lds, const Gemm g, const Sched& S, const Epi& E) {
;     ...
;             const bool last = (t == nt - 2);
;             if constexpr (HasMid<Epi>::value) { if (t == ns) E.mid(acc, cur, wr, wc, fr, fq); }
;             const char* sA1 = (t + 1 >= ns) ? cA2 : cA; const char* sA2 = (t + 2 >= ns) ? cA2 : cA; const char* sB2 = (t + 2 >= ns) ? cB2 : cB;
;             const char* a1 = sA1 + (size_t)(t + 1) * kstep;
;             const char* a2 = last ? nA : sA2 + (size_t)(t + 2) * kstep; const char* b2 = last ? nB : sB2 + (size_t)(t + 2) * kstep;
;             const char* a3 = a2 + kstep; const char* b3 = b2 + kstep;
;             if (last && has_next) S.a_ready(nxt);
;             if constexpr (SP2) {
;             PG8_LDB(B0, 0, 0); PG8_LDB(B1, 0, 1); PG8_SCHED; PG8_LDA(At, 0, 0); PG8_STAGEA(PG8_SA(1, 1), a1 + hstep, voffA);
;             PG8_WAIT_V(8); PG8_WAIT_L(0); PG8_BAR; PG8_MMA(0, 0, At, B0); PG8_MMA(0, 1, At, B1); PG8_BAR; PG8_SCHED;
;             PG8_LDA(At, 0, 1); PG8_STAGEB(PG8_SB(0, 0), b2, voffB); PG8_STAGEB(PG8_SB(0, 1), b2 + hstep, voffB); PG8_STAGEA(PG8_SA(0, 0), a2, voffA);
;             PG8_WAIT_V(8); PG8_WAIT_L(0); PG8_BAR; PG8_MMA(1, 0, At, B0); PG8_MMA(1, 1, At, B1); PG8_BAR; PG8_SCHED;
;             PG8_LDB(B0, 1, 0); PG8_LDB(B1, 1, 1); PG8_SCHED; PG8_LDA(At, 1, 0); PG8_STAGEA(PG8_SA(0, 1), a2 + hstep, voffA);
;             PG8_WAIT_V(8); PG8_WAIT_L(0); PG8_BAR; PG8_MMA(0, 0, At, B0); PG8_MMA(0, 1, At, B1); PG8_BAR; PG8_SCHED;
.LBB0_750:
	s_add_i32 s91, s70, 2
	s_cmp_gt_u32 s91, 29
	s_cselect_b64 s[34:35], -1, 0
	s_and_b64 vcc, s[34:35], exec
	s_cselect_b32 s29, s4, s66
	ds_read_b128 v[152:155], v148
	ds_read_b128 v[156:159], v148 offset:1024
	ds_read_b128 v[160:163], v148 offset:2048
	ds_read_b128 v[164:167], v148 offset:3072
	ds_read_b128 v[168:171], v149
	ds_read_b128 v[172:175], v149 offset:1024
	ds_read_b128 v[176:179], v149 offset:2048
	ds_read_b128 v[180:183], v149 offset:3072
	s_cselect_b32 s24, s3, s65
	s_cselect_b32 s25, s2, s64
	s_cselect_b32 s28, s5, s67
	s_add_u32 s29, s29, s68
	s_addc_u32 s28, s28, s69
	s_add_u32 s29, s29, 0xfff80080
	s_addc_u32 s28, s28, -1
	s_add_u32 s25, s25, s68
	s_addc_u32 s24, s24, s69
	s_add_u32 s25, s25, 0xfff80080
	s_addc_u32 s24, s24, -1
	s_cmp_eq_u32 s70, 28
	s_cselect_b32 s70, s90, s25
	s_cselect_b32 s73, s55, s28
	s_cselect_b32 s72, s87, s29
	s_cselect_b32 s71, s53, s24
	v_lshl_add_u64 v[216:217], v[142:143], 0, s[68:69]
	s_add_i32 m0, s63, 0xc000
	ds_read_b128 v[184:187], v150
	ds_read_b128 v[188:191], v150 offset:1024
	ds_read_b128 v[192:195], v150 offset:2048
	ds_read_b128 v[196:199], v150 offset:3072
	ds_read_b128 v[200:203], v150 offset:4096
	ds_read_b128 v[204:207], v150 offset:5120
	ds_read_b128 v[208:211], v150 offset:6144
	ds_read_b128 v[212:215], v150 offset:7168
	global_load_lds_dwordx4 v[216:217], off
	v_lshl_add_u64 v[216:217], v[144:145], 0, s[68:69]
	s_add_i32 m0, s63, 0xe000
	s_nop 0
	global_load_lds_dwordx4 v[216:217], off
	s_waitcnt vmcnt(8)
	s_waitcnt lgkmcnt(0)
	s_barrier
	s_setprio 1
	s_waitcnt lgkmcnt(0)
	.p2align 3
	v_mfma_f32_16x16x32_bf16 v[126:129], v[152:155], v[184:187], v[126:129]
	v_mfma_f32_16x16x32_bf16 v[122:125], v[160:163], v[184:187], v[122:125]
	v_mfma_f32_16x16x32_bf16 v[118:121], v[152:155], v[192:195], v[118:121]
	v_mfma_f32_16x16x32_bf16 v[110:113], v[160:163], v[192:195], v[110:113]
	v_mfma_f32_16x16x32_bf16 v[102:105], v[152:155], v[200:203], v[102:105]
	v_mfma_f32_16x16x32_bf16 v[94:97], v[160:163], v[200:203], v[94:97]
	v_mfma_f32_16x16x32_bf16 v[86:89], v[152:155], v[208:211], v[86:89]
	v_mfma_f32_16x16x32_bf16 v[78:81], v[160:163], v[208:211], v[78:81]
	v_mfma_f32_16x16x32_bf16 v[126:129], v[156:159], v[188:191], v[126:129]
	v_mfma_f32_16x16x32_bf16 v[122:125], v[164:167], v[188:191], v[122:125]
	v_mfma_f32_16x16x32_bf16 v[118:121], v[156:159], v[196:199], v[118:121]
	v_mfma_f32_16x16x32_bf16 v[110:113], v[164:167], v[196:199], v[110:113]
	v_mfma_f32_16x16x32_bf16 v[102:105], v[156:159], v[204:207], v[102:105]
	v_mfma_f32_16x16x32_bf16 v[94:97], v[164:167], v[204:207], v[94:97]
	v_mfma_f32_16x16x32_bf16 v[86:89], v[156:159], v[212:215], v[86:89]
	v_mfma_f32_16x16x32_bf16 v[78:81], v[164:167], v[212:215], v[78:81]
	s_setprio 0
	s_setprio 1
	.p2align 3
	v_mfma_f32_16x16x32_bf16 v[114:117], v[168:171], v[184:187], v[114:117]
	v_mfma_f32_16x16x32_bf16 v[106:109], v[176:179], v[184:187], v[106:109]
	v_mfma_f32_16x16x32_bf16 v[98:101], v[168:171], v[192:195], v[98:101]
	v_mfma_f32_16x16x32_bf16 v[90:93], v[176:179], v[192:195], v[90:93]
	v_mfma_f32_16x16x32_bf16 v[82:85], v[168:171], v[200:203], v[82:85]
	v_mfma_f32_16x16x32_bf16 v[74:77], v[176:179], v[200:203], v[74:77]
	v_mfma_f32_16x16x32_bf16 v[70:73], v[168:171], v[208:211], v[70:73]
	v_mfma_f32_16x16x32_bf16 v[66:69], v[176:179], v[208:211], v[66:69]
	v_mfma_f32_16x16x32_bf16 v[114:117], v[172:175], v[188:191], v[114:117]
	v_mfma_f32_16x16x32_bf16 v[106:109], v[180:183], v[188:191], v[106:109]
	v_mfma_f32_16x16x32_bf16 v[98:101], v[172:175], v[196:199], v[98:101]
	v_mfma_f32_16x16x32_bf16 v[90:93], v[180:183], v[196:199], v[90:93]
	v_mfma_f32_16x16x32_bf16 v[82:85], v[172:175], v[204:207], v[82:85]
	v_mfma_f32_16x16x32_bf16 v[74:77], v[180:183], v[204:207], v[74:77]
	v_mfma_f32_16x16x32_bf16 v[70:73], v[172:175], v[212:215], v[70:73]
	v_mfma_f32_16x16x32_bf16 v[66:69], v[180:183], v[212:215], v[66:69]
	s_setprio 0
	s_barrier
	s_add_i32 s24, s82, s74
	v_lshl_add_u64 v[216:217], s[70:71], 0, v[134:135]
	s_mov_b32 m0, s24
	ds_read_b128 v[184:187], v150 offset:16384
	ds_read_b128 v[188:191], v150 offset:17408
	ds_read_b128 v[192:195], v150 offset:18432
	ds_read_b128 v[196:199], v150 offset:19456
	ds_read_b128 v[200:203], v150 offset:20480
	ds_read_b128 v[204:207], v150 offset:21504
	ds_read_b128 v[208:211], v150 offset:22528
	ds_read_b128 v[212:215], v150 offset:23552
	global_load_lds_dwordx4 v[216:217], off
	s_add_i32 m0, s24, 0x2000
	s_add_u32 s34, s70, 0x80000
	v_lshl_add_u64 v[218:219], s[70:71], 0, v[130:131]
	s_addc_u32 s35, s71, 0
	s_add_i32 s24, s83, s74
	global_load_lds_dwordx4 v[218:219], off
	v_lshl_add_u64 v[220:221], s[34:35], 0, v[134:135]
	s_mov_b32 m0, s24
	v_lshl_add_u64 v[222:223], s[72:73], 0, v[132:133]
	global_load_lds_dwordx4 v[220:221], off
	v_lshl_add_u64 v[220:221], s[34:35], 0, v[130:131]
	s_add_i32 m0, s24, 0x2000
	s_nop 0
	global_load_lds_dwordx4 v[220:221], off
	v_lshl_add_u64 v[220:221], s[72:73], 0, v[136:137]
	s_mov_b32 m0, s63
	s_nop 0
	global_load_lds_dwordx4 v[220:221], off
	s_mov_b32 m0, s76
	s_nop 0
	global_load_lds_dwordx4 v[222:223], off
	s_waitcnt vmcnt(8)
	s_waitcnt lgkmcnt(0)
	s_barrier
; #define PG8_STAGEA(bufoff, gbase, voff) PG8_STAGE_X(bufoff, gbase, voff, PG8_AUX_A)
; #define PG8_LDA(dst, b, h) do { _Pragma("unroll") for (int m = 0; m < 4; ++m) _Pragma("unroll") for (int k = 0; k < 2; ++k) dst[m][k] = *(const PG8_LAS bf16x8*)(lds + PG8_SA(b, h) + aoff + m * 2048 + k * 1024); } while (0)
; #define PG8_LDB(dst, b, h) do { _Pragma("unroll") for (int n = 0; n < 2; ++n) _Pragma("unroll") for (int k = 0; k < 2; ++k) dst[n][k] = *(const PG8_LAS bf16x8*)(lds + PG8_SB(b, h) + boff + n * 2048 + k * 1024); } while (0)
; #define PG8_MMA(ai, bj, At, Bt) do { __builtin_amdgcn_s_setprio(1); _Pragma("unroll") for (int m = 0; m < 4; ++m) _Pragma("unroll") for (int n = 0; n < 2; ++n) _Pragma("unroll") for (int k = 0; k < 2; ++k) \
;         acc[ai][bj][m][n] = __builtin_amdgcn_mfma_f32_16x16x32_bf16(Bt[n][k], At[m][k], acc[ai][bj][m][n], 0, 0, 0); __builtin_amdgcn_s_setprio(0); } while (0)
; #define PG8_WAIT_V(n) asm volatile("s_waitcnt vmcnt(" #n ")" ::: "memory")
; #define PG8_WAIT_L(n) asm volatile("s_waitcnt lgkmcnt(" #n ")" ::: "memory")
; #define PG8_BAR __builtin_amdgcn_s_barrier()
; #define PG8_SCHED __builtin_amdgcn_sched_barrier(0)
; template <class Epi, class Sched, bool ALIGN_EPI = false, bool SP2 = false>
; __device__ __forceinline__ void gemm_phase(PG8_LAS unsigned char* lds, const Gemm g, const Sched& S, const Epi& E) {
;     ...
;             PG8_WAIT_V(8); PG8_WAIT_L(0); PG8_BAR; PG8_MMA(1, 0, At, B0); PG8_MMA(1, 1, At, B1); PG8_BAR; PG8_SCHED;
;             PG8_LDB(B0, 1, 0); PG8_LDB(B1, 1, 1); PG8_SCHED; PG8_LDA(At, 1, 0); PG8_STAGEA(PG8_SA(0, 1), a2 + hstep, voffA);
;             PG8_WAIT_V(8); PG8_WAIT_L(0); PG8_BAR; PG8_MMA(0, 0, At, B0); PG8_MMA(0, 1, At, B1); PG8_BAR; PG8_SCHED;
	s_setprio 1
	s_waitcnt lgkmcnt(0)
	.p2align 3
	v_mfma_f32_16x16x32_bf16 v[62:65], v[152:155], v[184:187], v[62:65]
	v_mfma_f32_16x16x32_bf16 v[58:61], v[160:163], v[184:187], v[58:61]
	v_mfma_f32_16x16x32_bf16 v[54:57], v[152:155], v[192:195], v[54:57]
	v_mfma_f32_16x16x32_bf16 v[46:49], v[160:163], v[192:195], v[46:49]
	v_mfma_f32_16x16x32_bf16 v[38:41], v[152:155], v[200:203], v[38:41]
	v_mfma_f32_16x16x32_bf16 v[30:33], v[160:163], v[200:203], v[30:33]
	v_mfma_f32_16x16x32_bf16 v[22:25], v[152:155], v[208:211], v[22:25]
	v_mfma_f32_16x16x32_bf16 v[14:17], v[160:163], v[208:211], v[14:17]
	v_mfma_f32_16x16x32_bf16 v[62:65], v[156:159], v[188:191], v[62:65]
	v_mfma_f32_16x16x32_bf16 v[58:61], v[164:167], v[188:191], v[58:61]
	v_mfma_f32_16x16x32_bf16 v[54:57], v[156:159], v[196:199], v[54:57]
	v_mfma_f32_16x16x32_bf16 v[46:49], v[164:167], v[196:199], v[46:49]
	v_mfma_f32_16x16x32_bf16 v[38:41], v[156:159], v[204:207], v[38:41]
	v_mfma_f32_16x16x32_bf16 v[30:33], v[164:167], v[204:207], v[30:33]
	v_mfma_f32_16x16x32_bf16 v[22:25], v[156:159], v[212:215], v[22:25]
	v_mfma_f32_16x16x32_bf16 v[14:17], v[164:167], v[212:215], v[14:17]
	s_setprio 0
	s_setprio 1
	.p2align 3
	v_mfma_f32_16x16x32_bf16 v[50:53], v[168:171], v[184:187], v[50:53]
	v_mfma_f32_16x16x32_bf16 v[42:45], v[176:179], v[184:187], v[42:45]
	v_mfma_f32_16x16x32_bf16 v[34:37], v[168:171], v[192:195], v[34:37]
	v_mfma_f32_16x16x32_bf16 v[26:29], v[176:179], v[192:195], v[26:29]
	v_mfma_f32_16x16x32_bf16 v[18:21], v[168:171], v[200:203], v[18:21]
	v_mfma_f32_16x16x32_bf16 v[10:13], v[176:179], v[200:203], v[10:13]
	v_mfma_f32_16x16x32_bf16 v[6:9], v[168:171], v[208:211], v[6:9]
	v_mfma_f32_16x16x32_bf16 v[2:5], v[176:179], v[208:211], v[2:5]
	v_mfma_f32_16x16x32_bf16 v[50:53], v[172:175], v[188:191], v[50:53]
	v_mfma_f32_16x16x32_bf16 v[42:45], v[180:183], v[188:191], v[42:45]
	v_mfma_f32_16x16x32_bf16 v[34:37], v[172:175], v[196:199], v[34:37]
	v_mfma_f32_16x16x32_bf16 v[26:29], v[180:183], v[196:199], v[26:29]
	v_mfma_f32_16x16x32_bf16 v[18:21], v[172:175], v[204:207], v[18:21]
	v_mfma_f32_16x16x32_bf16 v[10:13], v[180:183], v[204:207], v[10:13]
	v_mfma_f32_16x16x32_bf16 v[6:9], v[172:175], v[212:215], v[6:9]
	v_mfma_f32_16x16x32_bf16 v[2:5], v[180:183], v[212:215], v[2:5]
	s_setprio 0
	s_barrier
	s_add_i32 s24, 0, 0x18000
	v_add_u32_e32 v151, s24, v146
	s_add_i32 s25, 0, 0x1c000
	ds_read_b128 v[152:155], v151
	ds_read_b128 v[156:159], v151 offset:1024
	ds_read_b128 v[160:163], v151 offset:2048
	ds_read_b128 v[164:167], v151 offset:3072
	v_add_u32_e32 v151, s25, v146
	ds_read_b128 v[168:171], v151
	ds_read_b128 v[172:175], v151 offset:1024
	ds_read_b128 v[176:179], v151 offset:2048
	ds_read_b128 v[180:183], v151 offset:3072
	s_add_u32 s34, s72, 0x80000
	s_addc_u32 s35, s73, 0
	s_mov_b32 m0, s77
	v_lshl_add_u64 v[224:225], s[34:35], 0, v[136:137]
	ds_read_b128 v[184:187], v150 offset:32768
	ds_read_b128 v[188:191], v150 offset:33792
	ds_read_b128 v[192:195], v150 offset:34816
	ds_read_b128 v[196:199], v150 offset:35840
	ds_read_b128 v[200:203], v150 offset:36864
	ds_read_b128 v[204:207], v150 offset:37888
	ds_read_b128 v[208:211], v150 offset:38912
	ds_read_b128 v[212:215], v150 offset:39936
	global_load_lds_dwordx4 v[224:225], off
	v_lshl_add_u64 v[224:225], s[34:35], 0, v[132:133]
	s_mov_b32 m0, s78
	s_nop 0
	global_load_lds_dwordx4 v[224:225], off
	s_waitcnt vmcnt(8)
	s_waitcnt lgkmcnt(0)
	s_barrier
	s_setprio 1
	s_waitcnt lgkmcnt(0)
	.p2align 3
	v_mfma_f32_16x16x32_bf16 v[126:129], v[152:155], v[184:187], v[126:129]
	v_mfma_f32_16x16x32_bf16 v[122:125], v[160:163], v[184:187], v[122:125]
	v_mfma_f32_16x16x32_bf16 v[118:121], v[152:155], v[192:195], v[118:121]
	v_mfma_f32_16x16x32_bf16 v[110:113], v[160:163], v[192:195], v[110:113]
	v_mfma_f32_16x16x32_bf16 v[102:105], v[152:155], v[200:203], v[102:105]
	v_mfma_f32_16x16x32_bf16 v[94:97], v[160:163], v[200:203], v[94:97]
	v_mfma_f32_16x16x32_bf16 v[86:89], v[152:155], v[208:211], v[86:89]
	v_mfma_f32_16x16x32_bf16 v[78:81], v[160:163], v[208:211], v[78:81]
	v_mfma_f32_16x16x32_bf16 v[126:129], v[156:159], v[188:191], v[126:129]
	v_mfma_f32_16x16x32_bf16 v[122:125], v[164:167], v[188:191], v[122:125]
	v_mfma_f32_16x16x32_bf16 v[118:121], v[156:159], v[196:199], v[118:121]
	v_mfma_f32_16x16x32_bf16 v[110:113], v[164:167], v[196:199], v[110:113]
	v_mfma_f32_16x16x32_bf16 v[102:105], v[156:159], v[204:207], v[102:105]
	v_mfma_f32_16x16x32_bf16 v[94:97], v[164:167], v[204:207], v[94:97]
	v_mfma_f32_16x16x32_bf16 v[86:89], v[156:159], v[212:215], v[86:89]
	v_mfma_f32_16x16x32_bf16 v[78:81], v[164:167], v[212:215], v[78:81]
	s_setprio 0
	s_setprio 1
	.p2align 3
	v_mfma_f32_16x16x32_bf16 v[114:117], v[168:171], v[184:187], v[114:117]
	v_mfma_f32_16x16x32_bf16 v[106:109], v[176:179], v[184:187], v[106:109]
	v_mfma_f32_16x16x32_bf16 v[98:101], v[168:171], v[192:195], v[98:101]
	v_mfma_f32_16x16x32_bf16 v[90:93], v[176:179], v[192:195], v[90:93]
	v_mfma_f32_16x16x32_bf16 v[82:85], v[168:171], v[200:203], v[82:85]
	v_mfma_f32_16x16x32_bf16 v[74:77], v[176:179], v[200:203], v[74:77]
	v_mfma_f32_16x16x32_bf16 v[70:73], v[168:171], v[208:211], v[70:73]
	v_mfma_f32_16x16x32_bf16 v[66:69], v[176:179], v[208:211], v[66:69]
	v_mfma_f32_16x16x32_bf16 v[114:117], v[172:175], v[188:191], v[114:117]
	v_mfma_f32_16x16x32_bf16 v[106:109], v[180:183], v[188:191], v[106:109]
	v_mfma_f32_16x16x32_bf16 v[98:101], v[172:175], v[196:199], v[98:101]
	v_mfma_f32_16x16x32_bf16 v[90:93], v[180:183], v[196:199], v[90:93]
	v_mfma_f32_16x16x32_bf16 v[82:85], v[172:175], v[204:207], v[82:85]
	v_mfma_f32_16x16x32_bf16 v[74:77], v[180:183], v[204:207], v[74:77]
	v_mfma_f32_16x16x32_bf16 v[70:73], v[172:175], v[212:215], v[70:73]
	v_mfma_f32_16x16x32_bf16 v[66:69], v[180:183], v[212:215], v[66:69]
	s_setprio 0
	s_barrier
; #define PG8_STAGEA(bufoff, gbase, voff) PG8_STAGE_X(bufoff, gbase, voff, PG8_AUX_A)
; #define PG8_STAGEB(bufoff, gbase, voff) PG8_STAGE_X(bufoff, gbase, voff, PG8_AUX_B)
; #define PG8_LDA(dst, b, h) do { _Pragma("unroll") for (int m = 0; m < 4; ++m) _Pragma("unroll") for (int k = 0; k < 2; ++k) dst[m][k] = *(const PG8_LAS bf16x8*)(lds + PG8_SA(b, h) + aoff + m * 2048 + k * 1024); } while (0)
; #define PG8_MMA(ai, bj, At, Bt) do { __builtin_amdgcn_s_setprio(1); _Pragma("unroll") for (int m = 0; m < 4; ++m) _Pragma("unroll") for (int n = 0; n < 2; ++n) _Pragma("unroll") for (int k = 0; k < 2; ++k) \
;         acc[ai][bj][m][n] = __builtin_amdgcn_mfma_f32_16x16x32_bf16(Bt[n][k], At[m][k], acc[ai][bj][m][n], 0, 0, 0); __builtin_amdgcn_s_setprio(0); } while (0)
; #define PG8_WAIT_V(n) asm volatile("s_waitcnt vmcnt(" #n ")" ::: "memory")
; #define PG8_WAIT_L(n) asm volatile("s_waitcnt lgkmcnt(" #n ")" ::: "memory")
; #define PG8_BAR __builtin_amdgcn_s_barrier()
; #define PG8_SCHED __builtin_amdgcn_sched_barrier(0)
; template <class Epi, class Sched, bool ALIGN_EPI = false, bool SP2 = false>
; __device__ __forceinline__ void gemm_phase(PG8_LAS unsigned char* lds, const Gemm g, const Sched& S, const Epi& E) {
;     ...
;             PG8_LDA(At, 1, 1); PG8_STAGEB(PG8_SB(1, 0), b3, voffB); PG8_STAGEB(PG8_SB(1, 1), b3 + hstep, voffB); PG8_STAGEA(PG8_SA(1, 0), a3, voffA);
;             PG8_WAIT_V(8); PG8_WAIT_L(0); PG8_BAR; PG8_MMA(1, 0, At, B0); PG8_MMA(1, 1, At, B1); PG8_BAR; PG8_SCHED;
;     ...
;         if constexpr (ALIGN_EPI) { if (wr == 0) PG8_BAR; }
	s_add_i32 s24, s24, s74
	v_lshl_add_u64 v[216:217], v[216:217], 0, s[46:47]
	s_mov_b32 m0, s24
	ds_read_b128 v[184:187], v150 offset:49152
	ds_read_b128 v[188:191], v150 offset:50176
	ds_read_b128 v[192:195], v150 offset:51200
	ds_read_b128 v[196:199], v150 offset:52224
	ds_read_b128 v[200:203], v150 offset:53248
	ds_read_b128 v[204:207], v150 offset:54272
	ds_read_b128 v[208:211], v150 offset:55296
	ds_read_b128 v[212:215], v150 offset:56320
	global_load_lds_dwordx4 v[216:217], off
	s_add_i32 m0, s24, 0x2000
	s_add_u32 s34, s70, 0x80080
	v_lshl_add_u64 v[216:217], v[218:219], 0, s[46:47]
	s_addc_u32 s35, s71, 0
	s_add_i32 s24, s25, s74
	global_load_lds_dwordx4 v[216:217], off
	v_lshl_add_u64 v[216:217], s[34:35], 0, v[134:135]
	s_mov_b32 m0, s24
	s_nop 0
	global_load_lds_dwordx4 v[216:217], off
	v_lshl_add_u64 v[216:217], s[34:35], 0, v[130:131]
	s_add_i32 m0, s24, 0x2000
	s_nop 0
	global_load_lds_dwordx4 v[216:217], off
	v_lshl_add_u64 v[216:217], v[220:221], 0, s[46:47]
	s_mov_b32 m0, s79
	s_nop 0
	global_load_lds_dwordx4 v[216:217], off
	v_lshl_add_u64 v[216:217], v[222:223], 0, s[46:47]
	s_mov_b32 m0, s80
	s_nop 0
	global_load_lds_dwordx4 v[216:217], off
	s_waitcnt vmcnt(8)
	s_waitcnt lgkmcnt(0)
	s_barrier
	s_setprio 1
	s_waitcnt lgkmcnt(0)
	.p2align 3
	v_mfma_f32_16x16x32_bf16 v[62:65], v[152:155], v[184:187], v[62:65]
	v_mfma_f32_16x16x32_bf16 v[58:61], v[160:163], v[184:187], v[58:61]
	v_mfma_f32_16x16x32_bf16 v[54:57], v[152:155], v[192:195], v[54:57]
	v_mfma_f32_16x16x32_bf16 v[46:49], v[160:163], v[192:195], v[46:49]
	v_mfma_f32_16x16x32_bf16 v[38:41], v[152:155], v[200:203], v[38:41]
	v_mfma_f32_16x16x32_bf16 v[30:33], v[160:163], v[200:203], v[30:33]
	v_mfma_f32_16x16x32_bf16 v[22:25], v[152:155], v[208:211], v[22:25]
	v_mfma_f32_16x16x32_bf16 v[14:17], v[160:163], v[208:211], v[14:17]
	v_mfma_f32_16x16x32_bf16 v[62:65], v[156:159], v[188:191], v[62:65]
	v_mfma_f32_16x16x32_bf16 v[58:61], v[164:167], v[188:191], v[58:61]
	v_mfma_f32_16x16x32_bf16 v[54:57], v[156:159], v[196:199], v[54:57]
	v_mfma_f32_16x16x32_bf16 v[46:49], v[164:167], v[196:199], v[46:49]
	v_mfma_f32_16x16x32_bf16 v[38:41], v[156:159], v[204:207], v[38:41]
	v_mfma_f32_16x16x32_bf16 v[30:33], v[164:167], v[204:207], v[30:33]
	v_mfma_f32_16x16x32_bf16 v[22:25], v[156:159], v[212:215], v[22:25]
	v_mfma_f32_16x16x32_bf16 v[14:17], v[164:167], v[212:215], v[14:17]
	s_setprio 0
	s_setprio 1
	.p2align 3
	v_mfma_f32_16x16x32_bf16 v[50:53], v[168:171], v[184:187], v[50:53]
	v_mfma_f32_16x16x32_bf16 v[42:45], v[176:179], v[184:187], v[42:45]
	v_mfma_f32_16x16x32_bf16 v[34:37], v[168:171], v[192:195], v[34:37]
	v_mfma_f32_16x16x32_bf16 v[26:29], v[176:179], v[192:195], v[26:29]
	v_mfma_f32_16x16x32_bf16 v[18:21], v[168:171], v[200:203], v[18:21]
	v_mfma_f32_16x16x32_bf16 v[10:13], v[176:179], v[200:203], v[10:13]
	v_mfma_f32_16x16x32_bf16 v[6:9], v[168:171], v[208:211], v[6:9]
	v_mfma_f32_16x16x32_bf16 v[2:5], v[176:179], v[208:211], v[2:5]
	v_mfma_f32_16x16x32_bf16 v[50:53], v[172:175], v[188:191], v[50:53]
	v_mfma_f32_16x16x32_bf16 v[42:45], v[180:183], v[188:191], v[42:45]
	v_mfma_f32_16x16x32_bf16 v[34:37], v[172:175], v[196:199], v[34:37]
	v_mfma_f32_16x16x32_bf16 v[26:29], v[180:183], v[196:199], v[26:29]
	v_mfma_f32_16x16x32_bf16 v[18:21], v[172:175], v[204:207], v[18:21]
	v_mfma_f32_16x16x32_bf16 v[10:13], v[180:183], v[204:207], v[10:13]
	v_mfma_f32_16x16x32_bf16 v[6:9], v[172:175], v[212:215], v[6:9]
	v_mfma_f32_16x16x32_bf16 v[2:5], v[180:183], v[212:215], v[2:5]
	s_setprio 0
	s_barrier
	s_add_u32 s68, s68, 0x100
	s_addc_u32 s69, s69, 0
	s_mov_b32 s70, s91
	s_cbranch_vccz .LBB0_750
	s_and_b64 vcc, exec, s[48:49]
	s_cbranch_vccz .LBB0_753
	s_barrier

; #define PG8_STAGEA(bufoff, gbase, voff) PG8_STAGE_X(bufoff, gbase, voff, PG8_AUX_A)
; #define PG8_STAGEB(bufoff, gbase, voff) PG8_STAGE_X(bufoff, gbase, voff, PG8_AUX_B)
; #define PG8_LDA(dst, b, h) do { _Pragma("unroll") for (int m = 0; m < 4; ++m) _Pragma("unroll") for (int k = 0; k < 2; ++k) dst[m][k] = *(const PG8_LAS bf16x8*)(lds + PG8_SA(b, h) + aoff + m * 2048 + k * 1024); } while (0)
; #define PG8_LDB(dst, b, h) do { _Pragma("unroll") for (int n = 0; n < 2; ++n) _Pragma("unroll") for (int k = 0; k < 2; ++k) dst[n][k] = *(const PG8_LAS bf16x8*)(lds + PG8_SB(b, h) + boff + n * 2048 + k * 1024); } while (0)
; #define PG8_WAIT_V(n) asm volatile("s_waitcnt vmcnt(" #n ")" ::: "memory")
; #define PG8_WAIT_L(n) asm volatile("s_waitcnt lgkmcnt(" #n ")" ::: "memory")
; template <class Epi, class Sched, bool ALIGN_EPI = false, bool SP2 = false>
; __device__ __forceinline__ void gemm_phase(PG8_LAS unsigned char* lds, const Gemm g, const Sched& S, const Epi& E) {
;     ...
;             const bool last = (t == nt - 2);
;             if constexpr (HasMid<Epi>::value) { if (t == ns) E.mid(acc, cur, wr, wc, fr, fq); }
;             const char* sA1 = (t + 1 >= ns) ? cA2 : cA; const char* sA2 = (t + 2 >= ns) ? cA2 : cA; const char* sB2 = (t + 2 >= ns) ? cB2 : cB;
;             const char* a1 = sA1 + (size_t)(t + 1) * kstep;
;             const char* a2 = last ? nA : sA2 + (size_t)(t + 2) * kstep; const char* b2 = last ? nB : sB2 + (size_t)(t + 2) * kstep;
;             const char* a3 = a2 + kstep; const char* b3 = b2 + kstep;
;             if (last && has_next) S.a_ready(nxt);
;             if constexpr (SP2) {
;             PG8_LDB(B0, 0, 0); PG8_LDB(B1, 0, 1); PG8_SCHED; PG8_LDA(At, 0, 0); PG8_STAGEA(PG8_SA(1, 1), a1 + hstep, voffA);
;             PG8_WAIT_V(8); PG8_WAIT_L(0); PG8_BAR; PG8_MMA(0, 0, At, B0); PG8_MMA(0, 1, At, B1); PG8_BAR; PG8_SCHED;
;             PG8_LDA(At, 0, 1); PG8_STAGEB(PG8_SB(0, 0), b2, voffB); PG8_STAGEB(PG8_SB(0, 1), b2 + hstep, voffB); PG8_STAGEA(PG8_SA(0, 0), a2, voffA);
;             PG8_WAIT_V(8); PG8_WAIT_L(0); PG8_BAR; PG8_MMA(1, 0, At, B0); PG8_MMA(1, 1, At, B1); PG8_BAR; PG8_SCHED;
;             PG8_LDB(B0, 1, 0); PG8_LDB(B1, 1, 1); PG8_SCHED; PG8_LDA(At, 1, 0); PG8_STAGEA(PG8_SA(0, 1), a2 + hstep, voffA);
;             PG8_WAIT_V(8); PG8_WAIT_L(0); PG8_BAR; PG8_MMA(0, 0, At, B0); PG8_MMA(0, 1, At, B1); PG8_BAR; PG8_SCHED;
.LBB0_766:
	s_add_i32 s91, s70, 2
	s_cmp_gt_u32 s91, 29
	s_cselect_b64 s[72:73], -1, 0
	s_and_b64 vcc, s[72:73], exec
	s_cselect_b32 s29, s4, s66
	ds_read_b128 v[152:155], v148
	ds_read_b128 v[156:159], v148 offset:1024
	ds_read_b128 v[160:163], v148 offset:2048
	ds_read_b128 v[164:167], v148 offset:3072
	ds_read_b128 v[168:171], v149
	ds_read_b128 v[172:175], v149 offset:1024
	ds_read_b128 v[176:179], v149 offset:2048
	ds_read_b128 v[180:183], v149 offset:3072
	s_cselect_b32 s24, s3, s65
	s_cselect_b32 s25, s2, s64
	s_cselect_b32 s28, s5, s67
	s_add_u32 s29, s29, s68
	s_addc_u32 s28, s28, s69
	s_add_u32 s29, s29, 0xfff80080
	s_addc_u32 s28, s28, -1
	s_add_u32 s25, s25, s68
	s_addc_u32 s24, s24, s69
	s_add_u32 s25, s25, 0xfff80080
	s_addc_u32 s24, s24, -1
	s_cmp_eq_u32 s70, 28
	s_cselect_b32 s70, s90, s25
	s_cselect_b32 s73, s55, s28
	s_cselect_b32 s72, s87, s29
	s_cselect_b32 s71, s53, s24
	v_lshl_add_u64 v[216:217], v[142:143], 0, s[68:69]
	s_add_i32 m0, s63, 0xc000
	ds_read_b128 v[184:187], v150
	ds_read_b128 v[188:191], v150 offset:1024
	ds_read_b128 v[192:195], v150 offset:2048
	ds_read_b128 v[196:199], v150 offset:3072
	ds_read_b128 v[200:203], v150 offset:4096
	ds_read_b128 v[204:207], v150 offset:5120
	ds_read_b128 v[208:211], v150 offset:6144
	ds_read_b128 v[212:215], v150 offset:7168
	global_load_lds_dwordx4 v[216:217], off
	v_lshl_add_u64 v[216:217], v[144:145], 0, s[68:69]
	s_add_i32 m0, s63, 0xe000
	s_nop 0
	global_load_lds_dwordx4 v[216:217], off
	s_waitcnt vmcnt(8)
	s_waitcnt lgkmcnt(0)
	s_barrier
	s_setprio 1
	s_waitcnt lgkmcnt(0)
	.p2align 3
	v_mfma_f32_16x16x32_bf16 v[126:129], v[152:155], v[184:187], v[126:129]
	v_mfma_f32_16x16x32_bf16 v[122:125], v[160:163], v[184:187], v[122:125]
	v_mfma_f32_16x16x32_bf16 v[118:121], v[152:155], v[192:195], v[118:121]
	v_mfma_f32_16x16x32_bf16 v[110:113], v[160:163], v[192:195], v[110:113]
	v_mfma_f32_16x16x32_bf16 v[102:105], v[152:155], v[200:203], v[102:105]
	v_mfma_f32_16x16x32_bf16 v[94:97], v[160:163], v[200:203], v[94:97]
	v_mfma_f32_16x16x32_bf16 v[86:89], v[152:155], v[208:211], v[86:89]
	v_mfma_f32_16x16x32_bf16 v[78:81], v[160:163], v[208:211], v[78:81]
	v_mfma_f32_16x16x32_bf16 v[126:129], v[156:159], v[188:191], v[126:129]
	v_mfma_f32_16x16x32_bf16 v[122:125], v[164:167], v[188:191], v[122:125]
	v_mfma_f32_16x16x32_bf16 v[118:121], v[156:159], v[196:199], v[118:121]
	v_mfma_f32_16x16x32_bf16 v[110:113], v[164:167], v[196:199], v[110:113]
	v_mfma_f32_16x16x32_bf16 v[102:105], v[156:159], v[204:207], v[102:105]
	v_mfma_f32_16x16x32_bf16 v[94:97], v[164:167], v[204:207], v[94:97]
	v_mfma_f32_16x16x32_bf16 v[86:89], v[156:159], v[212:215], v[86:89]
	v_mfma_f32_16x16x32_bf16 v[78:81], v[164:167], v[212:215], v[78:81]
	s_setprio 0
	s_setprio 1
	.p2align 3
	v_mfma_f32_16x16x32_bf16 v[114:117], v[168:171], v[184:187], v[114:117]
	v_mfma_f32_16x16x32_bf16 v[106:109], v[176:179], v[184:187], v[106:109]
	v_mfma_f32_16x16x32_bf16 v[98:101], v[168:171], v[192:195], v[98:101]
	v_mfma_f32_16x16x32_bf16 v[90:93], v[176:179], v[192:195], v[90:93]
	v_mfma_f32_16x16x32_bf16 v[82:85], v[168:171], v[200:203], v[82:85]
	v_mfma_f32_16x16x32_bf16 v[74:77], v[176:179], v[200:203], v[74:77]
	v_mfma_f32_16x16x32_bf16 v[70:73], v[168:171], v[208:211], v[70:73]
	v_mfma_f32_16x16x32_bf16 v[66:69], v[176:179], v[208:211], v[66:69]
	v_mfma_f32_16x16x32_bf16 v[114:117], v[172:175], v[188:191], v[114:117]
	v_mfma_f32_16x16x32_bf16 v[106:109], v[180:183], v[188:191], v[106:109]
	v_mfma_f32_16x16x32_bf16 v[98:101], v[172:175], v[196:199], v[98:101]
	v_mfma_f32_16x16x32_bf16 v[90:93], v[180:183], v[196:199], v[90:93]
	v_mfma_f32_16x16x32_bf16 v[82:85], v[172:175], v[204:207], v[82:85]
	v_mfma_f32_16x16x32_bf16 v[74:77], v[180:183], v[204:207], v[74:77]
	v_mfma_f32_16x16x32_bf16 v[70:73], v[172:175], v[212:215], v[70:73]
	v_mfma_f32_16x16x32_bf16 v[66:69], v[180:183], v[212:215], v[66:69]
	s_setprio 0
	s_barrier
	s_add_i32 s24, s81, s23
	v_lshl_add_u64 v[216:217], s[70:71], 0, v[134:135]
	s_mov_b32 m0, s24
	ds_read_b128 v[184:187], v150 offset:16384
	ds_read_b128 v[188:191], v150 offset:17408
	ds_read_b128 v[192:195], v150 offset:18432
	ds_read_b128 v[196:199], v150 offset:19456
	ds_read_b128 v[200:203], v150 offset:20480
	ds_read_b128 v[204:207], v150 offset:21504
	ds_read_b128 v[208:211], v150 offset:22528
	ds_read_b128 v[212:215], v150 offset:23552
	global_load_lds_dwordx4 v[216:217], off
	s_add_i32 m0, s24, 0x2000
	s_add_u32 s92, s70, 0x80000
	v_lshl_add_u64 v[218:219], s[70:71], 0, v[130:131]
	s_addc_u32 s93, s71, 0
	s_add_i32 s24, s82, s23
	global_load_lds_dwordx4 v[218:219], off
	v_lshl_add_u64 v[220:221], s[92:93], 0, v[134:135]
	s_mov_b32 m0, s24
	v_lshl_add_u64 v[222:223], s[72:73], 0, v[132:133]
	global_load_lds_dwordx4 v[220:221], off
	v_lshl_add_u64 v[220:221], s[92:93], 0, v[130:131]
	s_add_i32 m0, s24, 0x2000
	s_nop 0
	global_load_lds_dwordx4 v[220:221], off
	v_lshl_add_u64 v[220:221], s[72:73], 0, v[136:137]
	s_mov_b32 m0, s63
	s_nop 0
	global_load_lds_dwordx4 v[220:221], off
	s_mov_b32 m0, s75
	s_nop 0
	global_load_lds_dwordx4 v[222:223], off
	s_waitcnt vmcnt(8)
	s_waitcnt lgkmcnt(0)
	s_barrier
; #define PG8_STAGEA(bufoff, gbase, voff) PG8_STAGE_X(bufoff, gbase, voff, PG8_AUX_A)
; #define PG8_LDA(dst, b, h) do { _Pragma("unroll") for (int m = 0; m < 4; ++m) _Pragma("unroll") for (int k = 0; k < 2; ++k) dst[m][k] = *(const PG8_LAS bf16x8*)(lds + PG8_SA(b, h) + aoff + m * 2048 + k * 1024); } while (0)
; #define PG8_LDB(dst, b, h) do { _Pragma("unroll") for (int n = 0; n < 2; ++n) _Pragma("unroll") for (int k = 0; k < 2; ++k) dst[n][k] = *(const PG8_LAS bf16x8*)(lds + PG8_SB(b, h) + boff + n * 2048 + k * 1024); } while (0)
; #define PG8_MMA(ai, bj, At, Bt) do { __builtin_amdgcn_s_setprio(1); _Pragma("unroll") for (int m = 0; m < 4; ++m) _Pragma("unroll") for (int n = 0; n < 2; ++n) _Pragma("unroll") for (int k = 0; k < 2; ++k) \
;         acc[ai][bj][m][n] = __builtin_amdgcn_mfma_f32_16x16x32_bf16(Bt[n][k], At[m][k], acc[ai][bj][m][n], 0, 0, 0); __builtin_amdgcn_s_setprio(0); } while (0)
; #define PG8_WAIT_V(n) asm volatile("s_waitcnt vmcnt(" #n ")" ::: "memory")
; #define PG8_WAIT_L(n) asm volatile("s_waitcnt lgkmcnt(" #n ")" ::: "memory")
; #define PG8_BAR __builtin_amdgcn_s_barrier()
; #define PG8_SCHED __builtin_amdgcn_sched_barrier(0)
; template <class Epi, class Sched, bool ALIGN_EPI = false, bool SP2 = false>
; __device__ __forceinline__ void gemm_phase(PG8_LAS unsigned char* lds, const Gemm g, const Sched& S, const Epi& E) {
;     ...
;             PG8_WAIT_V(8); PG8_WAIT_L(0); PG8_BAR; PG8_MMA(1, 0, At, B0); PG8_MMA(1, 1, At, B1); PG8_BAR; PG8_SCHED;
;             PG8_LDB(B0, 1, 0); PG8_LDB(B1, 1, 1); PG8_SCHED; PG8_LDA(At, 1, 0); PG8_STAGEA(PG8_SA(0, 1), a2 + hstep, voffA);
;             PG8_WAIT_V(8); PG8_WAIT_L(0); PG8_BAR; PG8_MMA(0, 0, At, B0); PG8_MMA(0, 1, At, B1); PG8_BAR; PG8_SCHED;
	s_setprio 1
	s_waitcnt lgkmcnt(0)
	.p2align 3
	v_mfma_f32_16x16x32_bf16 v[62:65], v[152:155], v[184:187], v[62:65]
	v_mfma_f32_16x16x32_bf16 v[58:61], v[160:163], v[184:187], v[58:61]
	v_mfma_f32_16x16x32_bf16 v[54:57], v[152:155], v[192:195], v[54:57]
	v_mfma_f32_16x16x32_bf16 v[46:49], v[160:163], v[192:195], v[46:49]
	v_mfma_f32_16x16x32_bf16 v[38:41], v[152:155], v[200:203], v[38:41]
	v_mfma_f32_16x16x32_bf16 v[30:33], v[160:163], v[200:203], v[30:33]
	v_mfma_f32_16x16x32_bf16 v[22:25], v[152:155], v[208:211], v[22:25]
	v_mfma_f32_16x16x32_bf16 v[14:17], v[160:163], v[208:211], v[14:17]
	v_mfma_f32_16x16x32_bf16 v[62:65], v[156:159], v[188:191], v[62:65]
	v_mfma_f32_16x16x32_bf16 v[58:61], v[164:167], v[188:191], v[58:61]
	v_mfma_f32_16x16x32_bf16 v[54:57], v[156:159], v[196:199], v[54:57]
	v_mfma_f32_16x16x32_bf16 v[46:49], v[164:167], v[196:199], v[46:49]
	v_mfma_f32_16x16x32_bf16 v[38:41], v[156:159], v[204:207], v[38:41]
	v_mfma_f32_16x16x32_bf16 v[30:33], v[164:167], v[204:207], v[30:33]
	v_mfma_f32_16x16x32_bf16 v[22:25], v[156:159], v[212:215], v[22:25]
	v_mfma_f32_16x16x32_bf16 v[14:17], v[164:167], v[212:215], v[14:17]
	s_setprio 0
	s_setprio 1
	.p2align 3
	v_mfma_f32_16x16x32_bf16 v[50:53], v[168:171], v[184:187], v[50:53]
	v_mfma_f32_16x16x32_bf16 v[42:45], v[176:179], v[184:187], v[42:45]
	v_mfma_f32_16x16x32_bf16 v[34:37], v[168:171], v[192:195], v[34:37]
	v_mfma_f32_16x16x32_bf16 v[26:29], v[176:179], v[192:195], v[26:29]
	v_mfma_f32_16x16x32_bf16 v[18:21], v[168:171], v[200:203], v[18:21]
	v_mfma_f32_16x16x32_bf16 v[10:13], v[176:179], v[200:203], v[10:13]
	v_mfma_f32_16x16x32_bf16 v[6:9], v[168:171], v[208:211], v[6:9]
	v_mfma_f32_16x16x32_bf16 v[2:5], v[176:179], v[208:211], v[2:5]
	v_mfma_f32_16x16x32_bf16 v[50:53], v[172:175], v[188:191], v[50:53]
	v_mfma_f32_16x16x32_bf16 v[42:45], v[180:183], v[188:191], v[42:45]
	v_mfma_f32_16x16x32_bf16 v[34:37], v[172:175], v[196:199], v[34:37]
	v_mfma_f32_16x16x32_bf16 v[26:29], v[180:183], v[196:199], v[26:29]
	v_mfma_f32_16x16x32_bf16 v[18:21], v[172:175], v[204:207], v[18:21]
	v_mfma_f32_16x16x32_bf16 v[10:13], v[180:183], v[204:207], v[10:13]
	v_mfma_f32_16x16x32_bf16 v[6:9], v[172:175], v[212:215], v[6:9]
	v_mfma_f32_16x16x32_bf16 v[2:5], v[180:183], v[212:215], v[2:5]
	s_setprio 0
	s_barrier
	s_add_i32 s24, 0, 0x18000
	v_add_u32_e32 v151, s24, v146
	s_add_i32 s25, 0, 0x1c000
	ds_read_b128 v[152:155], v151
	ds_read_b128 v[156:159], v151 offset:1024
	ds_read_b128 v[160:163], v151 offset:2048
	ds_read_b128 v[164:167], v151 offset:3072
	v_add_u32_e32 v151, s25, v146
	ds_read_b128 v[168:171], v151
	ds_read_b128 v[172:175], v151 offset:1024
	ds_read_b128 v[176:179], v151 offset:2048
	ds_read_b128 v[180:183], v151 offset:3072
	s_add_u32 s72, s72, 0x80000
	s_addc_u32 s73, s73, 0
	s_mov_b32 m0, s76
	v_lshl_add_u64 v[224:225], s[72:73], 0, v[136:137]
	ds_read_b128 v[184:187], v150 offset:32768
	ds_read_b128 v[188:191], v150 offset:33792
	ds_read_b128 v[192:195], v150 offset:34816
	ds_read_b128 v[196:199], v150 offset:35840
	ds_read_b128 v[200:203], v150 offset:36864
	ds_read_b128 v[204:207], v150 offset:37888
	ds_read_b128 v[208:211], v150 offset:38912
	ds_read_b128 v[212:215], v150 offset:39936
	global_load_lds_dwordx4 v[224:225], off
	v_lshl_add_u64 v[224:225], s[72:73], 0, v[132:133]
	s_mov_b32 m0, s77
	s_nop 0
	global_load_lds_dwordx4 v[224:225], off
	s_waitcnt vmcnt(8)
	s_waitcnt lgkmcnt(0)
	s_barrier
	s_setprio 1
	s_waitcnt lgkmcnt(0)
	.p2align 3
	v_mfma_f32_16x16x32_bf16 v[126:129], v[152:155], v[184:187], v[126:129]
	v_mfma_f32_16x16x32_bf16 v[122:125], v[160:163], v[184:187], v[122:125]
	v_mfma_f32_16x16x32_bf16 v[118:121], v[152:155], v[192:195], v[118:121]
	v_mfma_f32_16x16x32_bf16 v[110:113], v[160:163], v[192:195], v[110:113]
	v_mfma_f32_16x16x32_bf16 v[102:105], v[152:155], v[200:203], v[102:105]
	v_mfma_f32_16x16x32_bf16 v[94:97], v[160:163], v[200:203], v[94:97]
	v_mfma_f32_16x16x32_bf16 v[86:89], v[152:155], v[208:211], v[86:89]
	v_mfma_f32_16x16x32_bf16 v[78:81], v[160:163], v[208:211], v[78:81]
	v_mfma_f32_16x16x32_bf16 v[126:129], v[156:159], v[188:191], v[126:129]
	v_mfma_f32_16x16x32_bf16 v[122:125], v[164:167], v[188:191], v[122:125]
	v_mfma_f32_16x16x32_bf16 v[118:121], v[156:159], v[196:199], v[118:121]
	v_mfma_f32_16x16x32_bf16 v[110:113], v[164:167], v[196:199], v[110:113]
	v_mfma_f32_16x16x32_bf16 v[102:105], v[156:159], v[204:207], v[102:105]
	v_mfma_f32_16x16x32_bf16 v[94:97], v[164:167], v[204:207], v[94:97]
	v_mfma_f32_16x16x32_bf16 v[86:89], v[156:159], v[212:215], v[86:89]
	v_mfma_f32_16x16x32_bf16 v[78:81], v[164:167], v[212:215], v[78:81]
	s_setprio 0
	s_setprio 1
	.p2align 3
	v_mfma_f32_16x16x32_bf16 v[114:117], v[168:171], v[184:187], v[114:117]
	v_mfma_f32_16x16x32_bf16 v[106:109], v[176:179], v[184:187], v[106:109]
	v_mfma_f32_16x16x32_bf16 v[98:101], v[168:171], v[192:195], v[98:101]
	v_mfma_f32_16x16x32_bf16 v[90:93], v[176:179], v[192:195], v[90:93]
	v_mfma_f32_16x16x32_bf16 v[82:85], v[168:171], v[200:203], v[82:85]
	v_mfma_f32_16x16x32_bf16 v[74:77], v[176:179], v[200:203], v[74:77]
	v_mfma_f32_16x16x32_bf16 v[70:73], v[168:171], v[208:211], v[70:73]
	v_mfma_f32_16x16x32_bf16 v[66:69], v[176:179], v[208:211], v[66:69]
	v_mfma_f32_16x16x32_bf16 v[114:117], v[172:175], v[188:191], v[114:117]
	v_mfma_f32_16x16x32_bf16 v[106:109], v[180:183], v[188:191], v[106:109]
	v_mfma_f32_16x16x32_bf16 v[98:101], v[172:175], v[196:199], v[98:101]
	v_mfma_f32_16x16x32_bf16 v[90:93], v[180:183], v[196:199], v[90:93]
	v_mfma_f32_16x16x32_bf16 v[82:85], v[172:175], v[204:207], v[82:85]
	v_mfma_f32_16x16x32_bf16 v[74:77], v[180:183], v[204:207], v[74:77]
	v_mfma_f32_16x16x32_bf16 v[70:73], v[172:175], v[212:215], v[70:73]
	v_mfma_f32_16x16x32_bf16 v[66:69], v[180:183], v[212:215], v[66:69]
	s_setprio 0
	s_barrier
; #define PG8_STAGEA(bufoff, gbase, voff) PG8_STAGE_X(bufoff, gbase, voff, PG8_AUX_A)
; #define PG8_STAGEB(bufoff, gbase, voff) PG8_STAGE_X(bufoff, gbase, voff, PG8_AUX_B)
; #define PG8_LDA(dst, b, h) do { _Pragma("unroll") for (int m = 0; m < 4; ++m) _Pragma("unroll") for (int k = 0; k < 2; ++k) dst[m][k] = *(const PG8_LAS bf16x8*)(lds + PG8_SA(b, h) + aoff + m * 2048 + k * 1024); } while (0)
; #define PG8_MMA(ai, bj, At, Bt) do { __builtin_amdgcn_s_setprio(1); _Pragma("unroll") for (int m = 0; m < 4; ++m) _Pragma("unroll") for (int n = 0; n < 2; ++n) _Pragma("unroll") for (int k = 0; k < 2; ++k) \
;         acc[ai][bj][m][n] = __builtin_amdgcn_mfma_f32_16x16x32_bf16(Bt[n][k], At[m][k], acc[ai][bj][m][n], 0, 0, 0); __builtin_amdgcn_s_setprio(0); } while (0)
; #define PG8_WAIT_V(n) asm volatile("s_waitcnt vmcnt(" #n ")" ::: "memory")
; #define PG8_WAIT_L(n) asm volatile("s_waitcnt lgkmcnt(" #n ")" ::: "memory")
; #define PG8_BAR __builtin_amdgcn_s_barrier()
; #define PG8_SCHED __builtin_amdgcn_sched_barrier(0)
; template <class Epi, class Sched, bool ALIGN_EPI = false, bool SP2 = false>
; __device__ __forceinline__ void gemm_phase(PG8_LAS unsigned char* lds, const Gemm g, const Sched& S, const Epi& E) {
;     ...
;             PG8_LDA(At, 1, 1); PG8_STAGEB(PG8_SB(1, 0), b3, voffB); PG8_STAGEB(PG8_SB(1, 1), b3 + hstep, voffB); PG8_STAGEA(PG8_SA(1, 0), a3, voffA);
;             PG8_WAIT_V(8); PG8_WAIT_L(0); PG8_BAR; PG8_MMA(1, 0, At, B0); PG8_MMA(1, 1, At, B1); PG8_BAR; PG8_SCHED;
;     ...
;         if constexpr (ALIGN_EPI) { if (wr == 0) PG8_BAR; }
	s_add_i32 s24, s24, s23
	v_lshl_add_u64 v[216:217], v[216:217], 0, s[36:37]
	s_mov_b32 m0, s24
	ds_read_b128 v[184:187], v150 offset:49152
	ds_read_b128 v[188:191], v150 offset:50176
	ds_read_b128 v[192:195], v150 offset:51200
	ds_read_b128 v[196:199], v150 offset:52224
	ds_read_b128 v[200:203], v150 offset:53248
	ds_read_b128 v[204:207], v150 offset:54272
	ds_read_b128 v[208:211], v150 offset:55296
	ds_read_b128 v[212:215], v150 offset:56320
	global_load_lds_dwordx4 v[216:217], off
	s_add_i32 m0, s24, 0x2000
	s_add_u32 s70, s70, 0x80080
	v_lshl_add_u64 v[216:217], v[218:219], 0, s[36:37]
	s_addc_u32 s71, s71, 0
	s_add_i32 s24, s25, s23
	global_load_lds_dwordx4 v[216:217], off
	v_lshl_add_u64 v[216:217], s[70:71], 0, v[134:135]
	s_mov_b32 m0, s24
	s_nop 0
	global_load_lds_dwordx4 v[216:217], off
	v_lshl_add_u64 v[216:217], s[70:71], 0, v[130:131]
	s_add_i32 m0, s24, 0x2000
	s_nop 0
	global_load_lds_dwordx4 v[216:217], off
	v_lshl_add_u64 v[216:217], v[220:221], 0, s[36:37]
	s_mov_b32 m0, s79
	s_nop 0
	global_load_lds_dwordx4 v[216:217], off
	v_lshl_add_u64 v[216:217], v[222:223], 0, s[36:37]
	s_mov_b32 m0, s80
	s_nop 0
	global_load_lds_dwordx4 v[216:217], off
	s_waitcnt vmcnt(8)
	s_waitcnt lgkmcnt(0)
	s_barrier
	s_setprio 1
	s_waitcnt lgkmcnt(0)
	.p2align 3
	v_mfma_f32_16x16x32_bf16 v[62:65], v[152:155], v[184:187], v[62:65]
	v_mfma_f32_16x16x32_bf16 v[58:61], v[160:163], v[184:187], v[58:61]
	v_mfma_f32_16x16x32_bf16 v[54:57], v[152:155], v[192:195], v[54:57]
	v_mfma_f32_16x16x32_bf16 v[46:49], v[160:163], v[192:195], v[46:49]
	v_mfma_f32_16x16x32_bf16 v[38:41], v[152:155], v[200:203], v[38:41]
	v_mfma_f32_16x16x32_bf16 v[30:33], v[160:163], v[200:203], v[30:33]
	v_mfma_f32_16x16x32_bf16 v[22:25], v[152:155], v[208:211], v[22:25]
	v_mfma_f32_16x16x32_bf16 v[14:17], v[160:163], v[208:211], v[14:17]
	v_mfma_f32_16x16x32_bf16 v[62:65], v[156:159], v[188:191], v[62:65]
	v_mfma_f32_16x16x32_bf16 v[58:61], v[164:167], v[188:191], v[58:61]
	v_mfma_f32_16x16x32_bf16 v[54:57], v[156:159], v[196:199], v[54:57]
	v_mfma_f32_16x16x32_bf16 v[46:49], v[164:167], v[196:199], v[46:49]
	v_mfma_f32_16x16x32_bf16 v[38:41], v[156:159], v[204:207], v[38:41]
	v_mfma_f32_16x16x32_bf16 v[30:33], v[164:167], v[204:207], v[30:33]
	v_mfma_f32_16x16x32_bf16 v[22:25], v[156:159], v[212:215], v[22:25]
	v_mfma_f32_16x16x32_bf16 v[14:17], v[164:167], v[212:215], v[14:17]
	s_setprio 0
	s_setprio 1
	.p2align 3
	v_mfma_f32_16x16x32_bf16 v[50:53], v[168:171], v[184:187], v[50:53]
	v_mfma_f32_16x16x32_bf16 v[42:45], v[176:179], v[184:187], v[42:45]
	v_mfma_f32_16x16x32_bf16 v[34:37], v[168:171], v[192:195], v[34:37]
	v_mfma_f32_16x16x32_bf16 v[26:29], v[176:179], v[192:195], v[26:29]
	v_mfma_f32_16x16x32_bf16 v[18:21], v[168:171], v[200:203], v[18:21]
	v_mfma_f32_16x16x32_bf16 v[10:13], v[176:179], v[200:203], v[10:13]
	v_mfma_f32_16x16x32_bf16 v[6:9], v[168:171], v[208:211], v[6:9]
	v_mfma_f32_16x16x32_bf16 v[2:5], v[176:179], v[208:211], v[2:5]
	v_mfma_f32_16x16x32_bf16 v[50:53], v[172:175], v[188:191], v[50:53]
	v_mfma_f32_16x16x32_bf16 v[42:45], v[180:183], v[188:191], v[42:45]
	v_mfma_f32_16x16x32_bf16 v[34:37], v[172:175], v[196:199], v[34:37]
	v_mfma_f32_16x16x32_bf16 v[26:29], v[180:183], v[196:199], v[26:29]
	v_mfma_f32_16x16x32_bf16 v[18:21], v[172:175], v[204:207], v[18:21]
	v_mfma_f32_16x16x32_bf16 v[10:13], v[180:183], v[204:207], v[10:13]
	v_mfma_f32_16x16x32_bf16 v[6:9], v[172:175], v[212:215], v[6:9]
	v_mfma_f32_16x16x32_bf16 v[2:5], v[180:183], v[212:215], v[2:5]
	s_setprio 0
	s_barrier
	s_add_u32 s68, s68, 0x100
	s_addc_u32 s69, s69, 0
	s_mov_b32 s70, s91
	s_cbranch_vccz .LBB0_766
	s_and_b64 vcc, exec, s[46:47]
	s_cbranch_vccz .LBB0_769
	s_barrier

; #define PG8_STAGEA(bufoff, gbase, voff) PG8_STAGE_X(bufoff, gbase, voff, PG8_AUX_A)
; #define PG8_STAGEB(bufoff, gbase, voff) PG8_STAGE_X(bufoff, gbase, voff, PG8_AUX_B)
; #define PG8_LDA(dst, b, h) do { _Pragma("unroll") for (int m = 0; m < 4; ++m) _Pragma("unroll") for (int k = 0; k < 2; ++k) dst[m][k] = *(const PG8_LAS bf16x8*)(lds + PG8_SA(b, h) + aoff + m * 2048 + k * 1024); } while (0)
; #define PG8_LDB(dst, b, h) do { _Pragma("unroll") for (int n = 0; n < 2; ++n) _Pragma("unroll") for (int k = 0; k < 2; ++k) dst[n][k] = *(const PG8_LAS bf16x8*)(lds + PG8_SB(b, h) + boff + n * 2048 + k * 1024); } while (0)
; #define PG8_WAIT_V(n) asm volatile("s_waitcnt vmcnt(" #n ")" ::: "memory")
; #define PG8_WAIT_L(n) asm volatile("s_waitcnt lgkmcnt(" #n ")" ::: "memory")
; template <class Epi, class Sched, bool ALIGN_EPI = false, bool SP2 = false>
; __device__ __forceinline__ void gemm_phase(PG8_LAS unsigned char* lds, const Gemm g, const Sched& S, const Epi& E) {
;     ...
;             const bool last = (t == nt - 2);
;             if constexpr (HasMid<Epi>::value) { if (t == ns) E.mid(acc, cur, wr, wc, fr, fq); }
;             const char* sA1 = (t + 1 >= ns) ? cA2 : cA; const char* sA2 = (t + 2 >= ns) ? cA2 : cA; const char* sB2 = (t + 2 >= ns) ? cB2 : cB;
;             const char* a1 = sA1 + (size_t)(t + 1) * kstep;
;             const char* a2 = last ? nA : sA2 + (size_t)(t + 2) * kstep; const char* b2 = last ? nB : sB2 + (size_t)(t + 2) * kstep;
;             const char* a3 = a2 + kstep; const char* b3 = b2 + kstep;
;             if (last && has_next) S.a_ready(nxt);
;             if constexpr (SP2) {
;             PG8_LDB(B0, 0, 0); PG8_LDB(B1, 0, 1); PG8_SCHED; PG8_LDA(At, 0, 0); PG8_STAGEA(PG8_SA(1, 1), a1 + hstep, voffA);
;             PG8_WAIT_V(8); PG8_WAIT_L(0); PG8_BAR; PG8_MMA(0, 0, At, B0); PG8_MMA(0, 1, At, B1); PG8_BAR; PG8_SCHED;
;             PG8_LDA(At, 0, 1); PG8_STAGEB(PG8_SB(0, 0), b2, voffB); PG8_STAGEB(PG8_SB(0, 1), b2 + hstep, voffB); PG8_STAGEA(PG8_SA(0, 0), a2, voffA);
;             PG8_WAIT_V(8); PG8_WAIT_L(0); PG8_BAR; PG8_MMA(1, 0, At, B0); PG8_MMA(1, 1, At, B1); PG8_BAR; PG8_SCHED;
;             PG8_LDB(B0, 1, 0); PG8_LDB(B1, 1, 1); PG8_SCHED; PG8_LDA(At, 1, 0); PG8_STAGEA(PG8_SA(0, 1), a2 + hstep, voffA);
;             PG8_WAIT_V(8); PG8_WAIT_L(0); PG8_BAR; PG8_MMA(0, 0, At, B0); PG8_MMA(0, 1, At, B1); PG8_BAR; PG8_SCHED;
.LBB0_920:
	s_add_i32 s87, s66, 2
	s_cmp_lt_u32 s87, 6
	s_cselect_b32 s29, s62, s40
	s_cselect_b32 s24, s61, s37
	s_cselect_b32 s25, s60, s36
	s_cselect_b32 s28, s63, s41
	s_add_u32 s29, s29, s64
	s_addc_u32 s28, s28, s65
	s_add_u32 s29, s29, 0xfffe0080
	s_addc_u32 s28, s28, -1
	s_add_u32 s25, s25, s64
	s_addc_u32 s24, s24, s65
	s_add_u32 s25, s25, 0xfffe0080
	s_addc_u32 s24, s24, -1
	s_cmp_eq_u32 s66, 4
	s_cselect_b32 s73, s51, s28
	s_cselect_b32 s72, s57, s29
	s_cselect_b32 s75, s49, s24
	s_cselect_b32 s74, s86, s25
	s_add_i32 s25, s84, s23
	s_add_i32 m0, s26, 0xc000
	s_add_i32 s24, s26, 0xe000
	s_add_i32 s28, s25, 0x2000
	s_add_u32 s76, s74, 0x20000
	ds_read_b128 v[82:85], v164
	ds_read_b128 v[90:93], v164 offset:1024
	ds_read_b128 v[94:97], v164 offset:2048
	ds_read_b128 v[158:161], v164 offset:3072
	ds_read_b128 v[168:171], v165
	ds_read_b128 v[172:175], v165 offset:1024
	ds_read_b128 v[176:179], v165 offset:2048
	ds_read_b128 v[180:183], v165 offset:3072
	s_addc_u32 s77, s75, 0
	s_add_i32 s29, s85, s23
	s_add_i32 s92, s29, 0x2000
	s_add_i32 s93, 0, 0x18000
	s_add_i32 s94, 0, 0x1c000
	s_add_u32 s70, s72, 0x20000
	s_addc_u32 s71, s73, 0
	s_add_i32 s90, s93, s23
	s_add_i32 s88, s90, 0x2000
	s_add_u32 s68, s74, 0x20080
	s_addc_u32 s69, s75, 0
	s_add_i32 s89, s94, s23
	s_add_i32 s91, s89, 0x2000
	s_add_u32 s66, s64, 0x100
	s_addc_u32 s67, s65, 0
	s_cmp_gt_u32 s87, 5
	v_lshl_add_u64 v[216:217], v[70:71], 0, s[64:65]
	ds_read_b128 v[184:187], v166
	ds_read_b128 v[188:191], v166 offset:1024
	ds_read_b128 v[192:195], v166 offset:2048
	ds_read_b128 v[196:199], v166 offset:3072
	ds_read_b128 v[200:203], v166 offset:4096
	ds_read_b128 v[204:207], v166 offset:5120
	ds_read_b128 v[208:211], v166 offset:6144
	ds_read_b128 v[212:215], v166 offset:7168
	global_load_lds_dwordx4 v[216:217], off
	v_lshl_add_u64 v[216:217], v[72:73], 0, s[64:65]
	s_mov_b32 m0, s24
	s_nop 0
	global_load_lds_dwordx4 v[216:217], off
	s_waitcnt vmcnt(8)
	s_waitcnt lgkmcnt(0)
	s_barrier
	s_setprio 1
	s_waitcnt lgkmcnt(0)
	.p2align 3
	v_mfma_f32_16x16x32_bf16 v[142:145], v[82:85], v[184:187], v[142:145]
	v_mfma_f32_16x16x32_bf16 v[138:141], v[94:97], v[184:187], v[138:141]
	v_mfma_f32_16x16x32_bf16 v[126:129], v[82:85], v[192:195], v[126:129]
	v_mfma_f32_16x16x32_bf16 v[122:125], v[94:97], v[192:195], v[122:125]
	v_mfma_f32_16x16x32_bf16 v[110:113], v[82:85], v[200:203], v[110:113]
	v_mfma_f32_16x16x32_bf16 v[106:109], v[94:97], v[200:203], v[106:109]
	v_mfma_f32_16x16x32_bf16 v[86:89], v[82:85], v[208:211], v[86:89]
	v_mfma_f32_16x16x32_bf16 v[78:81], v[94:97], v[208:211], v[78:81]
	v_mfma_f32_16x16x32_bf16 v[142:145], v[90:93], v[188:191], v[142:145]
	v_mfma_f32_16x16x32_bf16 v[138:141], v[158:161], v[188:191], v[138:141]
	v_mfma_f32_16x16x32_bf16 v[126:129], v[90:93], v[196:199], v[126:129]
	v_mfma_f32_16x16x32_bf16 v[122:125], v[158:161], v[196:199], v[122:125]
	v_mfma_f32_16x16x32_bf16 v[110:113], v[90:93], v[204:207], v[110:113]
	v_mfma_f32_16x16x32_bf16 v[106:109], v[158:161], v[204:207], v[106:109]
	v_mfma_f32_16x16x32_bf16 v[86:89], v[90:93], v[212:215], v[86:89]
	v_mfma_f32_16x16x32_bf16 v[78:81], v[158:161], v[212:215], v[78:81]
	s_setprio 0
	s_setprio 1
	.p2align 3
	v_mfma_f32_16x16x32_bf16 v[134:137], v[168:171], v[184:187], v[134:137]
	v_mfma_f32_16x16x32_bf16 v[130:133], v[176:179], v[184:187], v[130:133]
	v_mfma_f32_16x16x32_bf16 v[118:121], v[168:171], v[192:195], v[118:121]
	v_mfma_f32_16x16x32_bf16 v[114:117], v[176:179], v[192:195], v[114:117]
	v_mfma_f32_16x16x32_bf16 v[102:105], v[168:171], v[200:203], v[102:105]
	v_mfma_f32_16x16x32_bf16 v[98:101], v[176:179], v[200:203], v[98:101]
	v_mfma_f32_16x16x32_bf16 v[74:77], v[168:171], v[208:211], v[74:77]
	v_mfma_f32_16x16x32_bf16 v[66:69], v[176:179], v[208:211], v[66:69]
	v_mfma_f32_16x16x32_bf16 v[134:137], v[172:175], v[188:191], v[134:137]
	v_mfma_f32_16x16x32_bf16 v[130:133], v[180:183], v[188:191], v[130:133]
	v_mfma_f32_16x16x32_bf16 v[118:121], v[172:175], v[196:199], v[118:121]
	v_mfma_f32_16x16x32_bf16 v[114:117], v[180:183], v[196:199], v[114:117]
	v_mfma_f32_16x16x32_bf16 v[102:105], v[172:175], v[204:207], v[102:105]
	v_mfma_f32_16x16x32_bf16 v[98:101], v[180:183], v[204:207], v[98:101]
	v_mfma_f32_16x16x32_bf16 v[74:77], v[172:175], v[212:215], v[74:77]
	v_mfma_f32_16x16x32_bf16 v[66:69], v[180:183], v[212:215], v[66:69]
	s_setprio 0
	s_barrier
	s_mov_b32 m0, s25
	v_lshl_add_u64 v[216:217], s[74:75], 0, v[146:147]
	ds_read_b128 v[184:187], v166 offset:16384
	ds_read_b128 v[188:191], v166 offset:17408
	ds_read_b128 v[192:195], v166 offset:18432
	ds_read_b128 v[196:199], v166 offset:19456
	ds_read_b128 v[200:203], v166 offset:20480
	ds_read_b128 v[204:207], v166 offset:21504
	ds_read_b128 v[208:211], v166 offset:22528
	ds_read_b128 v[212:215], v166 offset:23552
	global_load_lds_dwordx4 v[216:217], off
	v_lshl_add_u64 v[218:219], s[74:75], 0, v[148:149]
	s_mov_b32 m0, s28
	v_lshl_add_u64 v[220:221], s[76:77], 0, v[146:147]
	global_load_lds_dwordx4 v[218:219], off
	s_mov_b32 m0, s29
	v_lshl_add_u64 v[222:223], s[72:73], 0, v[148:149]
	global_load_lds_dwordx4 v[220:221], off
	v_lshl_add_u64 v[220:221], s[76:77], 0, v[148:149]
	s_mov_b32 m0, s92
	s_nop 0
	global_load_lds_dwordx4 v[220:221], off
	v_lshl_add_u64 v[220:221], s[72:73], 0, v[146:147]
	s_mov_b32 m0, s26
	s_nop 0
	global_load_lds_dwordx4 v[220:221], off
	s_mov_b32 m0, s27
	s_nop 0
	global_load_lds_dwordx4 v[222:223], off
	s_waitcnt vmcnt(8)
	s_waitcnt lgkmcnt(0)
	s_barrier
; #define PG8_STAGEA(bufoff, gbase, voff) PG8_STAGE_X(bufoff, gbase, voff, PG8_AUX_A)
; #define PG8_LDA(dst, b, h) do { _Pragma("unroll") for (int m = 0; m < 4; ++m) _Pragma("unroll") for (int k = 0; k < 2; ++k) dst[m][k] = *(const PG8_LAS bf16x8*)(lds + PG8_SA(b, h) + aoff + m * 2048 + k * 1024); } while (0)
; #define PG8_LDB(dst, b, h) do { _Pragma("unroll") for (int n = 0; n < 2; ++n) _Pragma("unroll") for (int k = 0; k < 2; ++k) dst[n][k] = *(const PG8_LAS bf16x8*)(lds + PG8_SB(b, h) + boff + n * 2048 + k * 1024); } while (0)
; #define PG8_MMA(ai, bj, At, Bt) do { __builtin_amdgcn_s_setprio(1); _Pragma("unroll") for (int m = 0; m < 4; ++m) _Pragma("unroll") for (int n = 0; n < 2; ++n) _Pragma("unroll") for (int k = 0; k < 2; ++k) \
;         acc[ai][bj][m][n] = __builtin_amdgcn_mfma_f32_16x16x32_bf16(Bt[n][k], At[m][k], acc[ai][bj][m][n], 0, 0, 0); __builtin_amdgcn_s_setprio(0); } while (0)
; #define PG8_WAIT_V(n) asm volatile("s_waitcnt vmcnt(" #n ")" ::: "memory")
; #define PG8_WAIT_L(n) asm volatile("s_waitcnt lgkmcnt(" #n ")" ::: "memory")
; #define PG8_BAR __builtin_amdgcn_s_barrier()
; #define PG8_SCHED __builtin_amdgcn_sched_barrier(0)
; template <class Epi, class Sched, bool ALIGN_EPI = false, bool SP2 = false>
; __device__ __forceinline__ void gemm_phase(PG8_LAS unsigned char* lds, const Gemm g, const Sched& S, const Epi& E) {
;     ...
;             PG8_WAIT_V(8); PG8_WAIT_L(0); PG8_BAR; PG8_MMA(1, 0, At, B0); PG8_MMA(1, 1, At, B1); PG8_BAR; PG8_SCHED;
;             PG8_LDB(B0, 1, 0); PG8_LDB(B1, 1, 1); PG8_SCHED; PG8_LDA(At, 1, 0); PG8_STAGEA(PG8_SA(0, 1), a2 + hstep, voffA);
;             PG8_WAIT_V(8); PG8_WAIT_L(0); PG8_BAR; PG8_MMA(0, 0, At, B0); PG8_MMA(0, 1, At, B1); PG8_BAR; PG8_SCHED;
	s_setprio 1
	s_waitcnt lgkmcnt(0)
	.p2align 3
	v_mfma_f32_16x16x32_bf16 v[62:65], v[82:85], v[184:187], v[62:65]
	v_mfma_f32_16x16x32_bf16 v[58:61], v[94:97], v[184:187], v[58:61]
	v_mfma_f32_16x16x32_bf16 v[46:49], v[82:85], v[192:195], v[46:49]
	v_mfma_f32_16x16x32_bf16 v[42:45], v[94:97], v[192:195], v[42:45]
	v_mfma_f32_16x16x32_bf16 v[30:33], v[82:85], v[200:203], v[30:33]
	v_mfma_f32_16x16x32_bf16 v[26:29], v[94:97], v[200:203], v[26:29]
	v_mfma_f32_16x16x32_bf16 v[14:17], v[82:85], v[208:211], v[14:17]
	v_mfma_f32_16x16x32_bf16 v[10:13], v[94:97], v[208:211], v[10:13]
	v_mfma_f32_16x16x32_bf16 v[62:65], v[90:93], v[188:191], v[62:65]
	v_mfma_f32_16x16x32_bf16 v[58:61], v[158:161], v[188:191], v[58:61]
	v_mfma_f32_16x16x32_bf16 v[46:49], v[90:93], v[196:199], v[46:49]
	v_mfma_f32_16x16x32_bf16 v[42:45], v[158:161], v[196:199], v[42:45]
	v_mfma_f32_16x16x32_bf16 v[30:33], v[90:93], v[204:207], v[30:33]
	v_mfma_f32_16x16x32_bf16 v[26:29], v[158:161], v[204:207], v[26:29]
	v_mfma_f32_16x16x32_bf16 v[14:17], v[90:93], v[212:215], v[14:17]
	v_mfma_f32_16x16x32_bf16 v[10:13], v[158:161], v[212:215], v[10:13]
	s_setprio 0
	s_setprio 1
	.p2align 3
	v_mfma_f32_16x16x32_bf16 v[54:57], v[168:171], v[184:187], v[54:57]
	v_mfma_f32_16x16x32_bf16 v[50:53], v[176:179], v[184:187], v[50:53]
	v_mfma_f32_16x16x32_bf16 v[38:41], v[168:171], v[192:195], v[38:41]
	v_mfma_f32_16x16x32_bf16 v[34:37], v[176:179], v[192:195], v[34:37]
	v_mfma_f32_16x16x32_bf16 v[22:25], v[168:171], v[200:203], v[22:25]
	v_mfma_f32_16x16x32_bf16 v[18:21], v[176:179], v[200:203], v[18:21]
	v_mfma_f32_16x16x32_bf16 v[6:9], v[168:171], v[208:211], v[6:9]
	v_mfma_f32_16x16x32_bf16 v[2:5], v[176:179], v[208:211], v[2:5]
	v_mfma_f32_16x16x32_bf16 v[54:57], v[172:175], v[188:191], v[54:57]
	v_mfma_f32_16x16x32_bf16 v[50:53], v[180:183], v[188:191], v[50:53]
	v_mfma_f32_16x16x32_bf16 v[38:41], v[172:175], v[196:199], v[38:41]
	v_mfma_f32_16x16x32_bf16 v[34:37], v[180:183], v[196:199], v[34:37]
	v_mfma_f32_16x16x32_bf16 v[22:25], v[172:175], v[204:207], v[22:25]
	v_mfma_f32_16x16x32_bf16 v[18:21], v[180:183], v[204:207], v[18:21]
	v_mfma_f32_16x16x32_bf16 v[6:9], v[172:175], v[212:215], v[6:9]
	v_mfma_f32_16x16x32_bf16 v[2:5], v[180:183], v[212:215], v[2:5]
	s_setprio 0
	s_barrier
	v_add_u32_e32 v158, s93, v162
	v_add_u32_e32 v180, s94, v162
	ds_read_b128 v[82:85], v158
	ds_read_b128 v[90:93], v158 offset:1024
	ds_read_b128 v[94:97], v158 offset:2048
	ds_read_b128 v[158:161], v158 offset:3072
	ds_read_b128 v[168:171], v180
	ds_read_b128 v[172:175], v180 offset:1024
	ds_read_b128 v[176:179], v180 offset:2048
	ds_read_b128 v[180:183], v180 offset:3072
	s_mov_b32 m0, s33
	v_lshl_add_u64 v[224:225], s[70:71], 0, v[146:147]
	ds_read_b128 v[184:187], v166 offset:32768
	ds_read_b128 v[188:191], v166 offset:33792
	ds_read_b128 v[192:195], v166 offset:34816
	ds_read_b128 v[196:199], v166 offset:35840
	ds_read_b128 v[200:203], v166 offset:36864
	ds_read_b128 v[204:207], v166 offset:37888
	ds_read_b128 v[208:211], v166 offset:38912
	ds_read_b128 v[212:215], v166 offset:39936
	global_load_lds_dwordx4 v[224:225], off
	v_lshl_add_u64 v[224:225], s[70:71], 0, v[148:149]
	s_mov_b32 m0, s59
	s_nop 0
	global_load_lds_dwordx4 v[224:225], off
	s_waitcnt vmcnt(8)
	s_waitcnt lgkmcnt(0)
	s_barrier
	s_setprio 1
	s_waitcnt lgkmcnt(0)
	.p2align 3
	v_mfma_f32_16x16x32_bf16 v[142:145], v[82:85], v[184:187], v[142:145]
	v_mfma_f32_16x16x32_bf16 v[138:141], v[94:97], v[184:187], v[138:141]
	v_mfma_f32_16x16x32_bf16 v[126:129], v[82:85], v[192:195], v[126:129]
	v_mfma_f32_16x16x32_bf16 v[122:125], v[94:97], v[192:195], v[122:125]
	v_mfma_f32_16x16x32_bf16 v[110:113], v[82:85], v[200:203], v[110:113]
	v_mfma_f32_16x16x32_bf16 v[106:109], v[94:97], v[200:203], v[106:109]
	v_mfma_f32_16x16x32_bf16 v[86:89], v[82:85], v[208:211], v[86:89]
	v_mfma_f32_16x16x32_bf16 v[78:81], v[94:97], v[208:211], v[78:81]
	v_mfma_f32_16x16x32_bf16 v[142:145], v[90:93], v[188:191], v[142:145]
	v_mfma_f32_16x16x32_bf16 v[138:141], v[158:161], v[188:191], v[138:141]
	v_mfma_f32_16x16x32_bf16 v[126:129], v[90:93], v[196:199], v[126:129]
	v_mfma_f32_16x16x32_bf16 v[122:125], v[158:161], v[196:199], v[122:125]
	v_mfma_f32_16x16x32_bf16 v[110:113], v[90:93], v[204:207], v[110:113]
	v_mfma_f32_16x16x32_bf16 v[106:109], v[158:161], v[204:207], v[106:109]
	v_mfma_f32_16x16x32_bf16 v[86:89], v[90:93], v[212:215], v[86:89]
	v_mfma_f32_16x16x32_bf16 v[78:81], v[158:161], v[212:215], v[78:81]
	s_setprio 0
	s_setprio 1
	.p2align 3
	v_mfma_f32_16x16x32_bf16 v[134:137], v[168:171], v[184:187], v[134:137]
	v_mfma_f32_16x16x32_bf16 v[130:133], v[176:179], v[184:187], v[130:133]
	v_mfma_f32_16x16x32_bf16 v[118:121], v[168:171], v[192:195], v[118:121]
	v_mfma_f32_16x16x32_bf16 v[114:117], v[176:179], v[192:195], v[114:117]
	v_mfma_f32_16x16x32_bf16 v[102:105], v[168:171], v[200:203], v[102:105]
	v_mfma_f32_16x16x32_bf16 v[98:101], v[176:179], v[200:203], v[98:101]
	v_mfma_f32_16x16x32_bf16 v[74:77], v[168:171], v[208:211], v[74:77]
	v_mfma_f32_16x16x32_bf16 v[66:69], v[176:179], v[208:211], v[66:69]
	v_mfma_f32_16x16x32_bf16 v[134:137], v[172:175], v[188:191], v[134:137]
	v_mfma_f32_16x16x32_bf16 v[130:133], v[180:183], v[188:191], v[130:133]
	v_mfma_f32_16x16x32_bf16 v[118:121], v[172:175], v[196:199], v[118:121]
	v_mfma_f32_16x16x32_bf16 v[114:117], v[180:183], v[196:199], v[114:117]
	v_mfma_f32_16x16x32_bf16 v[102:105], v[172:175], v[204:207], v[102:105]
	v_mfma_f32_16x16x32_bf16 v[98:101], v[180:183], v[204:207], v[98:101]
	v_mfma_f32_16x16x32_bf16 v[74:77], v[172:175], v[212:215], v[74:77]
	v_mfma_f32_16x16x32_bf16 v[66:69], v[180:183], v[212:215], v[66:69]
	s_setprio 0
	s_barrier
; #define PG8_STAGEA(bufoff, gbase, voff) PG8_STAGE_X(bufoff, gbase, voff, PG8_AUX_A)
; #define PG8_STAGEB(bufoff, gbase, voff) PG8_STAGE_X(bufoff, gbase, voff, PG8_AUX_B)
; #define PG8_LDA(dst, b, h) do { _Pragma("unroll") for (int m = 0; m < 4; ++m) _Pragma("unroll") for (int k = 0; k < 2; ++k) dst[m][k] = *(const PG8_LAS bf16x8*)(lds + PG8_SA(b, h) + aoff + m * 2048 + k * 1024); } while (0)
; #define PG8_MMA(ai, bj, At, Bt) do { __builtin_amdgcn_s_setprio(1); _Pragma("unroll") for (int m = 0; m < 4; ++m) _Pragma("unroll") for (int n = 0; n < 2; ++n) _Pragma("unroll") for (int k = 0; k < 2; ++k) \
;         acc[ai][bj][m][n] = __builtin_amdgcn_mfma_f32_16x16x32_bf16(Bt[n][k], At[m][k], acc[ai][bj][m][n], 0, 0, 0); __builtin_amdgcn_s_setprio(0); } while (0)
; #define PG8_WAIT_V(n) asm volatile("s_waitcnt vmcnt(" #n ")" ::: "memory")
; #define PG8_WAIT_L(n) asm volatile("s_waitcnt lgkmcnt(" #n ")" ::: "memory")
; #define PG8_BAR __builtin_amdgcn_s_barrier()
; #define PG8_SCHED __builtin_amdgcn_sched_barrier(0)
; template <class Epi, class Sched, bool ALIGN_EPI = false, bool SP2 = false>
; __device__ __forceinline__ void gemm_phase(PG8_LAS unsigned char* lds, const Gemm g, const Sched& S, const Epi& E) {
;     ...
;             PG8_LDA(At, 1, 1); PG8_STAGEB(PG8_SB(1, 0), b3, voffB); PG8_STAGEB(PG8_SB(1, 1), b3 + hstep, voffB); PG8_STAGEA(PG8_SA(1, 0), a3, voffA);
;             PG8_WAIT_V(8); PG8_WAIT_L(0); PG8_BAR; PG8_MMA(1, 0, At, B0); PG8_MMA(1, 1, At, B1); PG8_BAR; PG8_SCHED;
;     ...
;         if constexpr (ALIGN_EPI) { if (wr == 0) PG8_BAR; }
	s_mov_b32 m0, s90
	v_lshl_add_u64 v[216:217], v[216:217], 0, s[44:45]
	ds_read_b128 v[184:187], v166 offset:49152
	ds_read_b128 v[188:191], v166 offset:50176
	ds_read_b128 v[192:195], v166 offset:51200
	ds_read_b128 v[196:199], v166 offset:52224
	ds_read_b128 v[200:203], v166 offset:53248
	ds_read_b128 v[204:207], v166 offset:54272
	ds_read_b128 v[208:211], v166 offset:55296
	ds_read_b128 v[212:215], v166 offset:56320
	global_load_lds_dwordx4 v[216:217], off
	v_lshl_add_u64 v[216:217], v[218:219], 0, s[44:45]
	s_mov_b32 m0, s88
	s_nop 0
	global_load_lds_dwordx4 v[216:217], off
	v_lshl_add_u64 v[216:217], s[68:69], 0, v[146:147]
	s_mov_b32 m0, s89
	s_nop 0
	global_load_lds_dwordx4 v[216:217], off
	v_lshl_add_u64 v[216:217], s[68:69], 0, v[148:149]
	s_mov_b32 m0, s91
	s_nop 0
	global_load_lds_dwordx4 v[216:217], off
	v_lshl_add_u64 v[216:217], v[220:221], 0, s[44:45]
	s_mov_b32 m0, s79
	s_nop 0
	global_load_lds_dwordx4 v[216:217], off
	v_lshl_add_u64 v[216:217], v[222:223], 0, s[44:45]
	s_mov_b32 m0, s80
	s_nop 0
	global_load_lds_dwordx4 v[216:217], off
	s_waitcnt vmcnt(8)
	s_waitcnt lgkmcnt(0)
	s_barrier
	s_setprio 1
	s_waitcnt lgkmcnt(0)
	.p2align 3
	v_mfma_f32_16x16x32_bf16 v[62:65], v[82:85], v[184:187], v[62:65]
	v_mfma_f32_16x16x32_bf16 v[58:61], v[94:97], v[184:187], v[58:61]
	v_mfma_f32_16x16x32_bf16 v[46:49], v[82:85], v[192:195], v[46:49]
	v_mfma_f32_16x16x32_bf16 v[42:45], v[94:97], v[192:195], v[42:45]
	v_mfma_f32_16x16x32_bf16 v[30:33], v[82:85], v[200:203], v[30:33]
	v_mfma_f32_16x16x32_bf16 v[26:29], v[94:97], v[200:203], v[26:29]
	v_mfma_f32_16x16x32_bf16 v[14:17], v[82:85], v[208:211], v[14:17]
	v_mfma_f32_16x16x32_bf16 v[10:13], v[94:97], v[208:211], v[10:13]
	v_mfma_f32_16x16x32_bf16 v[62:65], v[90:93], v[188:191], v[62:65]
	v_mfma_f32_16x16x32_bf16 v[58:61], v[158:161], v[188:191], v[58:61]
	v_mfma_f32_16x16x32_bf16 v[46:49], v[90:93], v[196:199], v[46:49]
	v_mfma_f32_16x16x32_bf16 v[42:45], v[158:161], v[196:199], v[42:45]
	v_mfma_f32_16x16x32_bf16 v[30:33], v[90:93], v[204:207], v[30:33]
	v_mfma_f32_16x16x32_bf16 v[26:29], v[158:161], v[204:207], v[26:29]
	v_mfma_f32_16x16x32_bf16 v[14:17], v[90:93], v[212:215], v[14:17]
	v_mfma_f32_16x16x32_bf16 v[10:13], v[158:161], v[212:215], v[10:13]
	s_setprio 0
	s_setprio 1
	.p2align 3
	v_mfma_f32_16x16x32_bf16 v[54:57], v[168:171], v[184:187], v[54:57]
	v_mfma_f32_16x16x32_bf16 v[50:53], v[176:179], v[184:187], v[50:53]
	v_mfma_f32_16x16x32_bf16 v[38:41], v[168:171], v[192:195], v[38:41]
	v_mfma_f32_16x16x32_bf16 v[34:37], v[176:179], v[192:195], v[34:37]
	v_mfma_f32_16x16x32_bf16 v[22:25], v[168:171], v[200:203], v[22:25]
	v_mfma_f32_16x16x32_bf16 v[18:21], v[176:179], v[200:203], v[18:21]
	v_mfma_f32_16x16x32_bf16 v[6:9], v[168:171], v[208:211], v[6:9]
	v_mfma_f32_16x16x32_bf16 v[2:5], v[176:179], v[208:211], v[2:5]
	v_mfma_f32_16x16x32_bf16 v[54:57], v[172:175], v[188:191], v[54:57]
	v_mfma_f32_16x16x32_bf16 v[50:53], v[180:183], v[188:191], v[50:53]
	v_mfma_f32_16x16x32_bf16 v[38:41], v[172:175], v[196:199], v[38:41]
	v_mfma_f32_16x16x32_bf16 v[34:37], v[180:183], v[196:199], v[34:37]
	v_mfma_f32_16x16x32_bf16 v[22:25], v[172:175], v[204:207], v[22:25]
	v_mfma_f32_16x16x32_bf16 v[18:21], v[180:183], v[204:207], v[18:21]
	v_mfma_f32_16x16x32_bf16 v[6:9], v[172:175], v[212:215], v[6:9]
	v_mfma_f32_16x16x32_bf16 v[2:5], v[180:183], v[212:215], v[2:5]
	s_setprio 0
	s_barrier
	s_mov_b64 s[64:65], s[66:67]
	s_mov_b32 s66, s87
	s_cbranch_scc0 .LBB0_920
	s_and_b64 vcc, exec, s[46:47]
	s_cbranch_vccz .LBB0_923
	s_barrier

; #define PG8_STAGEA(bufoff, gbase, voff) PG8_STAGE_X(bufoff, gbase, voff, PG8_AUX_A)
; #define PG8_STAGEB(bufoff, gbase, voff) PG8_STAGE_X(bufoff, gbase, voff, PG8_AUX_B)
; #define PG8_LDA(dst, b, h) do { _Pragma("unroll") for (int m = 0; m < 4; ++m) _Pragma("unroll") for (int k = 0; k < 2; ++k) dst[m][k] = *(const PG8_LAS bf16x8*)(lds + PG8_SA(b, h) + aoff + m * 2048 + k * 1024); } while (0)
; #define PG8_LDB(dst, b, h) do { _Pragma("unroll") for (int n = 0; n < 2; ++n) _Pragma("unroll") for (int k = 0; k < 2; ++k) dst[n][k] = *(const PG8_LAS bf16x8*)(lds + PG8_SB(b, h) + boff + n * 2048 + k * 1024); } while (0)
; #define PG8_WAIT_V(n) asm volatile("s_waitcnt vmcnt(" #n ")" ::: "memory")
; #define PG8_WAIT_L(n) asm volatile("s_waitcnt lgkmcnt(" #n ")" ::: "memory")
; template <class Epi, class Sched, bool ALIGN_EPI = false, bool SP2 = false>
; __device__ __forceinline__ void gemm_phase(PG8_LAS unsigned char* lds, const Gemm g, const Sched& S, const Epi& E) {
;     ...
;             const bool last = (t == nt - 2);
;             if constexpr (HasMid<Epi>::value) { if (t == ns) E.mid(acc, cur, wr, wc, fr, fq); }
;             const char* sA1 = (t + 1 >= ns) ? cA2 : cA; const char* sA2 = (t + 2 >= ns) ? cA2 : cA; const char* sB2 = (t + 2 >= ns) ? cB2 : cB;
;             const char* a1 = sA1 + (size_t)(t + 1) * kstep;
;             const char* a2 = last ? nA : sA2 + (size_t)(t + 2) * kstep; const char* b2 = last ? nB : sB2 + (size_t)(t + 2) * kstep;
;             const char* a3 = a2 + kstep; const char* b3 = b2 + kstep;
;             if (last && has_next) S.a_ready(nxt);
;             if constexpr (SP2) {
;             PG8_LDB(B0, 0, 0); PG8_LDB(B1, 0, 1); PG8_SCHED; PG8_LDA(At, 0, 0); PG8_STAGEA(PG8_SA(1, 1), a1 + hstep, voffA);
;             PG8_WAIT_V(8); PG8_WAIT_L(0); PG8_BAR; PG8_MMA(0, 0, At, B0); PG8_MMA(0, 1, At, B1); PG8_BAR; PG8_SCHED;
;             PG8_LDA(At, 0, 1); PG8_STAGEB(PG8_SB(0, 0), b2, voffB); PG8_STAGEB(PG8_SB(0, 1), b2 + hstep, voffB); PG8_STAGEA(PG8_SA(0, 0), a2, voffA);
;             PG8_WAIT_V(8); PG8_WAIT_L(0); PG8_BAR; PG8_MMA(1, 0, At, B0); PG8_MMA(1, 1, At, B1); PG8_BAR; PG8_SCHED;
;             PG8_LDB(B0, 1, 0); PG8_LDB(B1, 1, 1); PG8_SCHED; PG8_LDA(At, 1, 0); PG8_STAGEA(PG8_SA(0, 1), a2 + hstep, voffA);
;             PG8_WAIT_V(8); PG8_WAIT_L(0); PG8_BAR; PG8_MMA(0, 0, At, B0); PG8_MMA(0, 1, At, B1); PG8_BAR; PG8_SCHED;
.LBB0_1007:
	s_add_i32 s76, s58, 2
	s_cmp_gt_u32 s76, 29
	s_cselect_b64 s[60:61], -1, 0
	s_and_b64 vcc, s[60:61], exec
	s_cselect_b32 s29, s34, s54
	ds_read_b128 v[158:161], v152
	ds_read_b128 v[162:165], v152 offset:1024
	ds_read_b128 v[166:169], v152 offset:2048
	ds_read_b128 v[170:173], v152 offset:3072
	ds_read_b128 v[174:177], v153
	ds_read_b128 v[178:181], v153 offset:1024
	ds_read_b128 v[182:185], v153 offset:2048
	ds_read_b128 v[186:189], v153 offset:3072
	s_cselect_b32 s24, s27, s53
	s_cselect_b32 s25, s26, s52
	s_cselect_b32 s28, s35, s55
	s_add_u32 s29, s29, s56
	s_addc_u32 s28, s28, s57
	s_add_u32 s29, s29, 0xfff80080
	s_addc_u32 s28, s28, -1
	s_add_u32 s25, s25, s56
	s_addc_u32 s24, s24, s57
	s_add_u32 s25, s25, 0xfff80080
	s_addc_u32 s24, s24, -1
	s_cmp_eq_u32 s58, 28
	s_cselect_b32 s58, s75, s25
	s_cselect_b32 s61, s47, s28
	s_cselect_b32 s60, s74, s29
	s_cselect_b32 s59, s45, s24
	v_lshl_add_u64 v[222:223], v[146:147], 0, s[56:57]
	s_add_i32 m0, s33, 0xc000
	ds_read_b128 v[190:193], v154
	ds_read_b128 v[194:197], v154 offset:1024
	ds_read_b128 v[198:201], v154 offset:2048
	ds_read_b128 v[202:205], v154 offset:3072
	ds_read_b128 v[206:209], v154 offset:4096
	ds_read_b128 v[210:213], v154 offset:5120
	ds_read_b128 v[214:217], v154 offset:6144
	ds_read_b128 v[218:221], v154 offset:7168
	global_load_lds_dwordx4 v[222:223], off
	v_lshl_add_u64 v[222:223], v[148:149], 0, s[56:57]
	s_add_i32 m0, s33, 0xe000
	s_nop 0
	global_load_lds_dwordx4 v[222:223], off
	s_waitcnt vmcnt(8)
	s_waitcnt lgkmcnt(0)
	s_barrier
	s_setprio 1
	s_waitcnt lgkmcnt(0)
	.p2align 3
	v_mfma_f32_16x16x32_bf16 v[118:121], v[158:161], v[190:193], v[118:121]
	v_mfma_f32_16x16x32_bf16 v[114:117], v[166:169], v[190:193], v[114:117]
	v_mfma_f32_16x16x32_bf16 v[102:105], v[158:161], v[198:201], v[102:105]
	v_mfma_f32_16x16x32_bf16 v[98:101], v[166:169], v[198:201], v[98:101]
	v_mfma_f32_16x16x32_bf16 v[86:89], v[158:161], v[206:209], v[86:89]
	v_mfma_f32_16x16x32_bf16 v[82:85], v[166:169], v[206:209], v[82:85]
	v_mfma_f32_16x16x32_bf16 v[70:73], v[158:161], v[214:217], v[70:73]
	v_mfma_f32_16x16x32_bf16 v[66:69], v[166:169], v[214:217], v[66:69]
	v_mfma_f32_16x16x32_bf16 v[118:121], v[162:165], v[194:197], v[118:121]
	v_mfma_f32_16x16x32_bf16 v[114:117], v[170:173], v[194:197], v[114:117]
	v_mfma_f32_16x16x32_bf16 v[102:105], v[162:165], v[202:205], v[102:105]
	v_mfma_f32_16x16x32_bf16 v[98:101], v[170:173], v[202:205], v[98:101]
	v_mfma_f32_16x16x32_bf16 v[86:89], v[162:165], v[210:213], v[86:89]
	v_mfma_f32_16x16x32_bf16 v[82:85], v[170:173], v[210:213], v[82:85]
	v_mfma_f32_16x16x32_bf16 v[70:73], v[162:165], v[218:221], v[70:73]
	v_mfma_f32_16x16x32_bf16 v[66:69], v[170:173], v[218:221], v[66:69]
	s_setprio 0
	s_setprio 1
	.p2align 3
	v_mfma_f32_16x16x32_bf16 v[126:129], v[174:177], v[190:193], v[126:129]
	v_mfma_f32_16x16x32_bf16 v[122:125], v[182:185], v[190:193], v[122:125]
	v_mfma_f32_16x16x32_bf16 v[110:113], v[174:177], v[198:201], v[110:113]
	v_mfma_f32_16x16x32_bf16 v[106:109], v[182:185], v[198:201], v[106:109]
	v_mfma_f32_16x16x32_bf16 v[94:97], v[174:177], v[206:209], v[94:97]
	v_mfma_f32_16x16x32_bf16 v[90:93], v[182:185], v[206:209], v[90:93]
	v_mfma_f32_16x16x32_bf16 v[78:81], v[174:177], v[214:217], v[78:81]
	v_mfma_f32_16x16x32_bf16 v[74:77], v[182:185], v[214:217], v[74:77]
	v_mfma_f32_16x16x32_bf16 v[126:129], v[178:181], v[194:197], v[126:129]
	v_mfma_f32_16x16x32_bf16 v[122:125], v[186:189], v[194:197], v[122:125]
	v_mfma_f32_16x16x32_bf16 v[110:113], v[178:181], v[202:205], v[110:113]
	v_mfma_f32_16x16x32_bf16 v[106:109], v[186:189], v[202:205], v[106:109]
	v_mfma_f32_16x16x32_bf16 v[94:97], v[178:181], v[210:213], v[94:97]
	v_mfma_f32_16x16x32_bf16 v[90:93], v[186:189], v[210:213], v[90:93]
	v_mfma_f32_16x16x32_bf16 v[78:81], v[178:181], v[218:221], v[78:81]
	v_mfma_f32_16x16x32_bf16 v[74:77], v[186:189], v[218:221], v[74:77]
	s_setprio 0
	s_barrier
	s_add_i32 s24, s70, s11
	v_lshl_add_u64 v[222:223], s[58:59], 0, v[134:135]
	s_mov_b32 m0, s24
	ds_read_b128 v[190:193], v154 offset:16384
	ds_read_b128 v[194:197], v154 offset:17408
	ds_read_b128 v[198:201], v154 offset:18432
	ds_read_b128 v[202:205], v154 offset:19456
	ds_read_b128 v[206:209], v154 offset:20480
	ds_read_b128 v[210:213], v154 offset:21504
	ds_read_b128 v[214:217], v154 offset:22528
	ds_read_b128 v[218:221], v154 offset:23552
	global_load_lds_dwordx4 v[222:223], off
	s_add_i32 m0, s24, 0x2000
	s_add_u32 s78, s58, 0x80000
	v_lshl_add_u64 v[224:225], s[58:59], 0, v[130:131]
	s_addc_u32 s79, s59, 0
	s_add_i32 s24, s71, s11
	global_load_lds_dwordx4 v[224:225], off
	v_lshl_add_u64 v[226:227], s[78:79], 0, v[134:135]
	s_mov_b32 m0, s24
	v_lshl_add_u64 v[228:229], s[60:61], 0, v[132:133]
	global_load_lds_dwordx4 v[226:227], off
	v_lshl_add_u64 v[226:227], s[78:79], 0, v[130:131]
	s_add_i32 m0, s24, 0x2000
	s_nop 0
	global_load_lds_dwordx4 v[226:227], off
	v_lshl_add_u64 v[226:227], s[60:61], 0, v[136:137]
	s_mov_b32 m0, s33
	s_nop 0
	global_load_lds_dwordx4 v[226:227], off
	s_mov_b32 m0, s62
	s_nop 0
	global_load_lds_dwordx4 v[228:229], off
	s_waitcnt vmcnt(8)
	s_waitcnt lgkmcnt(0)
	s_barrier
; #define PG8_STAGEA(bufoff, gbase, voff) PG8_STAGE_X(bufoff, gbase, voff, PG8_AUX_A)
; #define PG8_LDA(dst, b, h) do { _Pragma("unroll") for (int m = 0; m < 4; ++m) _Pragma("unroll") for (int k = 0; k < 2; ++k) dst[m][k] = *(const PG8_LAS bf16x8*)(lds + PG8_SA(b, h) + aoff + m * 2048 + k * 1024); } while (0)
; #define PG8_LDB(dst, b, h) do { _Pragma("unroll") for (int n = 0; n < 2; ++n) _Pragma("unroll") for (int k = 0; k < 2; ++k) dst[n][k] = *(const PG8_LAS bf16x8*)(lds + PG8_SB(b, h) + boff + n * 2048 + k * 1024); } while (0)
; #define PG8_MMA(ai, bj, At, Bt) do { __builtin_amdgcn_s_setprio(1); _Pragma("unroll") for (int m = 0; m < 4; ++m) _Pragma("unroll") for (int n = 0; n < 2; ++n) _Pragma("unroll") for (int k = 0; k < 2; ++k) \
;         acc[ai][bj][m][n] = __builtin_amdgcn_mfma_f32_16x16x32_bf16(Bt[n][k], At[m][k], acc[ai][bj][m][n], 0, 0, 0); __builtin_amdgcn_s_setprio(0); } while (0)
; #define PG8_WAIT_V(n) asm volatile("s_waitcnt vmcnt(" #n ")" ::: "memory")
; #define PG8_WAIT_L(n) asm volatile("s_waitcnt lgkmcnt(" #n ")" ::: "memory")
; #define PG8_BAR __builtin_amdgcn_s_barrier()
; #define PG8_SCHED __builtin_amdgcn_sched_barrier(0)
; template <class Epi, class Sched, bool ALIGN_EPI = false, bool SP2 = false>
; __device__ __forceinline__ void gemm_phase(PG8_LAS unsigned char* lds, const Gemm g, const Sched& S, const Epi& E) {
;     ...
;             PG8_WAIT_V(8); PG8_WAIT_L(0); PG8_BAR; PG8_MMA(1, 0, At, B0); PG8_MMA(1, 1, At, B1); PG8_BAR; PG8_SCHED;
;             PG8_LDB(B0, 1, 0); PG8_LDB(B1, 1, 1); PG8_SCHED; PG8_LDA(At, 1, 0); PG8_STAGEA(PG8_SA(0, 1), a2 + hstep, voffA);
;             PG8_WAIT_V(8); PG8_WAIT_L(0); PG8_BAR; PG8_MMA(0, 0, At, B0); PG8_MMA(0, 1, At, B1); PG8_BAR; PG8_SCHED;
	s_setprio 1
	s_waitcnt lgkmcnt(0)
	.p2align 3
	v_mfma_f32_16x16x32_bf16 v[54:57], v[158:161], v[190:193], v[54:57]
	v_mfma_f32_16x16x32_bf16 v[50:53], v[166:169], v[190:193], v[50:53]
	v_mfma_f32_16x16x32_bf16 v[38:41], v[158:161], v[198:201], v[38:41]
	v_mfma_f32_16x16x32_bf16 v[34:37], v[166:169], v[198:201], v[34:37]
	v_mfma_f32_16x16x32_bf16 v[22:25], v[158:161], v[206:209], v[22:25]
	v_mfma_f32_16x16x32_bf16 v[18:21], v[166:169], v[206:209], v[18:21]
	v_mfma_f32_16x16x32_bf16 v[6:9], v[158:161], v[214:217], v[6:9]
	v_mfma_f32_16x16x32_bf16 v[2:5], v[166:169], v[214:217], v[2:5]
	v_mfma_f32_16x16x32_bf16 v[54:57], v[162:165], v[194:197], v[54:57]
	v_mfma_f32_16x16x32_bf16 v[50:53], v[170:173], v[194:197], v[50:53]
	v_mfma_f32_16x16x32_bf16 v[38:41], v[162:165], v[202:205], v[38:41]
	v_mfma_f32_16x16x32_bf16 v[34:37], v[170:173], v[202:205], v[34:37]
	v_mfma_f32_16x16x32_bf16 v[22:25], v[162:165], v[210:213], v[22:25]
	v_mfma_f32_16x16x32_bf16 v[18:21], v[170:173], v[210:213], v[18:21]
	v_mfma_f32_16x16x32_bf16 v[6:9], v[162:165], v[218:221], v[6:9]
	v_mfma_f32_16x16x32_bf16 v[2:5], v[170:173], v[218:221], v[2:5]
	s_setprio 0
	s_setprio 1
	.p2align 3
	v_mfma_f32_16x16x32_bf16 v[62:65], v[174:177], v[190:193], v[62:65]
	v_mfma_f32_16x16x32_bf16 v[58:61], v[182:185], v[190:193], v[58:61]
	v_mfma_f32_16x16x32_bf16 v[46:49], v[174:177], v[198:201], v[46:49]
	v_mfma_f32_16x16x32_bf16 v[42:45], v[182:185], v[198:201], v[42:45]
	v_mfma_f32_16x16x32_bf16 v[30:33], v[174:177], v[206:209], v[30:33]
	v_mfma_f32_16x16x32_bf16 v[26:29], v[182:185], v[206:209], v[26:29]
	v_mfma_f32_16x16x32_bf16 v[14:17], v[174:177], v[214:217], v[14:17]
	v_mfma_f32_16x16x32_bf16 v[10:13], v[182:185], v[214:217], v[10:13]
	v_mfma_f32_16x16x32_bf16 v[62:65], v[178:181], v[194:197], v[62:65]
	v_mfma_f32_16x16x32_bf16 v[58:61], v[186:189], v[194:197], v[58:61]
	v_mfma_f32_16x16x32_bf16 v[46:49], v[178:181], v[202:205], v[46:49]
	v_mfma_f32_16x16x32_bf16 v[42:45], v[186:189], v[202:205], v[42:45]
	v_mfma_f32_16x16x32_bf16 v[30:33], v[178:181], v[210:213], v[30:33]
	v_mfma_f32_16x16x32_bf16 v[26:29], v[186:189], v[210:213], v[26:29]
	v_mfma_f32_16x16x32_bf16 v[14:17], v[178:181], v[218:221], v[14:17]
	v_mfma_f32_16x16x32_bf16 v[10:13], v[186:189], v[218:221], v[10:13]
	s_setprio 0
	s_barrier
	s_add_i32 s24, 0, 0x18000
	v_add_u32_e32 v157, s24, v150
	s_add_i32 s25, 0, 0x1c000
	ds_read_b128 v[158:161], v157
	ds_read_b128 v[162:165], v157 offset:1024
	ds_read_b128 v[166:169], v157 offset:2048
	ds_read_b128 v[170:173], v157 offset:3072
	v_add_u32_e32 v157, s25, v150
	ds_read_b128 v[174:177], v157
	ds_read_b128 v[178:181], v157 offset:1024
	ds_read_b128 v[182:185], v157 offset:2048
	ds_read_b128 v[186:189], v157 offset:3072
	s_add_u32 s60, s60, 0x80000
	s_addc_u32 s61, s61, 0
	s_mov_b32 m0, s63
	v_lshl_add_u64 v[230:231], s[60:61], 0, v[136:137]
	ds_read_b128 v[190:193], v154 offset:32768
	ds_read_b128 v[194:197], v154 offset:33792
	ds_read_b128 v[198:201], v154 offset:34816
	ds_read_b128 v[202:205], v154 offset:35840
	ds_read_b128 v[206:209], v154 offset:36864
	ds_read_b128 v[210:213], v154 offset:37888
	ds_read_b128 v[214:217], v154 offset:38912
	ds_read_b128 v[218:221], v154 offset:39936
	global_load_lds_dwordx4 v[230:231], off
	v_lshl_add_u64 v[230:231], s[60:61], 0, v[132:133]
	s_mov_b32 m0, s64
	s_nop 0
	global_load_lds_dwordx4 v[230:231], off
	s_waitcnt vmcnt(8)
	s_waitcnt lgkmcnt(0)
	s_barrier
	s_setprio 1
	s_waitcnt lgkmcnt(0)
	.p2align 3
	v_mfma_f32_16x16x32_bf16 v[118:121], v[158:161], v[190:193], v[118:121]
	v_mfma_f32_16x16x32_bf16 v[114:117], v[166:169], v[190:193], v[114:117]
	v_mfma_f32_16x16x32_bf16 v[102:105], v[158:161], v[198:201], v[102:105]
	v_mfma_f32_16x16x32_bf16 v[98:101], v[166:169], v[198:201], v[98:101]
	v_mfma_f32_16x16x32_bf16 v[86:89], v[158:161], v[206:209], v[86:89]
	v_mfma_f32_16x16x32_bf16 v[82:85], v[166:169], v[206:209], v[82:85]
	v_mfma_f32_16x16x32_bf16 v[70:73], v[158:161], v[214:217], v[70:73]
	v_mfma_f32_16x16x32_bf16 v[66:69], v[166:169], v[214:217], v[66:69]
	v_mfma_f32_16x16x32_bf16 v[118:121], v[162:165], v[194:197], v[118:121]
	v_mfma_f32_16x16x32_bf16 v[114:117], v[170:173], v[194:197], v[114:117]
	v_mfma_f32_16x16x32_bf16 v[102:105], v[162:165], v[202:205], v[102:105]
	v_mfma_f32_16x16x32_bf16 v[98:101], v[170:173], v[202:205], v[98:101]
	v_mfma_f32_16x16x32_bf16 v[86:89], v[162:165], v[210:213], v[86:89]
	v_mfma_f32_16x16x32_bf16 v[82:85], v[170:173], v[210:213], v[82:85]
	v_mfma_f32_16x16x32_bf16 v[70:73], v[162:165], v[218:221], v[70:73]
	v_mfma_f32_16x16x32_bf16 v[66:69], v[170:173], v[218:221], v[66:69]
	s_setprio 0
	s_setprio 1
	.p2align 3
	v_mfma_f32_16x16x32_bf16 v[126:129], v[174:177], v[190:193], v[126:129]
	v_mfma_f32_16x16x32_bf16 v[122:125], v[182:185], v[190:193], v[122:125]
	v_mfma_f32_16x16x32_bf16 v[110:113], v[174:177], v[198:201], v[110:113]
	v_mfma_f32_16x16x32_bf16 v[106:109], v[182:185], v[198:201], v[106:109]
	v_mfma_f32_16x16x32_bf16 v[94:97], v[174:177], v[206:209], v[94:97]
	v_mfma_f32_16x16x32_bf16 v[90:93], v[182:185], v[206:209], v[90:93]
	v_mfma_f32_16x16x32_bf16 v[78:81], v[174:177], v[214:217], v[78:81]
	v_mfma_f32_16x16x32_bf16 v[74:77], v[182:185], v[214:217], v[74:77]
	v_mfma_f32_16x16x32_bf16 v[126:129], v[178:181], v[194:197], v[126:129]
	v_mfma_f32_16x16x32_bf16 v[122:125], v[186:189], v[194:197], v[122:125]
	v_mfma_f32_16x16x32_bf16 v[110:113], v[178:181], v[202:205], v[110:113]
	v_mfma_f32_16x16x32_bf16 v[106:109], v[186:189], v[202:205], v[106:109]
	v_mfma_f32_16x16x32_bf16 v[94:97], v[178:181], v[210:213], v[94:97]
	v_mfma_f32_16x16x32_bf16 v[90:93], v[186:189], v[210:213], v[90:93]
	v_mfma_f32_16x16x32_bf16 v[78:81], v[178:181], v[218:221], v[78:81]
	v_mfma_f32_16x16x32_bf16 v[74:77], v[186:189], v[218:221], v[74:77]
	s_setprio 0
	s_barrier
; #define PG8_STAGEA(bufoff, gbase, voff) PG8_STAGE_X(bufoff, gbase, voff, PG8_AUX_A)
; #define PG8_STAGEB(bufoff, gbase, voff) PG8_STAGE_X(bufoff, gbase, voff, PG8_AUX_B)
; #define PG8_LDA(dst, b, h) do { _Pragma("unroll") for (int m = 0; m < 4; ++m) _Pragma("unroll") for (int k = 0; k < 2; ++k) dst[m][k] = *(const PG8_LAS bf16x8*)(lds + PG8_SA(b, h) + aoff + m * 2048 + k * 1024); } while (0)
; #define PG8_MMA(ai, bj, At, Bt) do { __builtin_amdgcn_s_setprio(1); _Pragma("unroll") for (int m = 0; m < 4; ++m) _Pragma("unroll") for (int n = 0; n < 2; ++n) _Pragma("unroll") for (int k = 0; k < 2; ++k) \
;         acc[ai][bj][m][n] = __builtin_amdgcn_mfma_f32_16x16x32_bf16(Bt[n][k], At[m][k], acc[ai][bj][m][n], 0, 0, 0); __builtin_amdgcn_s_setprio(0); } while (0)
; #define PG8_WAIT_V(n) asm volatile("s_waitcnt vmcnt(" #n ")" ::: "memory")
; #define PG8_WAIT_L(n) asm volatile("s_waitcnt lgkmcnt(" #n ")" ::: "memory")
; #define PG8_BAR __builtin_amdgcn_s_barrier()
; #define PG8_SCHED __builtin_amdgcn_sched_barrier(0)
; template <class Epi, class Sched, bool ALIGN_EPI = false, bool SP2 = false>
; __device__ __forceinline__ void gemm_phase(PG8_LAS unsigned char* lds, const Gemm g, const Sched& S, const Epi& E) {
;     ...
;             PG8_LDA(At, 1, 1); PG8_STAGEB(PG8_SB(1, 0), b3, voffB); PG8_STAGEB(PG8_SB(1, 1), b3 + hstep, voffB); PG8_STAGEA(PG8_SA(1, 0), a3, voffA);
;             PG8_WAIT_V(8); PG8_WAIT_L(0); PG8_BAR; PG8_MMA(1, 0, At, B0); PG8_MMA(1, 1, At, B1); PG8_BAR; PG8_SCHED;
;     ...
;         if constexpr (ALIGN_EPI) { if (wr == 0) PG8_BAR; }
	s_add_i32 s24, s24, s11
	v_lshl_add_u64 v[222:223], v[222:223], 0, s[40:41]
	s_mov_b32 m0, s24
	ds_read_b128 v[190:193], v154 offset:49152
	ds_read_b128 v[194:197], v154 offset:50176
	ds_read_b128 v[198:201], v154 offset:51200
	ds_read_b128 v[202:205], v154 offset:52224
	ds_read_b128 v[206:209], v154 offset:53248
	ds_read_b128 v[210:213], v154 offset:54272
	ds_read_b128 v[214:217], v154 offset:55296
	ds_read_b128 v[218:221], v154 offset:56320
	global_load_lds_dwordx4 v[222:223], off
	s_add_i32 m0, s24, 0x2000
	s_add_u32 s58, s58, 0x80080
	v_lshl_add_u64 v[222:223], v[224:225], 0, s[40:41]
	s_addc_u32 s59, s59, 0
	s_add_i32 s24, s25, s11
	global_load_lds_dwordx4 v[222:223], off
	v_lshl_add_u64 v[222:223], s[58:59], 0, v[134:135]
	s_mov_b32 m0, s24
	s_nop 0
	global_load_lds_dwordx4 v[222:223], off
	v_lshl_add_u64 v[222:223], s[58:59], 0, v[130:131]
	s_add_i32 m0, s24, 0x2000
	s_nop 0
	global_load_lds_dwordx4 v[222:223], off
	v_lshl_add_u64 v[222:223], v[226:227], 0, s[40:41]
	s_mov_b32 m0, s67
	s_nop 0
	global_load_lds_dwordx4 v[222:223], off
	v_lshl_add_u64 v[222:223], v[228:229], 0, s[40:41]
	s_mov_b32 m0, s68
	s_nop 0
	global_load_lds_dwordx4 v[222:223], off
	s_waitcnt vmcnt(8)
	s_waitcnt lgkmcnt(0)
	s_barrier
	s_setprio 1
	s_waitcnt lgkmcnt(0)
	.p2align 3
	v_mfma_f32_16x16x32_bf16 v[54:57], v[158:161], v[190:193], v[54:57]
	v_mfma_f32_16x16x32_bf16 v[50:53], v[166:169], v[190:193], v[50:53]
	v_mfma_f32_16x16x32_bf16 v[38:41], v[158:161], v[198:201], v[38:41]
	v_mfma_f32_16x16x32_bf16 v[34:37], v[166:169], v[198:201], v[34:37]
	v_mfma_f32_16x16x32_bf16 v[22:25], v[158:161], v[206:209], v[22:25]
	v_mfma_f32_16x16x32_bf16 v[18:21], v[166:169], v[206:209], v[18:21]
	v_mfma_f32_16x16x32_bf16 v[6:9], v[158:161], v[214:217], v[6:9]
	v_mfma_f32_16x16x32_bf16 v[2:5], v[166:169], v[214:217], v[2:5]
	v_mfma_f32_16x16x32_bf16 v[54:57], v[162:165], v[194:197], v[54:57]
	v_mfma_f32_16x16x32_bf16 v[50:53], v[170:173], v[194:197], v[50:53]
	v_mfma_f32_16x16x32_bf16 v[38:41], v[162:165], v[202:205], v[38:41]
	v_mfma_f32_16x16x32_bf16 v[34:37], v[170:173], v[202:205], v[34:37]
	v_mfma_f32_16x16x32_bf16 v[22:25], v[162:165], v[210:213], v[22:25]
	v_mfma_f32_16x16x32_bf16 v[18:21], v[170:173], v[210:213], v[18:21]
	v_mfma_f32_16x16x32_bf16 v[6:9], v[162:165], v[218:221], v[6:9]
	v_mfma_f32_16x16x32_bf16 v[2:5], v[170:173], v[218:221], v[2:5]
	s_setprio 0
	s_setprio 1
	.p2align 3
	v_mfma_f32_16x16x32_bf16 v[62:65], v[174:177], v[190:193], v[62:65]
	v_mfma_f32_16x16x32_bf16 v[58:61], v[182:185], v[190:193], v[58:61]
	v_mfma_f32_16x16x32_bf16 v[46:49], v[174:177], v[198:201], v[46:49]
	v_mfma_f32_16x16x32_bf16 v[42:45], v[182:185], v[198:201], v[42:45]
	v_mfma_f32_16x16x32_bf16 v[30:33], v[174:177], v[206:209], v[30:33]
	v_mfma_f32_16x16x32_bf16 v[26:29], v[182:185], v[206:209], v[26:29]
	v_mfma_f32_16x16x32_bf16 v[14:17], v[174:177], v[214:217], v[14:17]
	v_mfma_f32_16x16x32_bf16 v[10:13], v[182:185], v[214:217], v[10:13]
	v_mfma_f32_16x16x32_bf16 v[62:65], v[178:181], v[194:197], v[62:65]
	v_mfma_f32_16x16x32_bf16 v[58:61], v[186:189], v[194:197], v[58:61]
	v_mfma_f32_16x16x32_bf16 v[46:49], v[178:181], v[202:205], v[46:49]
	v_mfma_f32_16x16x32_bf16 v[42:45], v[186:189], v[202:205], v[42:45]
	v_mfma_f32_16x16x32_bf16 v[30:33], v[178:181], v[210:213], v[30:33]
	v_mfma_f32_16x16x32_bf16 v[26:29], v[186:189], v[210:213], v[26:29]
	v_mfma_f32_16x16x32_bf16 v[14:17], v[178:181], v[218:221], v[14:17]
	v_mfma_f32_16x16x32_bf16 v[10:13], v[186:189], v[218:221], v[10:13]
	s_setprio 0
	s_barrier
	s_add_u32 s56, s56, 0x100
	s_addc_u32 s57, s57, 0
	s_mov_b32 s58, s76
	s_cbranch_vccz .LBB0_1007
	s_and_b64 vcc, exec, s[42:43]
	s_cbranch_vccz .LBB0_1010
	s_barrier

; #define PG8_STAGEA(bufoff, gbase, voff) PG8_STAGE_X(bufoff, gbase, voff, PG8_AUX_A)
; #define PG8_STAGEB(bufoff, gbase, voff) PG8_STAGE_X(bufoff, gbase, voff, PG8_AUX_B)
; #define PG8_LDA(dst, b, h) do { _Pragma("unroll") for (int m = 0; m < 4; ++m) _Pragma("unroll") for (int k = 0; k < 2; ++k) dst[m][k] = *(const PG8_LAS bf16x8*)(lds + PG8_SA(b, h) + aoff + m * 2048 + k * 1024); } while (0)
; #define PG8_LDB(dst, b, h) do { _Pragma("unroll") for (int n = 0; n < 2; ++n) _Pragma("unroll") for (int k = 0; k < 2; ++k) dst[n][k] = *(const PG8_LAS bf16x8*)(lds + PG8_SB(b, h) + boff + n * 2048 + k * 1024); } while (0)
; #define PG8_MMA(ai, bj, At, Bt) do { __builtin_amdgcn_s_setprio(1); _Pragma("unroll") for (int m = 0; m < 4; ++m) _Pragma("unroll") for (int n = 0; n < 2; ++n) _Pragma("unroll") for (int k = 0; k < 2; ++k) \
;         acc[ai][bj][m][n] = __builtin_amdgcn_mfma_f32_16x16x32_bf16(Bt[n][k], At[m][k], acc[ai][bj][m][n], 0, 0, 0); __builtin_amdgcn_s_setprio(0); } while (0)
; template <class Epi, class Sched, bool ALIGN_EPI = false, bool SP2 = false>
; __device__ __forceinline__ void gemm_phase(PG8_LAS unsigned char* lds, const Gemm g, const Sched& S, const Epi& E) {
;     ...
;         for (int t = 0; t < nt; t += 2) {
;             const bool last = (t == nt - 2);
;             if constexpr (HasMid<Epi>::value) { if (t == ns) E.mid(acc, cur, wr, wc, fr, fq); }
;             const char* sA1 = (t + 1 >= ns) ? cA2 : cA; const char* sA2 = (t + 2 >= ns) ? cA2 : cA; const char* sB2 = (t + 2 >= ns) ? cB2 : cB;
;             const char* a1 = sA1 + (size_t)(t + 1) * kstep;
;             const char* a2 = last ? nA : sA2 + (size_t)(t + 2) * kstep; const char* b2 = last ? nB : sB2 + (size_t)(t + 2) * kstep;
;             const char* a3 = a2 + kstep; const char* b3 = b2 + kstep;
;             if (last && has_next) S.a_ready(nxt);
;             if constexpr (SP2) {
;             PG8_LDB(B0, 0, 0); PG8_LDB(B1, 0, 1); PG8_SCHED; PG8_LDA(At, 0, 0); PG8_STAGEA(PG8_SA(1, 1), a1 + hstep, voffA);
;             PG8_WAIT_V(8); PG8_WAIT_L(0); PG8_BAR; PG8_MMA(0, 0, At, B0); PG8_MMA(0, 1, At, B1); PG8_BAR; PG8_SCHED;
;             PG8_LDA(At, 0, 1); PG8_STAGEB(PG8_SB(0, 0), b2, voffB); PG8_STAGEB(PG8_SB(0, 1), b2 + hstep, voffB); PG8_STAGEA(PG8_SA(0, 0), a2, voffA);
;             PG8_WAIT_V(8); PG8_WAIT_L(0); PG8_BAR; PG8_MMA(1, 0, At, B0); PG8_MMA(1, 1, At, B1); PG8_BAR; PG8_SCHED;
.LBB0_1090:
	s_add_i32 s75, s54, 2
	s_cmpk_gt_u32 s75, 0x55
	s_cselect_b64 s[56:57], -1, 0
	s_and_b64 vcc, s[56:57], exec
	s_cselect_b32 s56, s24, s50
	ds_read_b128 v[154:157], v150
	ds_read_b128 v[158:161], v150 offset:1024
	ds_read_b128 v[162:165], v150 offset:2048
	ds_read_b128 v[166:169], v150 offset:3072
	ds_read_b128 v[170:173], v151
	ds_read_b128 v[174:177], v151 offset:1024
	ds_read_b128 v[178:181], v151 offset:2048
	ds_read_b128 v[182:185], v151 offset:3072
	s_cselect_b32 s28, s9, s49
	s_cselect_b32 s29, s8, s48
	s_cselect_b32 s55, s25, s51
	s_add_u32 s56, s56, s52
	s_addc_u32 s55, s55, s53
	s_add_u32 s56, s56, 0xffea0080
	s_addc_u32 s55, s55, -1
	s_add_u32 s29, s29, s52
	s_addc_u32 s28, s28, s53
	s_add_u32 s29, s29, 0xffea0080
	s_addc_u32 s28, s28, -1
	s_cmpk_eq_i32 s54, 0x54
	s_cselect_b32 s54, s46, s29
	s_cselect_b32 s57, s5, s55
	s_cselect_b32 s56, s4, s56
	s_cselect_b32 s55, s47, s28
	v_lshl_add_u64 v[146:147], v[142:143], 0, s[52:53]
	s_add_i32 m0, s23, 0xc000
	ds_read_b128 v[186:189], v152
	ds_read_b128 v[190:193], v152 offset:1024
	ds_read_b128 v[194:197], v152 offset:2048
	ds_read_b128 v[198:201], v152 offset:3072
	ds_read_b128 v[202:205], v152 offset:4096
	ds_read_b128 v[206:209], v152 offset:5120
	ds_read_b128 v[210:213], v152 offset:6144
	ds_read_b128 v[214:217], v152 offset:7168
	global_load_lds_dwordx4 v[146:147], off
	v_lshl_add_u64 v[146:147], v[144:145], 0, s[52:53]
	s_add_i32 m0, s23, 0xe000
	s_nop 0
	global_load_lds_dwordx4 v[146:147], off
	s_waitcnt vmcnt(8)
	s_waitcnt lgkmcnt(0)
	s_barrier
	s_setprio 1
	s_waitcnt lgkmcnt(0)
	.p2align 3
	v_mfma_f32_16x16x32_bf16 v[126:129], v[154:157], v[186:189], v[126:129]
	v_mfma_f32_16x16x32_bf16 v[122:125], v[162:165], v[186:189], v[122:125]
	v_mfma_f32_16x16x32_bf16 v[114:117], v[154:157], v[194:197], v[114:117]
	v_mfma_f32_16x16x32_bf16 v[106:109], v[162:165], v[194:197], v[106:109]
	v_mfma_f32_16x16x32_bf16 v[94:97], v[154:157], v[202:205], v[94:97]
	v_mfma_f32_16x16x32_bf16 v[90:93], v[162:165], v[202:205], v[90:93]
	v_mfma_f32_16x16x32_bf16 v[78:81], v[154:157], v[210:213], v[78:81]
	v_mfma_f32_16x16x32_bf16 v[74:77], v[162:165], v[210:213], v[74:77]
	v_mfma_f32_16x16x32_bf16 v[126:129], v[158:161], v[190:193], v[126:129]
	v_mfma_f32_16x16x32_bf16 v[122:125], v[166:169], v[190:193], v[122:125]
	v_mfma_f32_16x16x32_bf16 v[114:117], v[158:161], v[198:201], v[114:117]
	v_mfma_f32_16x16x32_bf16 v[106:109], v[166:169], v[198:201], v[106:109]
	v_mfma_f32_16x16x32_bf16 v[94:97], v[158:161], v[206:209], v[94:97]
	v_mfma_f32_16x16x32_bf16 v[90:93], v[166:169], v[206:209], v[90:93]
	v_mfma_f32_16x16x32_bf16 v[78:81], v[158:161], v[214:217], v[78:81]
	v_mfma_f32_16x16x32_bf16 v[74:77], v[166:169], v[214:217], v[74:77]
	s_setprio 0
	s_setprio 1
	.p2align 3
	v_mfma_f32_16x16x32_bf16 v[118:121], v[170:173], v[186:189], v[118:121]
	v_mfma_f32_16x16x32_bf16 v[110:113], v[178:181], v[186:189], v[110:113]
	v_mfma_f32_16x16x32_bf16 v[102:105], v[170:173], v[194:197], v[102:105]
	v_mfma_f32_16x16x32_bf16 v[98:101], v[178:181], v[194:197], v[98:101]
	v_mfma_f32_16x16x32_bf16 v[86:89], v[170:173], v[202:205], v[86:89]
	v_mfma_f32_16x16x32_bf16 v[82:85], v[178:181], v[202:205], v[82:85]
	v_mfma_f32_16x16x32_bf16 v[70:73], v[170:173], v[210:213], v[70:73]
	v_mfma_f32_16x16x32_bf16 v[66:69], v[178:181], v[210:213], v[66:69]
	v_mfma_f32_16x16x32_bf16 v[118:121], v[174:177], v[190:193], v[118:121]
	v_mfma_f32_16x16x32_bf16 v[110:113], v[182:185], v[190:193], v[110:113]
	v_mfma_f32_16x16x32_bf16 v[102:105], v[174:177], v[198:201], v[102:105]
	v_mfma_f32_16x16x32_bf16 v[98:101], v[182:185], v[198:201], v[98:101]
	v_mfma_f32_16x16x32_bf16 v[86:89], v[174:177], v[206:209], v[86:89]
	v_mfma_f32_16x16x32_bf16 v[82:85], v[182:185], v[206:209], v[82:85]
	v_mfma_f32_16x16x32_bf16 v[70:73], v[174:177], v[214:217], v[70:73]
	v_mfma_f32_16x16x32_bf16 v[66:69], v[182:185], v[214:217], v[66:69]
	s_setprio 0
	s_barrier
	s_add_i32 s28, s65, s21
	v_lshl_add_u64 v[146:147], s[54:55], 0, v[130:131]
	s_mov_b32 m0, s28
	ds_read_b128 v[186:189], v152 offset:16384
	ds_read_b128 v[190:193], v152 offset:17408
	ds_read_b128 v[194:197], v152 offset:18432
	ds_read_b128 v[198:201], v152 offset:19456
	ds_read_b128 v[202:205], v152 offset:20480
	ds_read_b128 v[206:209], v152 offset:21504
	ds_read_b128 v[210:213], v152 offset:22528
	ds_read_b128 v[214:217], v152 offset:23552
	global_load_lds_dwordx4 v[146:147], off
	s_add_i32 m0, s28, 0x2000
	s_add_u32 s76, s54, 0x160000
	v_lshl_add_u64 v[218:219], s[54:55], 0, v[132:133]
	s_addc_u32 s77, s55, 0
	s_add_i32 s28, s66, s21
	global_load_lds_dwordx4 v[218:219], off
	v_lshl_add_u64 v[220:221], s[76:77], 0, v[130:131]
	s_mov_b32 m0, s28
	v_lshl_add_u64 v[222:223], s[56:57], 0, v[132:133]
	global_load_lds_dwordx4 v[220:221], off
	v_lshl_add_u64 v[220:221], s[76:77], 0, v[132:133]
	s_add_i32 m0, s28, 0x2000
	s_nop 0
	global_load_lds_dwordx4 v[220:221], off
	v_lshl_add_u64 v[220:221], s[56:57], 0, v[130:131]
	s_mov_b32 m0, s23
	s_nop 0
	global_load_lds_dwordx4 v[220:221], off
	s_mov_b32 m0, s33
	s_nop 0
	global_load_lds_dwordx4 v[222:223], off
	s_waitcnt vmcnt(8)
	s_waitcnt lgkmcnt(0)
	s_barrier
; #define PG8_STAGEA(bufoff, gbase, voff) PG8_STAGE_X(bufoff, gbase, voff, PG8_AUX_A)
; #define PG8_LDA(dst, b, h) do { _Pragma("unroll") for (int m = 0; m < 4; ++m) _Pragma("unroll") for (int k = 0; k < 2; ++k) dst[m][k] = *(const PG8_LAS bf16x8*)(lds + PG8_SA(b, h) + aoff + m * 2048 + k * 1024); } while (0)
; #define PG8_LDB(dst, b, h) do { _Pragma("unroll") for (int n = 0; n < 2; ++n) _Pragma("unroll") for (int k = 0; k < 2; ++k) dst[n][k] = *(const PG8_LAS bf16x8*)(lds + PG8_SB(b, h) + boff + n * 2048 + k * 1024); } while (0)
; #define PG8_MMA(ai, bj, At, Bt) do { __builtin_amdgcn_s_setprio(1); _Pragma("unroll") for (int m = 0; m < 4; ++m) _Pragma("unroll") for (int n = 0; n < 2; ++n) _Pragma("unroll") for (int k = 0; k < 2; ++k) \
;         acc[ai][bj][m][n] = __builtin_amdgcn_mfma_f32_16x16x32_bf16(Bt[n][k], At[m][k], acc[ai][bj][m][n], 0, 0, 0); __builtin_amdgcn_s_setprio(0); } while (0)
; #define PG8_WAIT_V(n) asm volatile("s_waitcnt vmcnt(" #n ")" ::: "memory")
; #define PG8_WAIT_L(n) asm volatile("s_waitcnt lgkmcnt(" #n ")" ::: "memory")
; #define PG8_BAR __builtin_amdgcn_s_barrier()
; #define PG8_SCHED __builtin_amdgcn_sched_barrier(0)
; template <class Epi, class Sched, bool ALIGN_EPI = false, bool SP2 = false>
; __device__ __forceinline__ void gemm_phase(PG8_LAS unsigned char* lds, const Gemm g, const Sched& S, const Epi& E) {
;     ...
;             PG8_WAIT_V(8); PG8_WAIT_L(0); PG8_BAR; PG8_MMA(1, 0, At, B0); PG8_MMA(1, 1, At, B1); PG8_BAR; PG8_SCHED;
;             PG8_LDB(B0, 1, 0); PG8_LDB(B1, 1, 1); PG8_SCHED; PG8_LDA(At, 1, 0); PG8_STAGEA(PG8_SA(0, 1), a2 + hstep, voffA);
;             PG8_WAIT_V(8); PG8_WAIT_L(0); PG8_BAR; PG8_MMA(0, 0, At, B0); PG8_MMA(0, 1, At, B1); PG8_BAR; PG8_SCHED;
	s_setprio 1
	s_waitcnt lgkmcnt(0)
	.p2align 3
	v_mfma_f32_16x16x32_bf16 v[62:65], v[154:157], v[186:189], v[62:65]
	v_mfma_f32_16x16x32_bf16 v[58:61], v[162:165], v[186:189], v[58:61]
	v_mfma_f32_16x16x32_bf16 v[46:49], v[154:157], v[194:197], v[46:49]
	v_mfma_f32_16x16x32_bf16 v[42:45], v[162:165], v[194:197], v[42:45]
	v_mfma_f32_16x16x32_bf16 v[30:33], v[154:157], v[202:205], v[30:33]
	v_mfma_f32_16x16x32_bf16 v[26:29], v[162:165], v[202:205], v[26:29]
	v_mfma_f32_16x16x32_bf16 v[14:17], v[154:157], v[210:213], v[14:17]
	v_mfma_f32_16x16x32_bf16 v[10:13], v[162:165], v[210:213], v[10:13]
	v_mfma_f32_16x16x32_bf16 v[62:65], v[158:161], v[190:193], v[62:65]
	v_mfma_f32_16x16x32_bf16 v[58:61], v[166:169], v[190:193], v[58:61]
	v_mfma_f32_16x16x32_bf16 v[46:49], v[158:161], v[198:201], v[46:49]
	v_mfma_f32_16x16x32_bf16 v[42:45], v[166:169], v[198:201], v[42:45]
	v_mfma_f32_16x16x32_bf16 v[30:33], v[158:161], v[206:209], v[30:33]
	v_mfma_f32_16x16x32_bf16 v[26:29], v[166:169], v[206:209], v[26:29]
	v_mfma_f32_16x16x32_bf16 v[14:17], v[158:161], v[214:217], v[14:17]
	v_mfma_f32_16x16x32_bf16 v[10:13], v[166:169], v[214:217], v[10:13]
	s_setprio 0
	s_setprio 1
	.p2align 3
	v_mfma_f32_16x16x32_bf16 v[54:57], v[170:173], v[186:189], v[54:57]
	v_mfma_f32_16x16x32_bf16 v[50:53], v[178:181], v[186:189], v[50:53]
	v_mfma_f32_16x16x32_bf16 v[38:41], v[170:173], v[194:197], v[38:41]
	v_mfma_f32_16x16x32_bf16 v[34:37], v[178:181], v[194:197], v[34:37]
	v_mfma_f32_16x16x32_bf16 v[22:25], v[170:173], v[202:205], v[22:25]
	v_mfma_f32_16x16x32_bf16 v[18:21], v[178:181], v[202:205], v[18:21]
	v_mfma_f32_16x16x32_bf16 v[6:9], v[170:173], v[210:213], v[6:9]
	v_mfma_f32_16x16x32_bf16 v[2:5], v[178:181], v[210:213], v[2:5]
	v_mfma_f32_16x16x32_bf16 v[54:57], v[174:177], v[190:193], v[54:57]
	v_mfma_f32_16x16x32_bf16 v[50:53], v[182:185], v[190:193], v[50:53]
	v_mfma_f32_16x16x32_bf16 v[38:41], v[174:177], v[198:201], v[38:41]
	v_mfma_f32_16x16x32_bf16 v[34:37], v[182:185], v[198:201], v[34:37]
	v_mfma_f32_16x16x32_bf16 v[22:25], v[174:177], v[206:209], v[22:25]
	v_mfma_f32_16x16x32_bf16 v[18:21], v[182:185], v[206:209], v[18:21]
	v_mfma_f32_16x16x32_bf16 v[6:9], v[174:177], v[214:217], v[6:9]
	v_mfma_f32_16x16x32_bf16 v[2:5], v[182:185], v[214:217], v[2:5]
	s_setprio 0
	s_barrier
	s_add_i32 s28, 0, 0x18000
	v_add_u32_e32 v153, s28, v148
	s_add_i32 s29, 0, 0x1c000
	ds_read_b128 v[154:157], v153
	ds_read_b128 v[158:161], v153 offset:1024
	ds_read_b128 v[162:165], v153 offset:2048
	ds_read_b128 v[166:169], v153 offset:3072
	v_add_u32_e32 v153, s29, v148
	ds_read_b128 v[170:173], v153
	ds_read_b128 v[174:177], v153 offset:1024
	ds_read_b128 v[178:181], v153 offset:2048
	ds_read_b128 v[182:185], v153 offset:3072
	s_add_u32 s56, s56, 0x160000
	s_addc_u32 s57, s57, 0
	s_mov_b32 m0, s58
	v_lshl_add_u64 v[224:225], s[56:57], 0, v[130:131]
	ds_read_b128 v[186:189], v152 offset:32768
	ds_read_b128 v[190:193], v152 offset:33792
	ds_read_b128 v[194:197], v152 offset:34816
	ds_read_b128 v[198:201], v152 offset:35840
	ds_read_b128 v[202:205], v152 offset:36864
	ds_read_b128 v[206:209], v152 offset:37888
	ds_read_b128 v[210:213], v152 offset:38912
	ds_read_b128 v[214:217], v152 offset:39936
	global_load_lds_dwordx4 v[224:225], off
	v_lshl_add_u64 v[224:225], s[56:57], 0, v[132:133]
	s_mov_b32 m0, s59
	s_nop 0
	global_load_lds_dwordx4 v[224:225], off
	s_waitcnt vmcnt(8)
	s_waitcnt lgkmcnt(0)
	s_barrier
	s_setprio 1
	s_waitcnt lgkmcnt(0)
	.p2align 3
	v_mfma_f32_16x16x32_bf16 v[126:129], v[154:157], v[186:189], v[126:129]
	v_mfma_f32_16x16x32_bf16 v[122:125], v[162:165], v[186:189], v[122:125]
	v_mfma_f32_16x16x32_bf16 v[114:117], v[154:157], v[194:197], v[114:117]
	v_mfma_f32_16x16x32_bf16 v[106:109], v[162:165], v[194:197], v[106:109]
	v_mfma_f32_16x16x32_bf16 v[94:97], v[154:157], v[202:205], v[94:97]
	v_mfma_f32_16x16x32_bf16 v[90:93], v[162:165], v[202:205], v[90:93]
	v_mfma_f32_16x16x32_bf16 v[78:81], v[154:157], v[210:213], v[78:81]
	v_mfma_f32_16x16x32_bf16 v[74:77], v[162:165], v[210:213], v[74:77]
	v_mfma_f32_16x16x32_bf16 v[126:129], v[158:161], v[190:193], v[126:129]
	v_mfma_f32_16x16x32_bf16 v[122:125], v[166:169], v[190:193], v[122:125]
	v_mfma_f32_16x16x32_bf16 v[114:117], v[158:161], v[198:201], v[114:117]
	v_mfma_f32_16x16x32_bf16 v[106:109], v[166:169], v[198:201], v[106:109]
	v_mfma_f32_16x16x32_bf16 v[94:97], v[158:161], v[206:209], v[94:97]
	v_mfma_f32_16x16x32_bf16 v[90:93], v[166:169], v[206:209], v[90:93]
	v_mfma_f32_16x16x32_bf16 v[78:81], v[158:161], v[214:217], v[78:81]
	v_mfma_f32_16x16x32_bf16 v[74:77], v[166:169], v[214:217], v[74:77]
	s_setprio 0
	s_setprio 1
	.p2align 3
	v_mfma_f32_16x16x32_bf16 v[118:121], v[170:173], v[186:189], v[118:121]
	v_mfma_f32_16x16x32_bf16 v[110:113], v[178:181], v[186:189], v[110:113]
	v_mfma_f32_16x16x32_bf16 v[102:105], v[170:173], v[194:197], v[102:105]
	v_mfma_f32_16x16x32_bf16 v[98:101], v[178:181], v[194:197], v[98:101]
	v_mfma_f32_16x16x32_bf16 v[86:89], v[170:173], v[202:205], v[86:89]
	v_mfma_f32_16x16x32_bf16 v[82:85], v[178:181], v[202:205], v[82:85]
	v_mfma_f32_16x16x32_bf16 v[70:73], v[170:173], v[210:213], v[70:73]
	v_mfma_f32_16x16x32_bf16 v[66:69], v[178:181], v[210:213], v[66:69]
	v_mfma_f32_16x16x32_bf16 v[118:121], v[174:177], v[190:193], v[118:121]
	v_mfma_f32_16x16x32_bf16 v[110:113], v[182:185], v[190:193], v[110:113]
	v_mfma_f32_16x16x32_bf16 v[102:105], v[174:177], v[198:201], v[102:105]
	v_mfma_f32_16x16x32_bf16 v[98:101], v[182:185], v[198:201], v[98:101]
	v_mfma_f32_16x16x32_bf16 v[86:89], v[174:177], v[206:209], v[86:89]
	v_mfma_f32_16x16x32_bf16 v[82:85], v[182:185], v[206:209], v[82:85]
	v_mfma_f32_16x16x32_bf16 v[70:73], v[174:177], v[214:217], v[70:73]
	v_mfma_f32_16x16x32_bf16 v[66:69], v[182:185], v[214:217], v[66:69]
	s_setprio 0
	s_barrier
; #define PG8_STAGEA(bufoff, gbase, voff) PG8_STAGE_X(bufoff, gbase, voff, PG8_AUX_A)
; #define PG8_STAGEB(bufoff, gbase, voff) PG8_STAGE_X(bufoff, gbase, voff, PG8_AUX_B)
; #define PG8_LDA(dst, b, h) do { _Pragma("unroll") for (int m = 0; m < 4; ++m) _Pragma("unroll") for (int k = 0; k < 2; ++k) dst[m][k] = *(const PG8_LAS bf16x8*)(lds + PG8_SA(b, h) + aoff + m * 2048 + k * 1024); } while (0)
; #define PG8_MMA(ai, bj, At, Bt) do { __builtin_amdgcn_s_setprio(1); _Pragma("unroll") for (int m = 0; m < 4; ++m) _Pragma("unroll") for (int n = 0; n < 2; ++n) _Pragma("unroll") for (int k = 0; k < 2; ++k) \
;         acc[ai][bj][m][n] = __builtin_amdgcn_mfma_f32_16x16x32_bf16(Bt[n][k], At[m][k], acc[ai][bj][m][n], 0, 0, 0); __builtin_amdgcn_s_setprio(0); } while (0)
; #define PG8_WAIT_V(n) asm volatile("s_waitcnt vmcnt(" #n ")" ::: "memory")
; #define PG8_WAIT_L(n) asm volatile("s_waitcnt lgkmcnt(" #n ")" ::: "memory")
; #define PG8_BAR __builtin_amdgcn_s_barrier()
; #define PG8_SCHED __builtin_amdgcn_sched_barrier(0)
; template <class Epi, class Sched, bool ALIGN_EPI = false, bool SP2 = false>
; __device__ __forceinline__ void gemm_phase(PG8_LAS unsigned char* lds, const Gemm g, const Sched& S, const Epi& E) {
;     ...
;             PG8_WAIT_V(8); PG8_WAIT_L(0); PG8_BAR; PG8_MMA(0, 0, At, B0); PG8_MMA(0, 1, At, B1); PG8_BAR; PG8_SCHED;
;             PG8_LDA(At, 1, 1); PG8_STAGEB(PG8_SB(1, 0), b3, voffB); PG8_STAGEB(PG8_SB(1, 1), b3 + hstep, voffB); PG8_STAGEA(PG8_SA(1, 0), a3, voffA);
;             PG8_WAIT_V(8); PG8_WAIT_L(0); PG8_BAR; PG8_MMA(1, 0, At, B0); PG8_MMA(1, 1, At, B1); PG8_BAR; PG8_SCHED;
;     ...
;         if constexpr (ALIGN_EPI) { if (wr == 0) PG8_BAR; }
	s_add_i32 s28, s28, s21
	v_lshl_add_u64 v[146:147], v[146:147], 0, s[34:35]
	s_mov_b32 m0, s28
	ds_read_b128 v[186:189], v152 offset:49152
	ds_read_b128 v[190:193], v152 offset:50176
	ds_read_b128 v[194:197], v152 offset:51200
	ds_read_b128 v[198:201], v152 offset:52224
	ds_read_b128 v[202:205], v152 offset:53248
	ds_read_b128 v[206:209], v152 offset:54272
	ds_read_b128 v[210:213], v152 offset:55296
	ds_read_b128 v[214:217], v152 offset:56320
	global_load_lds_dwordx4 v[146:147], off
	s_add_i32 m0, s28, 0x2000
	s_add_u32 s54, s54, 0x160080
	v_lshl_add_u64 v[146:147], v[218:219], 0, s[34:35]
	s_addc_u32 s55, s55, 0
	s_add_i32 s28, s29, s21
	global_load_lds_dwordx4 v[146:147], off
	v_lshl_add_u64 v[146:147], s[54:55], 0, v[130:131]
	s_mov_b32 m0, s28
	s_nop 0
	global_load_lds_dwordx4 v[146:147], off
	v_lshl_add_u64 v[146:147], s[54:55], 0, v[132:133]
	s_add_i32 m0, s28, 0x2000
	s_nop 0
	global_load_lds_dwordx4 v[146:147], off
	v_lshl_add_u64 v[146:147], v[220:221], 0, s[34:35]
	s_mov_b32 m0, s61
	s_nop 0
	global_load_lds_dwordx4 v[146:147], off
	v_lshl_add_u64 v[146:147], v[222:223], 0, s[34:35]
	s_mov_b32 m0, s62
	s_nop 0
	global_load_lds_dwordx4 v[146:147], off
	s_waitcnt vmcnt(8)
	s_waitcnt lgkmcnt(0)
	s_barrier
	s_setprio 1
	s_waitcnt lgkmcnt(0)
	.p2align 3
	v_mfma_f32_16x16x32_bf16 v[62:65], v[154:157], v[186:189], v[62:65]
	v_mfma_f32_16x16x32_bf16 v[58:61], v[162:165], v[186:189], v[58:61]
	v_mfma_f32_16x16x32_bf16 v[46:49], v[154:157], v[194:197], v[46:49]
	v_mfma_f32_16x16x32_bf16 v[42:45], v[162:165], v[194:197], v[42:45]
	v_mfma_f32_16x16x32_bf16 v[30:33], v[154:157], v[202:205], v[30:33]
	v_mfma_f32_16x16x32_bf16 v[26:29], v[162:165], v[202:205], v[26:29]
	v_mfma_f32_16x16x32_bf16 v[14:17], v[154:157], v[210:213], v[14:17]
	v_mfma_f32_16x16x32_bf16 v[10:13], v[162:165], v[210:213], v[10:13]
	v_mfma_f32_16x16x32_bf16 v[62:65], v[158:161], v[190:193], v[62:65]
	v_mfma_f32_16x16x32_bf16 v[58:61], v[166:169], v[190:193], v[58:61]
	v_mfma_f32_16x16x32_bf16 v[46:49], v[158:161], v[198:201], v[46:49]
	v_mfma_f32_16x16x32_bf16 v[42:45], v[166:169], v[198:201], v[42:45]
	v_mfma_f32_16x16x32_bf16 v[30:33], v[158:161], v[206:209], v[30:33]
	v_mfma_f32_16x16x32_bf16 v[26:29], v[166:169], v[206:209], v[26:29]
	v_mfma_f32_16x16x32_bf16 v[14:17], v[158:161], v[214:217], v[14:17]
	v_mfma_f32_16x16x32_bf16 v[10:13], v[166:169], v[214:217], v[10:13]
	s_setprio 0
	s_setprio 1
	.p2align 3
	v_mfma_f32_16x16x32_bf16 v[54:57], v[170:173], v[186:189], v[54:57]
	v_mfma_f32_16x16x32_bf16 v[50:53], v[178:181], v[186:189], v[50:53]
	v_mfma_f32_16x16x32_bf16 v[38:41], v[170:173], v[194:197], v[38:41]
	v_mfma_f32_16x16x32_bf16 v[34:37], v[178:181], v[194:197], v[34:37]
	v_mfma_f32_16x16x32_bf16 v[22:25], v[170:173], v[202:205], v[22:25]
	v_mfma_f32_16x16x32_bf16 v[18:21], v[178:181], v[202:205], v[18:21]
	v_mfma_f32_16x16x32_bf16 v[6:9], v[170:173], v[210:213], v[6:9]
	v_mfma_f32_16x16x32_bf16 v[2:5], v[178:181], v[210:213], v[2:5]
	v_mfma_f32_16x16x32_bf16 v[54:57], v[174:177], v[190:193], v[54:57]
	v_mfma_f32_16x16x32_bf16 v[50:53], v[182:185], v[190:193], v[50:53]
	v_mfma_f32_16x16x32_bf16 v[38:41], v[174:177], v[198:201], v[38:41]
	v_mfma_f32_16x16x32_bf16 v[34:37], v[182:185], v[198:201], v[34:37]
	v_mfma_f32_16x16x32_bf16 v[22:25], v[174:177], v[206:209], v[22:25]
	v_mfma_f32_16x16x32_bf16 v[18:21], v[182:185], v[206:209], v[18:21]
	v_mfma_f32_16x16x32_bf16 v[6:9], v[174:177], v[214:217], v[6:9]
	v_mfma_f32_16x16x32_bf16 v[2:5], v[182:185], v[214:217], v[2:5]
	s_setprio 0
	s_barrier
	s_add_u32 s52, s52, 0x100
	s_addc_u32 s53, s53, 0
	s_mov_b32 s54, s75
	s_cbranch_vccz .LBB0_1090
	s_and_b64 vcc, exec, s[36:37]
	s_cbranch_vccz .LBB0_1093
	s_barrier
